# index scoring v8: no LDS staging/barriers, per-wave 16-key B tiles straight from global (keys stored tile-major by dsa_post), 8 queries x 16 heads as A in registers via a coalesced LDS image, permlane
# speedup vs baseline: 1.0165x; 1.0088x over previous
.LBB0_135:
	s_and_b32 s0, s76, 0x7ffff000
	s_mov_b32 s1, s77
	s_lshl_b64 s[0:1], s[0:1], 9
	v_mov_b32_e32 v72, 0
	s_and_b32 s29, s76, 0xfff
	v_mad_u64_u32 v[106:107], s[2:3], s76, v188, v[100:101]
	v_lshl_add_u64 v[108:109], v[102:103], 0, s[0:1]
	v_mov_b32_e32 v128, 0xff800000
	global_load_dwordx4 v[196:199], v[106:107], off
	global_load_dwordx4 v[200:203], v[106:107], off offset:64
	global_load_dwordx4 v[204:207], v[106:107], off offset:128
	global_load_dwordx4 v[208:211], v[106:107], off offset:192
	global_load_dwordx4 v[212:215], v[106:107], off offset:256
	global_load_dwordx4 v[216:219], v[106:107], off offset:320
	global_load_dwordx4 v[220:223], v[106:107], off offset:384
	global_load_dwordx4 v[224:227], v[106:107], off offset:448
	s_mov_b32 s30, 0
	v_mov_b32_e32 v68, 0
	v_mov_b32_e32 v69, v72
	v_mov_b32_e32 v70, v72
	v_mov_b32_e32 v71, v72
	v_mov_b32_e32 v24, 0
	v_mov_b32_e32 v25, v72
	v_mov_b32_e32 v26, v72
	v_mov_b32_e32 v27, v72
	v_mov_b32_e32 v64, 0
	v_mov_b32_e32 v65, v72
	v_mov_b32_e32 v66, v72
	v_mov_b32_e32 v67, v72
	v_mov_b32_e32 v60, 0
	v_mov_b32_e32 v61, v72
	v_mov_b32_e32 v62, v72
	v_mov_b32_e32 v63, v72
	v_mov_b32_e32 v56, 0
	v_mov_b32_e32 v57, v72
	v_mov_b32_e32 v58, v72
	v_mov_b32_e32 v59, v72
	v_mov_b32_e32 v52, 0
	v_mov_b32_e32 v53, v72
	v_mov_b32_e32 v54, v72
	v_mov_b32_e32 v55, v72
	v_mov_b32_e32 v48, 0
	v_mov_b32_e32 v49, v72
	v_mov_b32_e32 v50, v72
	v_mov_b32_e32 v51, v72
	v_mov_b32_e32 v44, 0
	v_mov_b32_e32 v45, v72
	v_mov_b32_e32 v46, v72
	v_mov_b32_e32 v47, v72
	v_mov_b32_e32 v40, 0
	v_mov_b32_e32 v41, v72
	v_mov_b32_e32 v42, v72
	v_mov_b32_e32 v43, v72
	v_mov_b32_e32 v28, 0
	v_mov_b32_e32 v29, v72
	v_mov_b32_e32 v30, v72
	v_mov_b32_e32 v31, v72
	v_mov_b32_e32 v20, 0
	v_mov_b32_e32 v21, v72
	v_mov_b32_e32 v22, v72
	v_mov_b32_e32 v23, v72
	v_mov_b32_e32 v16, 0
	v_mov_b32_e32 v17, v72
	v_mov_b32_e32 v18, v72
	v_mov_b32_e32 v19, v72
	v_mov_b32_e32 v12, 0
	v_mov_b32_e32 v13, v72
	v_mov_b32_e32 v14, v72
	v_mov_b32_e32 v15, v72
	v_mov_b32_e32 v8, 0
	v_mov_b32_e32 v9, v72
	v_mov_b32_e32 v10, v72
	v_mov_b32_e32 v11, v72
	v_mov_b32_e32 v4, 0
	v_mov_b32_e32 v5, v72
	v_mov_b32_e32 v6, v72
	v_mov_b32_e32 v7, v72
	v_mov_b32_e32 v0, 0
	v_mov_b32_e32 v1, v72
	v_mov_b32_e32 v2, v72
	v_mov_b32_e32 v3, v72
	v_mov_b32_e32 v244, v124
	v_readfirstlane_b32 s2, v108
	v_readfirstlane_b32 s3, v109
	v_and_b32_e32 v246, 31, v165
	v_lshlrev_b32_e32 v246, 4, v246
	s_nop 1
	v_readlane_b32 s0, v244, 0
	v_readlane_b32 s1, v244, 1
	v_readlane_b32 vcc_lo, v244, 2
	v_readlane_b32 vcc_hi, v244, 3
	s_mov_b32 exec_lo, 0xffff
	s_mov_b32 exec_hi, 0x0
	v_mov_b32_e32 v164, s0
	v_mov_b32_e32 v166, s1
	v_mov_b32_e32 v168, vcc_lo
	v_mov_b32_e32 v169, vcc_hi
	s_mov_b64 exec, -1
	s_max_i32 s0, s0, 0
	s_max_i32 s1, s1, 0
	s_max_i32 vcc_lo, vcc_lo, 0
	s_max_i32 vcc_hi, vcc_hi, 0
	s_sub_i32 s1, s1, s0
	s_sub_i32 vcc_hi, vcc_hi, vcc_lo
	s_lshl_b32 s0, s0, 9
	s_lshl_b32 s1, s1, 9
	s_lshl_b32 vcc_lo, vcc_lo, 9
	s_lshl_b32 vcc_hi, vcc_hi, 9
	v_add_u32_e32 v88, s0, v246
	v_add_u32_e32 v92, vcc_lo, v246
	v_mad_i32_i24 v88, v115, s1, v88
	v_mad_i32_i24 v92, v115, vcc_hi, v92
	global_load_dwordx4 v[88:91], v88, s[2:3]
	global_load_dwordx4 v[92:95], v92, s[2:3]
	v_readlane_b32 s0, v244, 4
	v_readlane_b32 s1, v244, 5
	v_readlane_b32 vcc_lo, v244, 6
	v_readlane_b32 vcc_hi, v244, 7
	s_mov_b32 exec_lo, 0xffff0000
	s_mov_b32 exec_hi, 0x0
	v_mov_b32_e32 v164, s0
	v_mov_b32_e32 v166, s1
	v_mov_b32_e32 v168, vcc_lo
	v_mov_b32_e32 v169, vcc_hi
	s_mov_b64 exec, -1
	s_max_i32 s0, s0, 0
	s_max_i32 s1, s1, 0
	s_max_i32 vcc_lo, vcc_lo, 0
	s_max_i32 vcc_hi, vcc_hi, 0
	s_sub_i32 s1, s1, s0
	s_sub_i32 vcc_hi, vcc_hi, vcc_lo
	s_lshl_b32 s0, s0, 9
	s_lshl_b32 s1, s1, 9
	s_lshl_b32 vcc_lo, vcc_lo, 9
	s_lshl_b32 vcc_hi, vcc_hi, 9
	v_add_u32_e32 v96, s0, v246
	v_add_u32_e32 v144, vcc_lo, v246
	v_mad_i32_i24 v96, v115, s1, v96
	v_mad_i32_i24 v144, v115, vcc_hi, v144
	global_load_dwordx4 v[96:99], v96, s[2:3]
	global_load_dwordx4 v[144:147], v144, s[2:3]
	v_readlane_b32 s0, v244, 8
	v_readlane_b32 s1, v244, 9
	v_readlane_b32 vcc_lo, v244, 10
	v_readlane_b32 vcc_hi, v244, 11
	s_mov_b32 exec_lo, 0x0
	s_mov_b32 exec_hi, 0xffff
	v_mov_b32_e32 v164, s0
	v_mov_b32_e32 v166, s1
	v_mov_b32_e32 v168, vcc_lo
	v_mov_b32_e32 v169, vcc_hi
	s_mov_b64 exec, -1
	s_max_i32 s0, s0, 0
	s_max_i32 s1, s1, 0
	s_max_i32 vcc_lo, vcc_lo, 0
	s_max_i32 vcc_hi, vcc_hi, 0
	s_sub_i32 s1, s1, s0
	s_sub_i32 vcc_hi, vcc_hi, vcc_lo
	s_lshl_b32 s0, s0, 9
	s_lshl_b32 s1, s1, 9
	s_lshl_b32 vcc_lo, vcc_lo, 9
	s_lshl_b32 vcc_hi, vcc_hi, 9
	v_add_u32_e32 v152, s0, v246
	v_add_u32_e32 v156, vcc_lo, v246
	v_mad_i32_i24 v152, v115, s1, v152
	v_mad_i32_i24 v156, v115, vcc_hi, v156
	global_load_dwordx4 v[152:155], v152, s[2:3]
	global_load_dwordx4 v[156:159], v156, s[2:3]
	v_readlane_b32 s0, v244, 12
	v_readlane_b32 s1, v244, 13
	v_readlane_b32 vcc_lo, v244, 14
	v_readlane_b32 vcc_hi, v244, 15
	s_mov_b32 exec_lo, 0x0
	s_mov_b32 exec_hi, 0xffff0000
	v_mov_b32_e32 v164, s0
	v_mov_b32_e32 v166, s1
	v_mov_b32_e32 v168, vcc_lo
	v_mov_b32_e32 v169, vcc_hi
	s_mov_b64 exec, -1
	s_max_i32 s0, s0, 0
	s_max_i32 s1, s1, 0
	s_max_i32 vcc_lo, vcc_lo, 0
	s_max_i32 vcc_hi, vcc_hi, 0
	s_sub_i32 s1, s1, s0
	s_sub_i32 vcc_hi, vcc_hi, vcc_lo
	s_lshl_b32 s0, s0, 9
	s_lshl_b32 s1, s1, 9
	s_lshl_b32 vcc_lo, vcc_lo, 9
	s_lshl_b32 vcc_hi, vcc_hi, 9
	v_add_u32_e32 v160, s0, v246
	v_add_u32_e32 v172, vcc_lo, v246
	v_mad_i32_i24 v160, v115, s1, v160
	v_mad_i32_i24 v172, v115, vcc_hi, v172
	global_load_dwordx4 v[160:163], v160, s[2:3]
	global_load_dwordx4 v[172:175], v172, s[2:3]
	v_readlane_b32 s0, v244, 16
	v_readlane_b32 s1, v244, 17
	v_readlane_b32 vcc_lo, v244, 18
	v_readlane_b32 vcc_hi, v244, 19
	s_mov_b32 exec_lo, 0xffff
	s_mov_b32 exec_hi, 0x0
	v_mov_b32_e32 v170, s0
	v_mov_b32_e32 v176, s1
	v_mov_b32_e32 v177, vcc_lo
	v_mov_b32_e32 v191, vcc_hi
	s_mov_b64 exec, -1
	s_max_i32 s0, s0, 0
	s_max_i32 s1, s1, 0
	s_max_i32 vcc_lo, vcc_lo, 0
	s_max_i32 vcc_hi, vcc_hi, 0
	s_sub_i32 s1, s1, s0
	s_sub_i32 vcc_hi, vcc_hi, vcc_lo
	s_lshl_b32 s0, s0, 9
	s_lshl_b32 s1, s1, 9
	s_lshl_b32 vcc_lo, vcc_lo, 9
	s_lshl_b32 vcc_hi, vcc_hi, 9
	v_add_u32_e32 v192, s0, v246
	v_add_u32_e32 v132, vcc_lo, v246
	v_mad_i32_i24 v192, v115, s1, v192
	v_mad_i32_i24 v132, v115, vcc_hi, v132
	global_load_dwordx4 v[192:195], v192, s[2:3]
	global_load_dwordx4 v[132:135], v132, s[2:3]
	v_readlane_b32 s0, v244, 20
	v_readlane_b32 s1, v244, 21
	v_readlane_b32 vcc_lo, v244, 22
	v_readlane_b32 vcc_hi, v244, 23
	s_mov_b32 exec_lo, 0xffff0000
	s_mov_b32 exec_hi, 0x0
	v_mov_b32_e32 v170, s0
	v_mov_b32_e32 v176, s1
	v_mov_b32_e32 v177, vcc_lo
	v_mov_b32_e32 v191, vcc_hi
	s_mov_b64 exec, -1
	s_max_i32 s0, s0, 0
	s_max_i32 s1, s1, 0
	s_max_i32 vcc_lo, vcc_lo, 0
	s_max_i32 vcc_hi, vcc_hi, 0
	s_sub_i32 s1, s1, s0
	s_sub_i32 vcc_hi, vcc_hi, vcc_lo
	s_lshl_b32 s0, s0, 9
	s_lshl_b32 s1, s1, 9
	s_lshl_b32 vcc_lo, vcc_lo, 9
	s_lshl_b32 vcc_hi, vcc_hi, 9
	v_add_u32_e32 v136, s0, v246
	v_add_u32_e32 v140, vcc_lo, v246
	v_mad_i32_i24 v136, v115, s1, v136
	v_mad_i32_i24 v140, v115, vcc_hi, v140
	global_load_dwordx4 v[136:139], v136, s[2:3]
	global_load_dwordx4 v[140:143], v140, s[2:3]
	v_readlane_b32 s0, v244, 24
	v_readlane_b32 s1, v244, 25
	v_readlane_b32 vcc_lo, v244, 26
	v_readlane_b32 vcc_hi, v244, 27
	s_mov_b32 exec_lo, 0x0
	s_mov_b32 exec_hi, 0xffff
	v_mov_b32_e32 v170, s0
	v_mov_b32_e32 v176, s1
	v_mov_b32_e32 v177, vcc_lo
	v_mov_b32_e32 v191, vcc_hi
	s_mov_b64 exec, -1
	s_max_i32 s0, s0, 0
	s_max_i32 s1, s1, 0
	s_max_i32 vcc_lo, vcc_lo, 0
	s_max_i32 vcc_hi, vcc_hi, 0
	s_sub_i32 s1, s1, s0
	s_sub_i32 vcc_hi, vcc_hi, vcc_lo
	s_lshl_b32 s0, s0, 9
	s_lshl_b32 s1, s1, 9
	s_lshl_b32 vcc_lo, vcc_lo, 9
	s_lshl_b32 vcc_hi, vcc_hi, 9
	v_add_u32_e32 v228, s0, v246
	v_add_u32_e32 v232, vcc_lo, v246
	v_mad_i32_i24 v228, v115, s1, v228
	v_mad_i32_i24 v232, v115, vcc_hi, v232
	global_load_dwordx4 v[228:231], v228, s[2:3]
	global_load_dwordx4 v[232:235], v232, s[2:3]
	v_readlane_b32 s0, v244, 28
	v_readlane_b32 s1, v244, 29
	v_readlane_b32 vcc_lo, v244, 30
	v_readlane_b32 vcc_hi, v244, 31
	s_mov_b32 exec_lo, 0x0
	s_mov_b32 exec_hi, 0xffff0000
	v_mov_b32_e32 v170, s0
	v_mov_b32_e32 v176, s1
	v_mov_b32_e32 v177, vcc_lo
	v_mov_b32_e32 v191, vcc_hi
	s_mov_b64 exec, -1
	s_max_i32 s0, s0, 0
	s_max_i32 s1, s1, 0
	s_max_i32 vcc_lo, vcc_lo, 0
	s_max_i32 vcc_hi, vcc_hi, 0
	s_sub_i32 s1, s1, s0
	s_sub_i32 vcc_hi, vcc_hi, vcc_lo
	s_lshl_b32 s0, s0, 9
	s_lshl_b32 s1, s1, 9
	s_lshl_b32 vcc_lo, vcc_lo, 9
	s_lshl_b32 vcc_hi, vcc_hi, 9
	v_add_u32_e32 v236, s0, v246
	v_add_u32_e32 v240, vcc_lo, v246
	v_mad_i32_i24 v236, v115, s1, v236
	v_mad_i32_i24 v240, v115, vcc_hi, v240
	global_load_dwordx4 v[236:239], v236, s[2:3]
	global_load_dwordx4 v[240:243], v240, s[2:3]
.LBB0_136:
	v_mov_b32_e32 v129, v72
	s_waitcnt vmcnt(15)
	ds_write_b128 v117, v[88:91]
	s_waitcnt vmcnt(14)
	ds_write_b128 v117, v[92:95] offset:1056
	s_waitcnt vmcnt(13)
	ds_write_b128 v117, v[96:99] offset:2112
	s_waitcnt vmcnt(12)
	ds_write_b128 v117, v[144:147] offset:3168
	s_waitcnt vmcnt(11)
	ds_write_b128 v117, v[152:155] offset:4224
	s_waitcnt vmcnt(10)
	ds_write_b128 v117, v[156:159] offset:5280
	s_waitcnt vmcnt(9)
	ds_write_b128 v117, v[160:163] offset:6336
	s_waitcnt vmcnt(8)
	ds_write_b128 v117, v[172:175] offset:7392
	s_waitcnt vmcnt(7)
	ds_write_b128 v117, v[192:195] offset:8448
	s_waitcnt vmcnt(6)
	ds_write_b128 v117, v[132:135] offset:9504
	s_waitcnt vmcnt(5)
	ds_write_b128 v117, v[136:139] offset:10560
	s_waitcnt vmcnt(4)
	ds_write_b128 v117, v[140:143] offset:11616
	s_waitcnt vmcnt(3)
	ds_write_b128 v117, v[228:231] offset:12672
	s_waitcnt vmcnt(2)
	ds_write_b128 v117, v[232:235] offset:13728
	s_waitcnt vmcnt(1)
	ds_write_b128 v117, v[236:239] offset:14784
	s_waitcnt vmcnt(0)
	ds_write_b128 v117, v[240:243] offset:15840
	s_waitcnt lgkmcnt(7)
	v_cmp_lt_i32_e32 vcc, -1, v164
	s_waitcnt lgkmcnt(0)
	ds_read_b128 v[228:231], v118
	ds_read_b128 v[232:235], v118 offset:64
	ds_read_b128 v[236:239], v118 offset:128
	ds_read_b128 v[240:243], v118 offset:192
	s_waitcnt lgkmcnt(3)
	v_mfma_f32_16x16x32_bf16 v[134:137], v[228:231], v[196:199], 0
	ds_read_b128 v[228:231], v118 offset:256
	s_waitcnt lgkmcnt(3)
	v_mfma_f32_16x16x32_bf16 v[134:137], v[232:235], v[200:203], v[134:137]
	ds_read_b128 v[232:235], v118 offset:320
	s_waitcnt lgkmcnt(3)
	v_mfma_f32_16x16x32_bf16 v[134:137], v[236:239], v[204:207], v[134:137]
	ds_read_b128 v[236:239], v118 offset:384
	s_waitcnt lgkmcnt(3)
	v_mfma_f32_16x16x32_bf16 v[134:137], v[240:243], v[208:211], v[134:137]
	ds_read_b128 v[240:243], v118 offset:448
	s_waitcnt lgkmcnt(3)
	v_mfma_f32_16x16x32_bf16 v[134:137], v[228:231], v[212:215], v[134:137]
	ds_read_b128 v[228:231], v118 offset:8448
	s_waitcnt lgkmcnt(3)
	v_mfma_f32_16x16x32_bf16 v[134:137], v[232:235], v[216:219], v[134:137]
	ds_read_b128 v[232:235], v118 offset:8512
	s_waitcnt lgkmcnt(3)
	v_mfma_f32_16x16x32_bf16 v[134:137], v[236:239], v[220:223], v[134:137]
	ds_read_b128 v[236:239], v118 offset:8576
	s_waitcnt lgkmcnt(3)
	v_mfma_f32_16x16x32_bf16 v[134:137], v[240:243], v[224:227], v[134:137]
	ds_read_b128 v[240:243], v118 offset:8640
	s_waitcnt lgkmcnt(3)
	v_mfma_f32_16x16x32_bf16 v[72:75], v[228:231], v[196:199], 0
	ds_read_b128 v[228:231], v118 offset:8704
	s_waitcnt lgkmcnt(3)
	v_mfma_f32_16x16x32_bf16 v[72:75], v[232:235], v[200:203], v[72:75]
	ds_read_b128 v[232:235], v118 offset:8768
	s_waitcnt lgkmcnt(3)
	v_mfma_f32_16x16x32_bf16 v[72:75], v[236:239], v[204:207], v[72:75]
	ds_read_b128 v[236:239], v118 offset:8832
	s_waitcnt lgkmcnt(3)
	v_mfma_f32_16x16x32_bf16 v[72:75], v[240:243], v[208:211], v[72:75]
	ds_read_b128 v[240:243], v118 offset:8896
	v_subrev_u32_e32 v80, s29, v170
	v_med3_i32 v80, v80, s4, v189
	v_lshl_add_u32 v80, v80, 6, v116
	ds_read_b32 v80, v80 offset:8192
	s_waitcnt lgkmcnt(4)
	v_mfma_f32_16x16x32_bf16 v[72:75], v[228:231], v[212:215], v[72:75]
	s_waitcnt lgkmcnt(3)
	v_mfma_f32_16x16x32_bf16 v[72:75], v[232:235], v[216:219], v[72:75]
	s_waitcnt lgkmcnt(2)
	v_mfma_f32_16x16x32_bf16 v[72:75], v[236:239], v[220:223], v[72:75]
	s_waitcnt lgkmcnt(1)
	v_mfma_f32_16x16x32_bf16 v[72:75], v[240:243], v[224:227], v[72:75]
	v_subrev_u32_e32 v76, s29, v164
	v_med3_i32 v76, v76, s4, v189
	v_subrev_u32_e32 v77, s29, v166
	v_lshl_add_u32 v76, v76, 6, v116
	v_med3_i32 v77, v77, s4, v189
	v_subrev_u32_e32 v78, s29, v168
	ds_read_b32 v76, v76 offset:8192
	v_lshl_add_u32 v77, v77, 6, v116
	v_med3_i32 v78, v78, s4, v189
	v_subrev_u32_e32 v79, s29, v169
	ds_read_b32 v77, v77 offset:8192
	v_lshl_add_u32 v78, v78, 6, v116
	v_med3_i32 v79, v79, s4, v189
	ds_read_b32 v78, v78 offset:8192
	v_lshl_add_u32 v79, v79, 6, v116
	ds_read_b32 v79, v79 offset:8192
	s_waitcnt lgkmcnt(3)
	v_fmac_f32_e32 v76, 0x3d800000, v134
	v_cndmask_b32_e32 v76, v190, v76, vcc
	s_waitcnt lgkmcnt(2)
	v_fmac_f32_e32 v77, 0x3d800000, v135
	v_cmp_lt_i32_e32 vcc, -1, v166
	s_waitcnt lgkmcnt(1)
	v_fmac_f32_e32 v78, 0x3d800000, v136
	s_waitcnt lgkmcnt(0)
	v_fmac_f32_e32 v79, 0x3d800000, v137
	v_cndmask_b32_e32 v77, v190, v77, vcc
	v_cmp_lt_i32_e32 vcc, -1, v168
	v_fmac_f32_e32 v80, 0x3d800000, v72
	s_nop 0
	v_cndmask_b32_e32 v78, v190, v78, vcc
	v_cmp_lt_i32_e32 vcc, -1, v169
	s_nop 1
	v_cndmask_b32_e32 v79, v190, v79, vcc
	v_cmp_lt_i32_e32 vcc, -1, v170
	v_max_f32_e32 v81, v78, v79
	s_nop 0
	v_cndmask_b32_e32 v72, v190, v80, vcc
	v_subrev_u32_e32 v80, s29, v176
	v_med3_i32 v80, v80, s4, v189
	v_lshl_add_u32 v80, v80, 6, v116
	ds_read_b32 v80, v80 offset:8192
	v_cmp_lt_i32_e32 vcc, -1, v176
	s_waitcnt lgkmcnt(0)
	v_fmac_f32_e32 v80, 0x3d800000, v73
	v_subrev_u32_e32 v73, s29, v177
	v_med3_i32 v73, v73, s4, v189
	v_lshl_add_u32 v73, v73, 6, v116
	ds_read_b32 v73, v73 offset:8192
	v_cndmask_b32_e32 v80, v190, v80, vcc
	v_cmp_lt_i32_e32 vcc, -1, v177
	s_waitcnt lgkmcnt(0)
	v_fmac_f32_e32 v73, 0x3d800000, v74
	v_cndmask_b32_e32 v74, v190, v73, vcc
	v_subrev_u32_e32 v73, s29, v191
	v_med3_i32 v73, v73, s4, v189
	v_lshl_add_u32 v73, v73, 6, v116
	ds_read_b32 v73, v73 offset:8192
	v_cmp_lt_i32_e32 vcc, -1, v191
	s_waitcnt lgkmcnt(0)
	v_fmac_f32_e32 v73, 0x3d800000, v75
	v_cndmask_b32_e32 v75, v190, v73, vcc
	s_add_i32 s2, s30, 1
	s_cmp_eq_u32 s2, 8
	s_cbranch_scc1 .Latt_nopf
	s_lshr_b32 s3, s2, 1
	s_cmp_eq_u32 s3, 2
	s_cselect_b64 vcc, -1, 0
	v_cndmask_b32_e32 v244, v127, v126, vcc
	s_cmp_eq_u32 s3, 1
	s_cselect_b64 vcc, -1, 0
	v_cndmask_b32_e32 v244, v244, v125, vcc
	s_cmp_eq_u32 s3, 0
	s_cselect_b64 vcc, -1, 0
	v_cndmask_b32_e32 v244, v244, v124, vcc
	s_bitcmp1_b32 s2, 0
	v_readfirstlane_b32 s2, v108
	v_readfirstlane_b32 s3, v109
	s_cbranch_scc1 .Latt_pf_odd
	v_readlane_b32 s0, v244, 0
	v_readlane_b32 s1, v244, 1
	v_readlane_b32 vcc_lo, v244, 2
	v_readlane_b32 vcc_hi, v244, 3
	s_mov_b32 exec_lo, 0xffff
	s_mov_b32 exec_hi, 0x0
	v_mov_b32_e32 v164, s0
	v_mov_b32_e32 v166, s1
	v_mov_b32_e32 v168, vcc_lo
	v_mov_b32_e32 v169, vcc_hi
	s_mov_b64 exec, -1
	s_max_i32 s0, s0, 0
	s_max_i32 s1, s1, 0
	s_max_i32 vcc_lo, vcc_lo, 0
	s_max_i32 vcc_hi, vcc_hi, 0
	s_sub_i32 s1, s1, s0
	s_sub_i32 vcc_hi, vcc_hi, vcc_lo
	s_lshl_b32 s0, s0, 9
	s_lshl_b32 s1, s1, 9
	s_lshl_b32 vcc_lo, vcc_lo, 9
	s_lshl_b32 vcc_hi, vcc_hi, 9
	v_add_u32_e32 v88, s0, v246
	v_add_u32_e32 v92, vcc_lo, v246
	v_mad_i32_i24 v88, v115, s1, v88
	v_mad_i32_i24 v92, v115, vcc_hi, v92
	global_load_dwordx4 v[88:91], v88, s[2:3]
	global_load_dwordx4 v[92:95], v92, s[2:3]
	v_readlane_b32 s0, v244, 4
	v_readlane_b32 s1, v244, 5
	v_readlane_b32 vcc_lo, v244, 6
	v_readlane_b32 vcc_hi, v244, 7
	s_mov_b32 exec_lo, 0xffff0000
	s_mov_b32 exec_hi, 0x0
	v_mov_b32_e32 v164, s0
	v_mov_b32_e32 v166, s1
	v_mov_b32_e32 v168, vcc_lo
	v_mov_b32_e32 v169, vcc_hi
	s_mov_b64 exec, -1
	s_max_i32 s0, s0, 0
	s_max_i32 s1, s1, 0
	s_max_i32 vcc_lo, vcc_lo, 0
	s_max_i32 vcc_hi, vcc_hi, 0
	s_sub_i32 s1, s1, s0
	s_sub_i32 vcc_hi, vcc_hi, vcc_lo
	s_lshl_b32 s0, s0, 9
	s_lshl_b32 s1, s1, 9
	s_lshl_b32 vcc_lo, vcc_lo, 9
	s_lshl_b32 vcc_hi, vcc_hi, 9
	v_add_u32_e32 v96, s0, v246
	v_add_u32_e32 v144, vcc_lo, v246
	v_mad_i32_i24 v96, v115, s1, v96
	v_mad_i32_i24 v144, v115, vcc_hi, v144
	global_load_dwordx4 v[96:99], v96, s[2:3]
	global_load_dwordx4 v[144:147], v144, s[2:3]
	v_readlane_b32 s0, v244, 8
	v_readlane_b32 s1, v244, 9
	v_readlane_b32 vcc_lo, v244, 10
	v_readlane_b32 vcc_hi, v244, 11
	s_mov_b32 exec_lo, 0x0
	s_mov_b32 exec_hi, 0xffff
	v_mov_b32_e32 v164, s0
	v_mov_b32_e32 v166, s1
	v_mov_b32_e32 v168, vcc_lo
	v_mov_b32_e32 v169, vcc_hi
	s_mov_b64 exec, -1
	s_max_i32 s0, s0, 0
	s_max_i32 s1, s1, 0
	s_max_i32 vcc_lo, vcc_lo, 0
	s_max_i32 vcc_hi, vcc_hi, 0
	s_sub_i32 s1, s1, s0
	s_sub_i32 vcc_hi, vcc_hi, vcc_lo
	s_lshl_b32 s0, s0, 9
	s_lshl_b32 s1, s1, 9
	s_lshl_b32 vcc_lo, vcc_lo, 9
	s_lshl_b32 vcc_hi, vcc_hi, 9
	v_add_u32_e32 v152, s0, v246
	v_add_u32_e32 v156, vcc_lo, v246
	v_mad_i32_i24 v152, v115, s1, v152
	v_mad_i32_i24 v156, v115, vcc_hi, v156
	global_load_dwordx4 v[152:155], v152, s[2:3]
	global_load_dwordx4 v[156:159], v156, s[2:3]
	v_readlane_b32 s0, v244, 12
	v_readlane_b32 s1, v244, 13
	v_readlane_b32 vcc_lo, v244, 14
	v_readlane_b32 vcc_hi, v244, 15
	s_mov_b32 exec_lo, 0x0
	s_mov_b32 exec_hi, 0xffff0000
	v_mov_b32_e32 v164, s0
	v_mov_b32_e32 v166, s1
	v_mov_b32_e32 v168, vcc_lo
	v_mov_b32_e32 v169, vcc_hi
	s_mov_b64 exec, -1
	s_max_i32 s0, s0, 0
	s_max_i32 s1, s1, 0
	s_max_i32 vcc_lo, vcc_lo, 0
	s_max_i32 vcc_hi, vcc_hi, 0
	s_sub_i32 s1, s1, s0
	s_sub_i32 vcc_hi, vcc_hi, vcc_lo
	s_lshl_b32 s0, s0, 9
	s_lshl_b32 s1, s1, 9
	s_lshl_b32 vcc_lo, vcc_lo, 9
	s_lshl_b32 vcc_hi, vcc_hi, 9
	v_add_u32_e32 v160, s0, v246
	v_add_u32_e32 v172, vcc_lo, v246
	v_mad_i32_i24 v160, v115, s1, v160
	v_mad_i32_i24 v172, v115, vcc_hi, v172
	global_load_dwordx4 v[160:163], v160, s[2:3]
	global_load_dwordx4 v[172:175], v172, s[2:3]
	v_readlane_b32 s0, v244, 16
	v_readlane_b32 s1, v244, 17
	v_readlane_b32 vcc_lo, v244, 18
	v_readlane_b32 vcc_hi, v244, 19
	s_mov_b32 exec_lo, 0xffff
	s_mov_b32 exec_hi, 0x0
	v_mov_b32_e32 v170, s0
	v_mov_b32_e32 v176, s1
	v_mov_b32_e32 v177, vcc_lo
	v_mov_b32_e32 v191, vcc_hi
	s_mov_b64 exec, -1
	s_max_i32 s0, s0, 0
	s_max_i32 s1, s1, 0
	s_max_i32 vcc_lo, vcc_lo, 0
	s_max_i32 vcc_hi, vcc_hi, 0
	s_sub_i32 s1, s1, s0
	s_sub_i32 vcc_hi, vcc_hi, vcc_lo
	s_lshl_b32 s0, s0, 9
	s_lshl_b32 s1, s1, 9
	s_lshl_b32 vcc_lo, vcc_lo, 9
	s_lshl_b32 vcc_hi, vcc_hi, 9
	v_add_u32_e32 v192, s0, v246
	v_add_u32_e32 v132, vcc_lo, v246
	v_mad_i32_i24 v192, v115, s1, v192
	v_mad_i32_i24 v132, v115, vcc_hi, v132
	global_load_dwordx4 v[192:195], v192, s[2:3]
	global_load_dwordx4 v[132:135], v132, s[2:3]
	v_readlane_b32 s0, v244, 20
	v_readlane_b32 s1, v244, 21
	v_readlane_b32 vcc_lo, v244, 22
	v_readlane_b32 vcc_hi, v244, 23
	s_mov_b32 exec_lo, 0xffff0000
	s_mov_b32 exec_hi, 0x0
	v_mov_b32_e32 v170, s0
	v_mov_b32_e32 v176, s1
	v_mov_b32_e32 v177, vcc_lo
	v_mov_b32_e32 v191, vcc_hi
	s_mov_b64 exec, -1
	s_max_i32 s0, s0, 0
	s_max_i32 s1, s1, 0
	s_max_i32 vcc_lo, vcc_lo, 0
	s_max_i32 vcc_hi, vcc_hi, 0
	s_sub_i32 s1, s1, s0
	s_sub_i32 vcc_hi, vcc_hi, vcc_lo
	s_lshl_b32 s0, s0, 9
	s_lshl_b32 s1, s1, 9
	s_lshl_b32 vcc_lo, vcc_lo, 9
	s_lshl_b32 vcc_hi, vcc_hi, 9
	v_add_u32_e32 v136, s0, v246
	v_add_u32_e32 v140, vcc_lo, v246
	v_mad_i32_i24 v136, v115, s1, v136
	v_mad_i32_i24 v140, v115, vcc_hi, v140
	global_load_dwordx4 v[136:139], v136, s[2:3]
	global_load_dwordx4 v[140:143], v140, s[2:3]
	v_readlane_b32 s0, v244, 24
	v_readlane_b32 s1, v244, 25
	v_readlane_b32 vcc_lo, v244, 26
	v_readlane_b32 vcc_hi, v244, 27
	s_mov_b32 exec_lo, 0x0
	s_mov_b32 exec_hi, 0xffff
	v_mov_b32_e32 v170, s0
	v_mov_b32_e32 v176, s1
	v_mov_b32_e32 v177, vcc_lo
	v_mov_b32_e32 v191, vcc_hi
	s_mov_b64 exec, -1
	s_max_i32 s0, s0, 0
	s_max_i32 s1, s1, 0
	s_max_i32 vcc_lo, vcc_lo, 0
	s_max_i32 vcc_hi, vcc_hi, 0
	s_sub_i32 s1, s1, s0
	s_sub_i32 vcc_hi, vcc_hi, vcc_lo
	s_lshl_b32 s0, s0, 9
	s_lshl_b32 s1, s1, 9
	s_lshl_b32 vcc_lo, vcc_lo, 9
	s_lshl_b32 vcc_hi, vcc_hi, 9
	v_add_u32_e32 v228, s0, v246
	v_add_u32_e32 v232, vcc_lo, v246
	v_mad_i32_i24 v228, v115, s1, v228
	v_mad_i32_i24 v232, v115, vcc_hi, v232
	global_load_dwordx4 v[228:231], v228, s[2:3]
	global_load_dwordx4 v[232:235], v232, s[2:3]
	v_readlane_b32 s0, v244, 28
	v_readlane_b32 s1, v244, 29
	v_readlane_b32 vcc_lo, v244, 30
	v_readlane_b32 vcc_hi, v244, 31
	s_mov_b32 exec_lo, 0x0
	s_mov_b32 exec_hi, 0xffff0000
	v_mov_b32_e32 v170, s0
	v_mov_b32_e32 v176, s1
	v_mov_b32_e32 v177, vcc_lo
	v_mov_b32_e32 v191, vcc_hi
	s_mov_b64 exec, -1
	s_max_i32 s0, s0, 0
	s_max_i32 s1, s1, 0
	s_max_i32 vcc_lo, vcc_lo, 0
	s_max_i32 vcc_hi, vcc_hi, 0
	s_sub_i32 s1, s1, s0
	s_sub_i32 vcc_hi, vcc_hi, vcc_lo
	s_lshl_b32 s0, s0, 9
	s_lshl_b32 s1, s1, 9
	s_lshl_b32 vcc_lo, vcc_lo, 9
	s_lshl_b32 vcc_hi, vcc_hi, 9
	v_add_u32_e32 v236, s0, v246
	v_add_u32_e32 v240, vcc_lo, v246
	v_mad_i32_i24 v236, v115, s1, v236
	v_mad_i32_i24 v240, v115, vcc_hi, v240
	global_load_dwordx4 v[236:239], v236, s[2:3]
	global_load_dwordx4 v[240:243], v240, s[2:3]
	s_branch .Latt_nopf
.Latt_pf_odd:
	v_readlane_b32 s0, v244, 32
	v_readlane_b32 s1, v244, 33
	v_readlane_b32 vcc_lo, v244, 34
	v_readlane_b32 vcc_hi, v244, 35
	s_mov_b32 exec_lo, 0xffff
	s_mov_b32 exec_hi, 0x0
	v_mov_b32_e32 v164, s0
	v_mov_b32_e32 v166, s1
	v_mov_b32_e32 v168, vcc_lo
	v_mov_b32_e32 v169, vcc_hi
	s_mov_b64 exec, -1
	s_max_i32 s0, s0, 0
	s_max_i32 s1, s1, 0
	s_max_i32 vcc_lo, vcc_lo, 0
	s_max_i32 vcc_hi, vcc_hi, 0
	s_sub_i32 s1, s1, s0
	s_sub_i32 vcc_hi, vcc_hi, vcc_lo
	s_lshl_b32 s0, s0, 9
	s_lshl_b32 s1, s1, 9
	s_lshl_b32 vcc_lo, vcc_lo, 9
	s_lshl_b32 vcc_hi, vcc_hi, 9
	v_add_u32_e32 v88, s0, v246
	v_add_u32_e32 v92, vcc_lo, v246
	v_mad_i32_i24 v88, v115, s1, v88
	v_mad_i32_i24 v92, v115, vcc_hi, v92
	global_load_dwordx4 v[88:91], v88, s[2:3]
	global_load_dwordx4 v[92:95], v92, s[2:3]
	v_readlane_b32 s0, v244, 36
	v_readlane_b32 s1, v244, 37
	v_readlane_b32 vcc_lo, v244, 38
	v_readlane_b32 vcc_hi, v244, 39
	s_mov_b32 exec_lo, 0xffff0000
	s_mov_b32 exec_hi, 0x0
	v_mov_b32_e32 v164, s0
	v_mov_b32_e32 v166, s1
	v_mov_b32_e32 v168, vcc_lo
	v_mov_b32_e32 v169, vcc_hi
	s_mov_b64 exec, -1
	s_max_i32 s0, s0, 0
	s_max_i32 s1, s1, 0
	s_max_i32 vcc_lo, vcc_lo, 0
	s_max_i32 vcc_hi, vcc_hi, 0
	s_sub_i32 s1, s1, s0
	s_sub_i32 vcc_hi, vcc_hi, vcc_lo
	s_lshl_b32 s0, s0, 9
	s_lshl_b32 s1, s1, 9
	s_lshl_b32 vcc_lo, vcc_lo, 9
	s_lshl_b32 vcc_hi, vcc_hi, 9
	v_add_u32_e32 v96, s0, v246
	v_add_u32_e32 v144, vcc_lo, v246
	v_mad_i32_i24 v96, v115, s1, v96
	v_mad_i32_i24 v144, v115, vcc_hi, v144
	global_load_dwordx4 v[96:99], v96, s[2:3]
	global_load_dwordx4 v[144:147], v144, s[2:3]
	v_readlane_b32 s0, v244, 40
	v_readlane_b32 s1, v244, 41
	v_readlane_b32 vcc_lo, v244, 42
	v_readlane_b32 vcc_hi, v244, 43
	s_mov_b32 exec_lo, 0x0
	s_mov_b32 exec_hi, 0xffff
	v_mov_b32_e32 v164, s0
	v_mov_b32_e32 v166, s1
	v_mov_b32_e32 v168, vcc_lo
	v_mov_b32_e32 v169, vcc_hi
	s_mov_b64 exec, -1
	s_max_i32 s0, s0, 0
	s_max_i32 s1, s1, 0
	s_max_i32 vcc_lo, vcc_lo, 0
	s_max_i32 vcc_hi, vcc_hi, 0
	s_sub_i32 s1, s1, s0
	s_sub_i32 vcc_hi, vcc_hi, vcc_lo
	s_lshl_b32 s0, s0, 9
	s_lshl_b32 s1, s1, 9
	s_lshl_b32 vcc_lo, vcc_lo, 9
	s_lshl_b32 vcc_hi, vcc_hi, 9
	v_add_u32_e32 v152, s0, v246
	v_add_u32_e32 v156, vcc_lo, v246
	v_mad_i32_i24 v152, v115, s1, v152
	v_mad_i32_i24 v156, v115, vcc_hi, v156
	global_load_dwordx4 v[152:155], v152, s[2:3]
	global_load_dwordx4 v[156:159], v156, s[2:3]
	v_readlane_b32 s0, v244, 44
	v_readlane_b32 s1, v244, 45
	v_readlane_b32 vcc_lo, v244, 46
	v_readlane_b32 vcc_hi, v244, 47
	s_mov_b32 exec_lo, 0x0
	s_mov_b32 exec_hi, 0xffff0000
	v_mov_b32_e32 v164, s0
	v_mov_b32_e32 v166, s1
	v_mov_b32_e32 v168, vcc_lo
	v_mov_b32_e32 v169, vcc_hi
	s_mov_b64 exec, -1
	s_max_i32 s0, s0, 0
	s_max_i32 s1, s1, 0
	s_max_i32 vcc_lo, vcc_lo, 0
	s_max_i32 vcc_hi, vcc_hi, 0
	s_sub_i32 s1, s1, s0
	s_sub_i32 vcc_hi, vcc_hi, vcc_lo
	s_lshl_b32 s0, s0, 9
	s_lshl_b32 s1, s1, 9
	s_lshl_b32 vcc_lo, vcc_lo, 9
	s_lshl_b32 vcc_hi, vcc_hi, 9
	v_add_u32_e32 v160, s0, v246
	v_add_u32_e32 v172, vcc_lo, v246
	v_mad_i32_i24 v160, v115, s1, v160
	v_mad_i32_i24 v172, v115, vcc_hi, v172
	global_load_dwordx4 v[160:163], v160, s[2:3]
	global_load_dwordx4 v[172:175], v172, s[2:3]
	v_readlane_b32 s0, v244, 48
	v_readlane_b32 s1, v244, 49
	v_readlane_b32 vcc_lo, v244, 50
	v_readlane_b32 vcc_hi, v244, 51
	s_mov_b32 exec_lo, 0xffff
	s_mov_b32 exec_hi, 0x0
	v_mov_b32_e32 v170, s0
	v_mov_b32_e32 v176, s1
	v_mov_b32_e32 v177, vcc_lo
	v_mov_b32_e32 v191, vcc_hi
	s_mov_b64 exec, -1
	s_max_i32 s0, s0, 0
	s_max_i32 s1, s1, 0
	s_max_i32 vcc_lo, vcc_lo, 0
	s_max_i32 vcc_hi, vcc_hi, 0
	s_sub_i32 s1, s1, s0
	s_sub_i32 vcc_hi, vcc_hi, vcc_lo
	s_lshl_b32 s0, s0, 9
	s_lshl_b32 s1, s1, 9
	s_lshl_b32 vcc_lo, vcc_lo, 9
	s_lshl_b32 vcc_hi, vcc_hi, 9
	v_add_u32_e32 v192, s0, v246
	v_add_u32_e32 v132, vcc_lo, v246
	v_mad_i32_i24 v192, v115, s1, v192
	v_mad_i32_i24 v132, v115, vcc_hi, v132
	global_load_dwordx4 v[192:195], v192, s[2:3]
	global_load_dwordx4 v[132:135], v132, s[2:3]
	v_readlane_b32 s0, v244, 52
	v_readlane_b32 s1, v244, 53
	v_readlane_b32 vcc_lo, v244, 54
	v_readlane_b32 vcc_hi, v244, 55
	s_mov_b32 exec_lo, 0xffff0000
	s_mov_b32 exec_hi, 0x0
	v_mov_b32_e32 v170, s0
	v_mov_b32_e32 v176, s1
	v_mov_b32_e32 v177, vcc_lo
	v_mov_b32_e32 v191, vcc_hi
	s_mov_b64 exec, -1
	s_max_i32 s0, s0, 0
	s_max_i32 s1, s1, 0
	s_max_i32 vcc_lo, vcc_lo, 0
	s_max_i32 vcc_hi, vcc_hi, 0
	s_sub_i32 s1, s1, s0
	s_sub_i32 vcc_hi, vcc_hi, vcc_lo
	s_lshl_b32 s0, s0, 9
	s_lshl_b32 s1, s1, 9
	s_lshl_b32 vcc_lo, vcc_lo, 9
	s_lshl_b32 vcc_hi, vcc_hi, 9
	v_add_u32_e32 v136, s0, v246
	v_add_u32_e32 v140, vcc_lo, v246
	v_mad_i32_i24 v136, v115, s1, v136
	v_mad_i32_i24 v140, v115, vcc_hi, v140
	global_load_dwordx4 v[136:139], v136, s[2:3]
	global_load_dwordx4 v[140:143], v140, s[2:3]
	v_readlane_b32 s0, v244, 56
	v_readlane_b32 s1, v244, 57
	v_readlane_b32 vcc_lo, v244, 58
	v_readlane_b32 vcc_hi, v244, 59
	s_mov_b32 exec_lo, 0x0
	s_mov_b32 exec_hi, 0xffff
	v_mov_b32_e32 v170, s0
	v_mov_b32_e32 v176, s1
	v_mov_b32_e32 v177, vcc_lo
	v_mov_b32_e32 v191, vcc_hi
	s_mov_b64 exec, -1
	s_max_i32 s0, s0, 0
	s_max_i32 s1, s1, 0
	s_max_i32 vcc_lo, vcc_lo, 0
	s_max_i32 vcc_hi, vcc_hi, 0
	s_sub_i32 s1, s1, s0
	s_sub_i32 vcc_hi, vcc_hi, vcc_lo
	s_lshl_b32 s0, s0, 9
	s_lshl_b32 s1, s1, 9
	s_lshl_b32 vcc_lo, vcc_lo, 9
	s_lshl_b32 vcc_hi, vcc_hi, 9
	v_add_u32_e32 v228, s0, v246
	v_add_u32_e32 v232, vcc_lo, v246
	v_mad_i32_i24 v228, v115, s1, v228
	v_mad_i32_i24 v232, v115, vcc_hi, v232
	global_load_dwordx4 v[228:231], v228, s[2:3]
	global_load_dwordx4 v[232:235], v232, s[2:3]
	v_readlane_b32 s0, v244, 60
	v_readlane_b32 s1, v244, 61
	v_readlane_b32 vcc_lo, v244, 62
	v_readlane_b32 vcc_hi, v244, 63
	s_mov_b32 exec_lo, 0x0
	s_mov_b32 exec_hi, 0xffff0000
	v_mov_b32_e32 v170, s0
	v_mov_b32_e32 v176, s1
	v_mov_b32_e32 v177, vcc_lo
	v_mov_b32_e32 v191, vcc_hi
	s_mov_b64 exec, -1
	s_max_i32 s0, s0, 0
	s_max_i32 s1, s1, 0
	s_max_i32 vcc_lo, vcc_lo, 0
	s_max_i32 vcc_hi, vcc_hi, 0
	s_sub_i32 s1, s1, s0
	s_sub_i32 vcc_hi, vcc_hi, vcc_lo
	s_lshl_b32 s0, s0, 9
	s_lshl_b32 s1, s1, 9
	s_lshl_b32 vcc_lo, vcc_lo, 9
	s_lshl_b32 vcc_hi, vcc_hi, 9
	v_add_u32_e32 v236, s0, v246
	v_add_u32_e32 v240, vcc_lo, v246
	v_mad_i32_i24 v236, v115, s1, v236
	v_mad_i32_i24 v240, v115, vcc_hi, v240
	global_load_dwordx4 v[236:239], v236, s[2:3]
	global_load_dwordx4 v[240:243], v240, s[2:3]

.LBB0_149:
	s_lshl_b32 s1, s2, 3
	s_lshl_b32 s0, s3, 12
	s_add_i32 s27, s0, s1
	s_ashr_i32 s38, s2, 3
	v_lshrrev_b32_e32 v33, 4, v34
	v_lshlrev_b32_e32 v33, 4, v33
	v_and_b32_e32 v191, 15, v34
	v_lshl_or_b32 v191, v191, 6, v33
	s_lshl_b32 s4, s22, 9
	s_add_i32 s4, s4, 0x22000
	v_add_u32_e32 v164, s4, v33
	v_lshlrev_b32_e32 v166, 10, v33
	v_and_b32_e32 v169, 15, v34
	s_lshl_b32 s4, s22, 6
	v_lshl_add_u32 v166, v169, 2, v166
	v_add_u32_e32 v166, s4, v166
	s_lshl_b32 s4, s22, 8
	s_add_i32 s4, s4, 0x23000
	v_lshl_add_u32 v168, v34, 2, s4
	v_readlane_b32 s4, v253, 11
	v_readlane_b32 s5, v253, 12
	v_readlane_b32 s28, v253, 40
	v_readlane_b32 s29, v253, 41
	v_readlane_b32 s6, v253, 38
	v_readlane_b32 s7, v253, 39
	s_add_u32 s4, s4, 0x1d302200
	s_addc_u32 s5, s5, 0
	s_lshl_b32 s0, s27, 6
	s_add_u32 s28, s28, s0
	s_addc_u32 s29, s29, 0
	s_lshl_b32 s0, s3, 20
	s_lshl_b32 s1, s22, 12
	s_add_u32 s6, s6, s0
	s_addc_u32 s7, s7, 0
	s_add_u32 s6, s6, s1
	s_addc_u32 s7, s7, 0
	global_load_dwordx4 v[196:199], v33, s[28:29]
	global_load_dwordx4 v[200:203], v33, s[28:29] offset:64
	global_load_dwordx4 v[204:207], v33, s[28:29] offset:128
	global_load_dwordx4 v[208:211], v33, s[28:29] offset:192
	global_load_dwordx4 v[212:215], v33, s[28:29] offset:256
	global_load_dwordx4 v[216:219], v33, s[28:29] offset:320
	global_load_dwordx4 v[220:223], v33, s[28:29] offset:384
	global_load_dwordx4 v[224:227], v33, s[28:29] offset:448
	v_and_b32_e32 v9, 15, v34
	v_lshrrev_b32_e32 v10, 4, v34
	v_add_u32_e32 v11, 0, v10
	v_xor_b32_e32 v11, v11, v9
	v_lshlrev_b32_e32 v11, 4, v11
	v_lshl_add_u32 v0, v10, 8, v11
	v_add_u32_e32 v0, 0x18000, v0
	v_add_u32_e32 v11, 4, v10
	v_xor_b32_e32 v11, v11, v9
	v_lshlrev_b32_e32 v11, 4, v11
	v_lshl_add_u32 v1, v10, 8, v11
	v_add_u32_e32 v1, 0x18400, v1
	v_add_u32_e32 v11, 8, v10
	v_xor_b32_e32 v11, v11, v9
	v_lshlrev_b32_e32 v11, 4, v11
	v_lshl_add_u32 v2, v10, 8, v11
	v_add_u32_e32 v2, 0x18800, v2
	v_add_u32_e32 v11, 12, v10
	v_xor_b32_e32 v11, v11, v9
	v_lshlrev_b32_e32 v11, 4, v11
	v_lshl_add_u32 v3, v10, 8, v11
	v_add_u32_e32 v3, 0x18c00, v3
	v_lshrrev_b32_e32 v12, 2, v9
	v_and_b32_e32 v13, 3, v9
	v_xor_b32_e32 v14, v10, v13
	v_lshlrev_b32_e32 v15, 10, v12
	v_lshl_add_u32 v15, v13, 8, v15
	s_lshl_b32 s0, s22, 12
	s_add_i32 s0, s0, 0x18000
	v_add_u32_e32 v15, s0, v15
	v_xor_b32_e32 v16, 0, v12
	v_lshl_add_u32 v16, v16, 2, v14
	v_lshl_add_u32 v4, v16, 4, v15
	v_xor_b32_e32 v16, 1, v12
	v_lshl_add_u32 v16, v16, 2, v14
	v_lshl_add_u32 v5, v16, 4, v15
	v_xor_b32_e32 v16, 2, v12
	v_lshl_add_u32 v16, v16, 2, v14
	v_lshl_add_u32 v6, v16, 4, v15
	v_xor_b32_e32 v16, 3, v12
	v_lshl_add_u32 v16, v16, 2, v14
	v_lshl_add_u32 v7, v16, 4, v15
	v_lshlrev_b32_e32 v35, 4, v34
	s_cmp_lg_u32 s82, 0
	s_cbranch_scc1 .Lix_skipA
	s_add_i32 s30, s27, s22
	s_mul_i32 s30, s30, 0x3400
	s_add_u32 s30, s4, s30
	s_addc_u32 s31, s5, 0
	global_load_dwordx4 v[40:43], v35, s[30:31]
	global_load_dwordx4 v[44:47], v35, s[30:31] offset:1024
	global_load_dwordx4 v[48:51], v35, s[30:31] offset:2048
	global_load_dwordx4 v[52:55], v35, s[30:31] offset:3072
.Lix_skipA:
	s_waitcnt vmcnt(0)
	ds_write_b128 v4, v[40:43]
	ds_write_b128 v5, v[44:47]
	ds_write_b128 v6, v[48:51]
	ds_write_b128 v7, v[52:55]
	ds_write_b128 v164, v[196:199]
	ds_write_b128 v164, v[200:203] offset:64
	ds_write_b128 v164, v[204:207] offset:128
	ds_write_b128 v164, v[208:211] offset:192
	ds_write_b128 v164, v[212:215] offset:256
	ds_write_b128 v164, v[216:219] offset:320
	ds_write_b128 v164, v[220:223] offset:384
	ds_write_b128 v164, v[224:227] offset:448
	s_waitcnt lgkmcnt(0)
	s_barrier
	ds_read_b128 v[40:43], v0
	ds_read_b128 v[44:47], v1
	ds_read_b128 v[48:51], v2
	ds_read_b128 v[52:55], v3
	ds_read_b128 v[56:59], v0 offset:4096
	ds_read_b128 v[60:63], v1 offset:4096
	ds_read_b128 v[64:67], v2 offset:4096
	ds_read_b128 v[68:71], v3 offset:4096
	ds_read_b128 v[72:75], v0 offset:8192
	ds_read_b128 v[76:79], v1 offset:8192
	ds_read_b128 v[80:83], v2 offset:8192
	ds_read_b128 v[84:87], v3 offset:8192
	ds_read_b128 v[88:91], v0 offset:12288
	ds_read_b128 v[92:95], v1 offset:12288
	ds_read_b128 v[96:99], v2 offset:12288
	ds_read_b128 v[100:103], v3 offset:12288
	ds_read_b128 v[104:107], v0 offset:16384
	ds_read_b128 v[108:111], v1 offset:16384
	ds_read_b128 v[112:115], v2 offset:16384
	ds_read_b128 v[116:119], v3 offset:16384
	ds_read_b128 v[120:123], v0 offset:20480
	ds_read_b128 v[124:127], v1 offset:20480
	ds_read_b128 v[128:131], v2 offset:20480
	ds_read_b128 v[132:135], v3 offset:20480
	ds_read_b128 v[136:139], v0 offset:24576
	ds_read_b128 v[140:143], v1 offset:24576
	ds_read_b128 v[144:147], v2 offset:24576
	ds_read_b128 v[148:151], v3 offset:24576
	ds_read_b128 v[152:155], v0 offset:28672
	ds_read_b128 v[156:159], v1 offset:28672
	ds_read_b128 v[160:163], v2 offset:28672
	ds_read_b128 v[192:195], v3 offset:28672
	s_lshl_b32 s36, s38, 2
	s_add_i32 s36, s36, 11
	s_sub_i32 s36, s36, s22
	s_lshr_b32 s36, s36, 3
	global_load_dwordx4 v[196:199], v191, s[6:7]
	global_load_dwordx4 v[200:203], v191, s[6:7] offset:1024
	global_load_dwordx4 v[204:207], v191, s[6:7] offset:2048
	global_load_dwordx4 v[208:211], v191, s[6:7] offset:3072
	s_add_u32 s6, s6, 0x8000
	s_addc_u32 s7, s7, 0
	global_load_dwordx4 v[212:215], v191, s[6:7]
	global_load_dwordx4 v[216:219], v191, s[6:7] offset:1024
	global_load_dwordx4 v[220:223], v191, s[6:7] offset:2048
	global_load_dwordx4 v[224:227], v191, s[6:7] offset:3072
	s_add_u32 s6, s6, 0x8000
	s_addc_u32 s7, s7, 0
	global_load_dwordx4 v[228:231], v191, s[6:7]
	global_load_dwordx4 v[232:235], v191, s[6:7] offset:1024
	global_load_dwordx4 v[236:239], v191, s[6:7] offset:2048
	global_load_dwordx4 v[240:243], v191, s[6:7] offset:3072
	s_add_u32 s6, s6, 0x8000
	s_addc_u32 s7, s7, 0
	s_waitcnt lgkmcnt(0)
	s_barrier
	ds_read_b128 v[172:175], v164 offset:256
	ds_read_b128 v[244:247], v164 offset:320
.Lix_loop:
	s_cmp_eq_u32 s36, 0
	s_cbranch_scc1 .Lix_done
	s_waitcnt vmcnt(8)
	v_mfma_f32_16x16x32_bf16 v[0:3], v[40:43], v[196:199], 0
	s_waitcnt lgkmcnt(1)
	v_max_f32_e32 v16, 0, v16
	v_max_f32_e32 v17, 0, v17
	v_max_f32_e32 v18, 0, v18
	v_mfma_f32_16x16x32_bf16 v[4:7], v[56:59], v[196:199], 0
	v_max_f32_e32 v19, 0, v19
	v_mul_f32_e32 v169, v172, v16
	v_fmac_f32_e32 v169, v173, v17
	v_fmac_f32_e32 v169, v174, v18
	v_mfma_f32_16x16x32_bf16 v[8:11], v[72:75], v[196:199], 0
	v_fmac_f32_e32 v169, v175, v19
	ds_read_b128 v[172:175], v164 offset:384
	s_waitcnt lgkmcnt(1)
	v_max_f32_e32 v20, 0, v20
	v_mfma_f32_16x16x32_bf16 v[12:15], v[88:91], v[196:199], 0
	v_max_f32_e32 v21, 0, v21
	v_max_f32_e32 v22, 0, v22
	v_max_f32_e32 v23, 0, v23
	v_mul_f32_e32 v170, v244, v20
	v_mfma_f32_16x16x32_bf16 v[0:3], v[44:47], v[200:203], v[0:3]
	v_fmac_f32_e32 v170, v245, v21
	v_fmac_f32_e32 v170, v246, v22
	v_fmac_f32_e32 v170, v247, v23
	ds_read_b128 v[244:247], v164 offset:448
	v_mfma_f32_16x16x32_bf16 v[4:7], v[60:63], v[200:203], v[4:7]
	s_waitcnt lgkmcnt(1)
	v_max_f32_e32 v24, 0, v24
	v_max_f32_e32 v25, 0, v25
	v_max_f32_e32 v26, 0, v26
	v_mfma_f32_16x16x32_bf16 v[8:11], v[76:79], v[200:203], v[8:11]
	v_max_f32_e32 v27, 0, v27
	v_mul_f32_e32 v176, v172, v24
	v_fmac_f32_e32 v176, v173, v25
	v_fmac_f32_e32 v176, v174, v26
	v_mfma_f32_16x16x32_bf16 v[12:15], v[92:95], v[200:203], v[12:15]
	v_fmac_f32_e32 v176, v175, v27
	s_waitcnt lgkmcnt(0)
	v_max_f32_e32 v28, 0, v28
	v_max_f32_e32 v29, 0, v29
	v_mfma_f32_16x16x32_bf16 v[0:3], v[48:51], v[204:207], v[0:3]
	v_max_f32_e32 v30, 0, v30
	v_max_f32_e32 v31, 0, v31
	v_mul_f32_e32 v177, v244, v28
	v_fmac_f32_e32 v177, v245, v29
	v_mfma_f32_16x16x32_bf16 v[4:7], v[64:67], v[204:207], v[4:7]
	v_fmac_f32_e32 v177, v246, v30
	v_fmac_f32_e32 v177, v247, v31
	s_nop 1
	v_permlane16_swap_b32 v169, v170
	v_mfma_f32_16x16x32_bf16 v[8:11], v[80:83], v[204:207], v[8:11]
	v_permlane16_swap_b32 v176, v177
	v_add_f32_e32 v169, v169, v170
	v_add_f32_e32 v176, v176, v177
	s_nop 1
	v_mfma_f32_16x16x32_bf16 v[12:15], v[96:99], v[204:207], v[12:15]
	v_permlane32_swap_b32 v169, v176
	v_add_f32_e32 v169, v169, v176
	ds_write_b32 v168, v169
	ds_read_b128 v[172:175], v164
	v_mfma_f32_16x16x32_bf16 v[0:3], v[52:55], v[208:211], v[0:3]
	ds_read_b128 v[244:247], v164 offset:64
	v_mfma_f32_16x16x32_bf16 v[4:7], v[68:71], v[208:211], v[4:7]
	v_mfma_f32_16x16x32_bf16 v[8:11], v[84:87], v[208:211], v[8:11]
	v_mfma_f32_16x16x32_bf16 v[12:15], v[100:103], v[208:211], v[12:15]
	v_mfma_f32_16x16x32_bf16 v[16:19], v[104:107], v[196:199], 0
	s_waitcnt lgkmcnt(1)
	v_max_f32_e32 v0, 0, v0
	v_max_f32_e32 v1, 0, v1
	v_max_f32_e32 v2, 0, v2
	v_mfma_f32_16x16x32_bf16 v[20:23], v[120:123], v[196:199], 0
	v_max_f32_e32 v3, 0, v3
	v_mul_f32_e32 v169, v172, v0
	v_fmac_f32_e32 v169, v173, v1
	v_fmac_f32_e32 v169, v174, v2
	v_mfma_f32_16x16x32_bf16 v[24:27], v[136:139], v[196:199], 0
	v_fmac_f32_e32 v169, v175, v3
	ds_read_b128 v[172:175], v164 offset:128
	s_waitcnt lgkmcnt(1)
	v_max_f32_e32 v4, 0, v4
	v_mfma_f32_16x16x32_bf16 v[28:31], v[152:155], v[196:199], 0
	v_max_f32_e32 v5, 0, v5
	v_max_f32_e32 v6, 0, v6
	v_max_f32_e32 v7, 0, v7
	v_mul_f32_e32 v170, v244, v4
	v_mfma_f32_16x16x32_bf16 v[16:19], v[108:111], v[200:203], v[16:19]
	v_fmac_f32_e32 v170, v245, v5
	v_fmac_f32_e32 v170, v246, v6
	v_fmac_f32_e32 v170, v247, v7
	ds_read_b128 v[244:247], v164 offset:192
	v_mfma_f32_16x16x32_bf16 v[20:23], v[124:127], v[200:203], v[20:23]
	s_waitcnt lgkmcnt(1)
	v_max_f32_e32 v8, 0, v8
	v_max_f32_e32 v9, 0, v9
	v_max_f32_e32 v10, 0, v10
	v_mfma_f32_16x16x32_bf16 v[24:27], v[140:143], v[200:203], v[24:27]
	v_max_f32_e32 v11, 0, v11
	v_mul_f32_e32 v176, v172, v8
	v_fmac_f32_e32 v176, v173, v9
	v_fmac_f32_e32 v176, v174, v10
	v_mfma_f32_16x16x32_bf16 v[28:31], v[156:159], v[200:203], v[28:31]
	v_fmac_f32_e32 v176, v175, v11
	s_waitcnt lgkmcnt(0)
	v_max_f32_e32 v12, 0, v12
	v_max_f32_e32 v13, 0, v13
	v_mfma_f32_16x16x32_bf16 v[16:19], v[112:115], v[204:207], v[16:19]
	v_max_f32_e32 v14, 0, v14
	v_max_f32_e32 v15, 0, v15
	v_mul_f32_e32 v177, v244, v12
	v_fmac_f32_e32 v177, v245, v13
	v_mfma_f32_16x16x32_bf16 v[20:23], v[128:131], v[204:207], v[20:23]
	v_fmac_f32_e32 v177, v246, v14
	v_fmac_f32_e32 v177, v247, v15
	s_nop 1
	v_permlane16_swap_b32 v169, v170
	v_mfma_f32_16x16x32_bf16 v[24:27], v[144:147], v[204:207], v[24:27]
	v_permlane16_swap_b32 v176, v177
	v_add_f32_e32 v169, v169, v170
	v_add_f32_e32 v176, v176, v177
	s_nop 1
	v_mfma_f32_16x16x32_bf16 v[28:31], v[160:163], v[204:207], v[28:31]
	v_permlane32_swap_b32 v169, v176
	v_add_f32_e32 v169, v169, v176
	ds_write_b32 v166, v169
	ds_read_b128 v[172:175], v164 offset:256
	v_mfma_f32_16x16x32_bf16 v[16:19], v[116:119], v[208:211], v[16:19]
	ds_read_b128 v[244:247], v164 offset:320
	v_mfma_f32_16x16x32_bf16 v[20:23], v[132:135], v[208:211], v[20:23]
	v_mfma_f32_16x16x32_bf16 v[24:27], v[148:151], v[208:211], v[24:27]
	v_mfma_f32_16x16x32_bf16 v[28:31], v[192:195], v[208:211], v[28:31]
	global_load_dwordx4 v[196:199], v191, s[6:7]
	global_load_dwordx4 v[200:203], v191, s[6:7] offset:1024
	global_load_dwordx4 v[204:207], v191, s[6:7] offset:2048
	global_load_dwordx4 v[208:211], v191, s[6:7] offset:3072
	s_add_u32 s6, s6, 0x8000
	s_addc_u32 s7, s7, 0
	v_add_u32_e32 v168, 0x10000, v166
	v_add_u32_e32 v166, 0x200, v166
	s_add_i32 s36, s36, -1
	s_cmp_eq_u32 s36, 0
	s_cbranch_scc1 .Lix_done
	s_waitcnt vmcnt(8)
	v_mfma_f32_16x16x32_bf16 v[0:3], v[40:43], v[212:215], 0
	s_waitcnt lgkmcnt(1)
	v_max_f32_e32 v16, 0, v16
	v_max_f32_e32 v17, 0, v17
	v_max_f32_e32 v18, 0, v18
	v_mfma_f32_16x16x32_bf16 v[4:7], v[56:59], v[212:215], 0
	v_max_f32_e32 v19, 0, v19
	v_mul_f32_e32 v169, v172, v16
	v_fmac_f32_e32 v169, v173, v17
	v_fmac_f32_e32 v169, v174, v18
	v_mfma_f32_16x16x32_bf16 v[8:11], v[72:75], v[212:215], 0
	v_fmac_f32_e32 v169, v175, v19
	ds_read_b128 v[172:175], v164 offset:384
	s_waitcnt lgkmcnt(1)
	v_max_f32_e32 v20, 0, v20
	v_mfma_f32_16x16x32_bf16 v[12:15], v[88:91], v[212:215], 0
	v_max_f32_e32 v21, 0, v21
	v_max_f32_e32 v22, 0, v22
	v_max_f32_e32 v23, 0, v23
	v_mul_f32_e32 v170, v244, v20
	v_mfma_f32_16x16x32_bf16 v[0:3], v[44:47], v[216:219], v[0:3]
	v_fmac_f32_e32 v170, v245, v21
	v_fmac_f32_e32 v170, v246, v22
	v_fmac_f32_e32 v170, v247, v23
	ds_read_b128 v[244:247], v164 offset:448
	v_mfma_f32_16x16x32_bf16 v[4:7], v[60:63], v[216:219], v[4:7]
	s_waitcnt lgkmcnt(1)
	v_max_f32_e32 v24, 0, v24
	v_max_f32_e32 v25, 0, v25
	v_max_f32_e32 v26, 0, v26
	v_mfma_f32_16x16x32_bf16 v[8:11], v[76:79], v[216:219], v[8:11]
	v_max_f32_e32 v27, 0, v27
	v_mul_f32_e32 v176, v172, v24
	v_fmac_f32_e32 v176, v173, v25
	v_fmac_f32_e32 v176, v174, v26
	v_mfma_f32_16x16x32_bf16 v[12:15], v[92:95], v[216:219], v[12:15]
	v_fmac_f32_e32 v176, v175, v27
	s_waitcnt lgkmcnt(0)
	v_max_f32_e32 v28, 0, v28
	v_max_f32_e32 v29, 0, v29
	v_mfma_f32_16x16x32_bf16 v[0:3], v[48:51], v[220:223], v[0:3]
	v_max_f32_e32 v30, 0, v30
	v_max_f32_e32 v31, 0, v31
	v_mul_f32_e32 v177, v244, v28
	v_fmac_f32_e32 v177, v245, v29
	v_mfma_f32_16x16x32_bf16 v[4:7], v[64:67], v[220:223], v[4:7]
	v_fmac_f32_e32 v177, v246, v30
	v_fmac_f32_e32 v177, v247, v31
	s_nop 1
	v_permlane16_swap_b32 v169, v170
	v_mfma_f32_16x16x32_bf16 v[8:11], v[80:83], v[220:223], v[8:11]
	v_permlane16_swap_b32 v176, v177
	v_add_f32_e32 v169, v169, v170
	v_add_f32_e32 v176, v176, v177
	s_nop 1
	v_mfma_f32_16x16x32_bf16 v[12:15], v[96:99], v[220:223], v[12:15]
	v_permlane32_swap_b32 v169, v176
	v_add_f32_e32 v169, v169, v176
	ds_write_b32 v168, v169
	ds_read_b128 v[172:175], v164
	v_mfma_f32_16x16x32_bf16 v[0:3], v[52:55], v[224:227], v[0:3]
	ds_read_b128 v[244:247], v164 offset:64
	v_mfma_f32_16x16x32_bf16 v[4:7], v[68:71], v[224:227], v[4:7]
	v_mfma_f32_16x16x32_bf16 v[8:11], v[84:87], v[224:227], v[8:11]
	v_mfma_f32_16x16x32_bf16 v[12:15], v[100:103], v[224:227], v[12:15]
	v_mfma_f32_16x16x32_bf16 v[16:19], v[104:107], v[212:215], 0
	s_waitcnt lgkmcnt(1)
	v_max_f32_e32 v0, 0, v0
	v_max_f32_e32 v1, 0, v1
	v_max_f32_e32 v2, 0, v2
	v_mfma_f32_16x16x32_bf16 v[20:23], v[120:123], v[212:215], 0
	v_max_f32_e32 v3, 0, v3
	v_mul_f32_e32 v169, v172, v0
	v_fmac_f32_e32 v169, v173, v1
	v_fmac_f32_e32 v169, v174, v2
	v_mfma_f32_16x16x32_bf16 v[24:27], v[136:139], v[212:215], 0
	v_fmac_f32_e32 v169, v175, v3
	ds_read_b128 v[172:175], v164 offset:128
	s_waitcnt lgkmcnt(1)
	v_max_f32_e32 v4, 0, v4
	v_mfma_f32_16x16x32_bf16 v[28:31], v[152:155], v[212:215], 0
	v_max_f32_e32 v5, 0, v5
	v_max_f32_e32 v6, 0, v6
	v_max_f32_e32 v7, 0, v7
	v_mul_f32_e32 v170, v244, v4
	v_mfma_f32_16x16x32_bf16 v[16:19], v[108:111], v[216:219], v[16:19]
	v_fmac_f32_e32 v170, v245, v5
	v_fmac_f32_e32 v170, v246, v6
	v_fmac_f32_e32 v170, v247, v7
	ds_read_b128 v[244:247], v164 offset:192
	v_mfma_f32_16x16x32_bf16 v[20:23], v[124:127], v[216:219], v[20:23]
	s_waitcnt lgkmcnt(1)
	v_max_f32_e32 v8, 0, v8
	v_max_f32_e32 v9, 0, v9
	v_max_f32_e32 v10, 0, v10
	v_mfma_f32_16x16x32_bf16 v[24:27], v[140:143], v[216:219], v[24:27]
	v_max_f32_e32 v11, 0, v11
	v_mul_f32_e32 v176, v172, v8
	v_fmac_f32_e32 v176, v173, v9
	v_fmac_f32_e32 v176, v174, v10
	v_mfma_f32_16x16x32_bf16 v[28:31], v[156:159], v[216:219], v[28:31]
	v_fmac_f32_e32 v176, v175, v11
	s_waitcnt lgkmcnt(0)
	v_max_f32_e32 v12, 0, v12
	v_max_f32_e32 v13, 0, v13
	v_mfma_f32_16x16x32_bf16 v[16:19], v[112:115], v[220:223], v[16:19]
	v_max_f32_e32 v14, 0, v14
	v_max_f32_e32 v15, 0, v15
	v_mul_f32_e32 v177, v244, v12
	v_fmac_f32_e32 v177, v245, v13
	v_mfma_f32_16x16x32_bf16 v[20:23], v[128:131], v[220:223], v[20:23]
	v_fmac_f32_e32 v177, v246, v14
	v_fmac_f32_e32 v177, v247, v15
	s_nop 1
	v_permlane16_swap_b32 v169, v170
	v_mfma_f32_16x16x32_bf16 v[24:27], v[144:147], v[220:223], v[24:27]
	v_permlane16_swap_b32 v176, v177
	v_add_f32_e32 v169, v169, v170
	v_add_f32_e32 v176, v176, v177
	s_nop 1
	v_mfma_f32_16x16x32_bf16 v[28:31], v[160:163], v[220:223], v[28:31]
	v_permlane32_swap_b32 v169, v176
	v_add_f32_e32 v169, v169, v176
	ds_write_b32 v166, v169
	ds_read_b128 v[172:175], v164 offset:256
	v_mfma_f32_16x16x32_bf16 v[16:19], v[116:119], v[224:227], v[16:19]
	ds_read_b128 v[244:247], v164 offset:320
	v_mfma_f32_16x16x32_bf16 v[20:23], v[132:135], v[224:227], v[20:23]
	v_mfma_f32_16x16x32_bf16 v[24:27], v[148:151], v[224:227], v[24:27]
	v_mfma_f32_16x16x32_bf16 v[28:31], v[192:195], v[224:227], v[28:31]
	global_load_dwordx4 v[212:215], v191, s[6:7]
	global_load_dwordx4 v[216:219], v191, s[6:7] offset:1024
	global_load_dwordx4 v[220:223], v191, s[6:7] offset:2048
	global_load_dwordx4 v[224:227], v191, s[6:7] offset:3072
	s_add_u32 s6, s6, 0x8000
	s_addc_u32 s7, s7, 0
	v_add_u32_e32 v168, 0x10000, v166
	v_add_u32_e32 v166, 0x200, v166
	s_add_i32 s36, s36, -1
	s_cmp_eq_u32 s36, 0
	s_cbranch_scc1 .Lix_done
	s_waitcnt vmcnt(8)
	v_mfma_f32_16x16x32_bf16 v[0:3], v[40:43], v[228:231], 0
	s_waitcnt lgkmcnt(1)
	v_max_f32_e32 v16, 0, v16
	v_max_f32_e32 v17, 0, v17
	v_max_f32_e32 v18, 0, v18
	v_mfma_f32_16x16x32_bf16 v[4:7], v[56:59], v[228:231], 0
	v_max_f32_e32 v19, 0, v19
	v_mul_f32_e32 v169, v172, v16
	v_fmac_f32_e32 v169, v173, v17
	v_fmac_f32_e32 v169, v174, v18
	v_mfma_f32_16x16x32_bf16 v[8:11], v[72:75], v[228:231], 0
	v_fmac_f32_e32 v169, v175, v19
	ds_read_b128 v[172:175], v164 offset:384
	s_waitcnt lgkmcnt(1)
	v_max_f32_e32 v20, 0, v20
	v_mfma_f32_16x16x32_bf16 v[12:15], v[88:91], v[228:231], 0
	v_max_f32_e32 v21, 0, v21
	v_max_f32_e32 v22, 0, v22
	v_max_f32_e32 v23, 0, v23
	v_mul_f32_e32 v170, v244, v20
	v_mfma_f32_16x16x32_bf16 v[0:3], v[44:47], v[232:235], v[0:3]
	v_fmac_f32_e32 v170, v245, v21
	v_fmac_f32_e32 v170, v246, v22
	v_fmac_f32_e32 v170, v247, v23
	ds_read_b128 v[244:247], v164 offset:448
	v_mfma_f32_16x16x32_bf16 v[4:7], v[60:63], v[232:235], v[4:7]
	s_waitcnt lgkmcnt(1)
	v_max_f32_e32 v24, 0, v24
	v_max_f32_e32 v25, 0, v25
	v_max_f32_e32 v26, 0, v26
	v_mfma_f32_16x16x32_bf16 v[8:11], v[76:79], v[232:235], v[8:11]
	v_max_f32_e32 v27, 0, v27
	v_mul_f32_e32 v176, v172, v24
	v_fmac_f32_e32 v176, v173, v25
	v_fmac_f32_e32 v176, v174, v26
	v_mfma_f32_16x16x32_bf16 v[12:15], v[92:95], v[232:235], v[12:15]
	v_fmac_f32_e32 v176, v175, v27
	s_waitcnt lgkmcnt(0)
	v_max_f32_e32 v28, 0, v28
	v_max_f32_e32 v29, 0, v29
	v_mfma_f32_16x16x32_bf16 v[0:3], v[48:51], v[236:239], v[0:3]
	v_max_f32_e32 v30, 0, v30
	v_max_f32_e32 v31, 0, v31
	v_mul_f32_e32 v177, v244, v28
	v_fmac_f32_e32 v177, v245, v29
	v_mfma_f32_16x16x32_bf16 v[4:7], v[64:67], v[236:239], v[4:7]
	v_fmac_f32_e32 v177, v246, v30
	v_fmac_f32_e32 v177, v247, v31
	s_nop 1
	v_permlane16_swap_b32 v169, v170
	v_mfma_f32_16x16x32_bf16 v[8:11], v[80:83], v[236:239], v[8:11]
	v_permlane16_swap_b32 v176, v177
	v_add_f32_e32 v169, v169, v170
	v_add_f32_e32 v176, v176, v177
	s_nop 1
	v_mfma_f32_16x16x32_bf16 v[12:15], v[96:99], v[236:239], v[12:15]
	v_permlane32_swap_b32 v169, v176
	v_add_f32_e32 v169, v169, v176
	ds_write_b32 v168, v169
	ds_read_b128 v[172:175], v164
	v_mfma_f32_16x16x32_bf16 v[0:3], v[52:55], v[240:243], v[0:3]
	ds_read_b128 v[244:247], v164 offset:64
	v_mfma_f32_16x16x32_bf16 v[4:7], v[68:71], v[240:243], v[4:7]
	v_mfma_f32_16x16x32_bf16 v[8:11], v[84:87], v[240:243], v[8:11]
	v_mfma_f32_16x16x32_bf16 v[12:15], v[100:103], v[240:243], v[12:15]
	v_mfma_f32_16x16x32_bf16 v[16:19], v[104:107], v[228:231], 0
	s_waitcnt lgkmcnt(1)
	v_max_f32_e32 v0, 0, v0
	v_max_f32_e32 v1, 0, v1
	v_max_f32_e32 v2, 0, v2
	v_mfma_f32_16x16x32_bf16 v[20:23], v[120:123], v[228:231], 0
	v_max_f32_e32 v3, 0, v3
	v_mul_f32_e32 v169, v172, v0
	v_fmac_f32_e32 v169, v173, v1
	v_fmac_f32_e32 v169, v174, v2
	v_mfma_f32_16x16x32_bf16 v[24:27], v[136:139], v[228:231], 0
	v_fmac_f32_e32 v169, v175, v3
	ds_read_b128 v[172:175], v164 offset:128
	s_waitcnt lgkmcnt(1)
	v_max_f32_e32 v4, 0, v4
	v_mfma_f32_16x16x32_bf16 v[28:31], v[152:155], v[228:231], 0
	v_max_f32_e32 v5, 0, v5
	v_max_f32_e32 v6, 0, v6
	v_max_f32_e32 v7, 0, v7
	v_mul_f32_e32 v170, v244, v4
	v_mfma_f32_16x16x32_bf16 v[16:19], v[108:111], v[232:235], v[16:19]
	v_fmac_f32_e32 v170, v245, v5
	v_fmac_f32_e32 v170, v246, v6
	v_fmac_f32_e32 v170, v247, v7
	ds_read_b128 v[244:247], v164 offset:192
	v_mfma_f32_16x16x32_bf16 v[20:23], v[124:127], v[232:235], v[20:23]
	s_waitcnt lgkmcnt(1)
	v_max_f32_e32 v8, 0, v8
	v_max_f32_e32 v9, 0, v9
	v_max_f32_e32 v10, 0, v10
	v_mfma_f32_16x16x32_bf16 v[24:27], v[140:143], v[232:235], v[24:27]
	v_max_f32_e32 v11, 0, v11
	v_mul_f32_e32 v176, v172, v8
	v_fmac_f32_e32 v176, v173, v9
	v_fmac_f32_e32 v176, v174, v10
	v_mfma_f32_16x16x32_bf16 v[28:31], v[156:159], v[232:235], v[28:31]
	v_fmac_f32_e32 v176, v175, v11
	s_waitcnt lgkmcnt(0)
	v_max_f32_e32 v12, 0, v12
	v_max_f32_e32 v13, 0, v13
	v_mfma_f32_16x16x32_bf16 v[16:19], v[112:115], v[236:239], v[16:19]
	v_max_f32_e32 v14, 0, v14
	v_max_f32_e32 v15, 0, v15
	v_mul_f32_e32 v177, v244, v12
	v_fmac_f32_e32 v177, v245, v13
	v_mfma_f32_16x16x32_bf16 v[20:23], v[128:131], v[236:239], v[20:23]
	v_fmac_f32_e32 v177, v246, v14
	v_fmac_f32_e32 v177, v247, v15
	s_nop 1
	v_permlane16_swap_b32 v169, v170
	v_mfma_f32_16x16x32_bf16 v[24:27], v[144:147], v[236:239], v[24:27]
	v_permlane16_swap_b32 v176, v177
	v_add_f32_e32 v169, v169, v170
	v_add_f32_e32 v176, v176, v177
	s_nop 1
	v_mfma_f32_16x16x32_bf16 v[28:31], v[160:163], v[236:239], v[28:31]
	v_permlane32_swap_b32 v169, v176
	v_add_f32_e32 v169, v169, v176
	ds_write_b32 v166, v169
	ds_read_b128 v[172:175], v164 offset:256
	v_mfma_f32_16x16x32_bf16 v[16:19], v[116:119], v[240:243], v[16:19]
	ds_read_b128 v[244:247], v164 offset:320
	v_mfma_f32_16x16x32_bf16 v[20:23], v[132:135], v[240:243], v[20:23]
	v_mfma_f32_16x16x32_bf16 v[24:27], v[148:151], v[240:243], v[24:27]
	v_mfma_f32_16x16x32_bf16 v[28:31], v[192:195], v[240:243], v[28:31]
	global_load_dwordx4 v[228:231], v191, s[6:7]
	global_load_dwordx4 v[232:235], v191, s[6:7] offset:1024
	global_load_dwordx4 v[236:239], v191, s[6:7] offset:2048
	global_load_dwordx4 v[240:243], v191, s[6:7] offset:3072
	s_add_u32 s6, s6, 0x8000
	s_addc_u32 s7, s7, 0
	v_add_u32_e32 v168, 0x10000, v166
	v_add_u32_e32 v166, 0x200, v166
	s_add_i32 s36, s36, -1
	s_branch .Lix_loop
.Lix_done:
	s_nop 7
	s_nop 7
	s_waitcnt lgkmcnt(1)
	v_max_f32_e32 v16, 0, v16
	v_max_f32_e32 v17, 0, v17
	v_max_f32_e32 v18, 0, v18
	v_max_f32_e32 v19, 0, v19
	v_mul_f32_e32 v169, v172, v16
	v_fmac_f32_e32 v169, v173, v17
	v_fmac_f32_e32 v169, v174, v18
	v_fmac_f32_e32 v169, v175, v19
	ds_read_b128 v[172:175], v164 offset:384
	s_waitcnt lgkmcnt(1)
	v_max_f32_e32 v20, 0, v20
	v_max_f32_e32 v21, 0, v21
	v_max_f32_e32 v22, 0, v22
	v_max_f32_e32 v23, 0, v23
	v_mul_f32_e32 v170, v244, v20
	v_fmac_f32_e32 v170, v245, v21
	v_fmac_f32_e32 v170, v246, v22
	v_fmac_f32_e32 v170, v247, v23
	ds_read_b128 v[244:247], v164 offset:448
	s_waitcnt lgkmcnt(1)
	v_max_f32_e32 v24, 0, v24
	v_max_f32_e32 v25, 0, v25
	v_max_f32_e32 v26, 0, v26
	v_max_f32_e32 v27, 0, v27
	v_mul_f32_e32 v176, v172, v24
	v_fmac_f32_e32 v176, v173, v25
	v_fmac_f32_e32 v176, v174, v26
	v_fmac_f32_e32 v176, v175, v27
	s_waitcnt lgkmcnt(0)
	v_max_f32_e32 v28, 0, v28
	v_max_f32_e32 v29, 0, v29
	v_max_f32_e32 v30, 0, v30
	v_max_f32_e32 v31, 0, v31
	v_mul_f32_e32 v177, v244, v28
	v_fmac_f32_e32 v177, v245, v29
	v_fmac_f32_e32 v177, v246, v30
	v_fmac_f32_e32 v177, v247, v31
	s_nop 1
	v_permlane16_swap_b32 v169, v170
	v_permlane16_swap_b32 v176, v177
	v_add_f32_e32 v169, v169, v170
	v_add_f32_e32 v176, v176, v177
	s_nop 1
	v_permlane32_swap_b32 v169, v176
	v_add_f32_e32 v169, v169, v176
	ds_write_b32 v168, v169
	ds_read_b128 v[172:175], v164
	ds_read_b128 v[244:247], v164 offset:64
	s_waitcnt vmcnt(0)
.LBB0_160:
	s_waitcnt lgkmcnt(0)
	s_barrier
	s_add_i32 s2, s27, s22
	s_ashr_i32 s3, s2, 31
	s_lshl_b64 s[2:3], s[2:3], 10
	s_add_u32 s2, s26, s2
	s_addc_u32 s3, s76, s3
	v_lshlrev_b32_e32 v255, 2, v34
	s_add_i32 s4, s82, 1
	v_readlane_b32 s5, v253, 3
	v_readlane_b32 s0, v253, 42
	v_readlane_b32 s1, v253, 43
	v_readlane_b32 s7, v253, 44
	s_mul_i32 s6, s4, s5
	s_add_i32 s6, s6, s10
	s_cmpk_gt_i32 s6, 0x7ff
	s_cbranch_scc1 .Lsel_nopfA
	s_lshr_b32 s30, s4, 1
	s_bitcmp0_b32 s4, 0
	s_cselect_b32 s31, s10, s7
	s_cmp_eq_u64 s[0:1], 0
	s_cbranch_scc1 .Lsel_pfA_dec
	s_ashr_i32 s30, s6, 9
	s_and_b32 s31, s6, 0x1ff
.Lsel_pfA_dec:
	s_lshl_b32 s30, s30, 12
	s_lshl_b32 s31, s31, 3
	s_add_i32 s7, s30, s31
	v_readlane_b32 s4, v253, 11
	v_readlane_b32 s5, v253, 12
	s_add_u32 s4, s4, 0x1d302200
	s_addc_u32 s5, s5, 0
	s_add_i32 s30, s7, s22
	s_mul_i32 s30, s30, 0x3400
	s_add_u32 s30, s4, s30
	s_addc_u32 s31, s5, 0
	global_load_dwordx4 v[40:43], v35, s[30:31]
	global_load_dwordx4 v[44:47], v35, s[30:31] offset:1024
	global_load_dwordx4 v[48:51], v35, s[30:31] offset:2048
	global_load_dwordx4 v[52:55], v35, s[30:31] offset:3072
.Lsel_nopfA:
	s_cmp_gt_i32 s38, 3
	s_cbranch_scc1 .Lsel_big
	s_cmp_gt_i32 s38, -1
	s_cselect_b32 s4, 0, -1
	v_mov_b32_e32 v254, v34
	v_or_b32_e32 v254, s4, v254
	global_store_dword v255, v254, s[2:3]
	s_cmp_gt_i32 s38, 0
	s_cselect_b32 s4, 0, -1
	v_or_b32_e32 v254, 64, v34
	v_or_b32_e32 v254, s4, v254
	global_store_dword v255, v254, s[2:3] offset:256
	s_cmp_gt_i32 s38, 1
	s_cselect_b32 s4, 0, -1
	v_or_b32_e32 v254, 128, v34
	v_or_b32_e32 v254, s4, v254
	global_store_dword v255, v254, s[2:3] offset:512
	s_cmp_gt_i32 s38, 2
	s_cselect_b32 s4, 0, -1
	v_or_b32_e32 v254, 192, v34
	v_or_b32_e32 v254, s4, v254
	global_store_dword v255, v254, s[2:3] offset:768
	s_branch .Lsel_end
.Lsel_big:
	s_mov_b32 s28, 0x80000000
	s_lshl_b32 s27, s22, 10
	s_add_i32 s27, s27, 0x20000
	s_lshl_b32 s4, s22, 14
	v_lshl_add_u32 v249, v34, 2, s4
	v_mov_b32_e32 v232, 1
	v_mov_b32_e32 v172, 0
	v_mov_b32_e32 v173, 0
	v_mov_b32_e32 v174, 0
	v_mov_b32_e32 v175, 0
	v_lshlrev_b32_e32 v234, 4, v34
	v_sub_u32_e32 v235, 0x3f0, v234
	v_add_u32_e32 v234, s27, v234
	v_add_u32_e32 v235, s27, v235
	v_mov_b32_e32 v233, s27
	ds_write_b128 v234, v[172:175]
	ds_read_b32 v0, v249
	ds_read_b32 v1, v249 offset:256
	ds_read_b32 v2, v249 offset:512
	ds_read_b32 v3, v249 offset:768
	ds_read_b32 v4, v249 offset:1024
	ds_read_b32 v5, v249 offset:1280
	ds_read_b32 v6, v249 offset:1536
	ds_read_b32 v7, v249 offset:1792
	s_waitcnt lgkmcnt(0)
	v_cvt_f16_f32_sdwa v0, v0 dst_sel:WORD_1 dst_unused:UNUSED_PAD src0_sel:DWORD
	v_cvt_f16_f32_sdwa v1, v1 dst_sel:WORD_1 dst_unused:UNUSED_PAD src0_sel:DWORD
	s_nop 0
	v_ashrrev_i32_e32 v228, 31, v0
	v_ashrrev_i32_e32 v229, 31, v1
	v_bitop3_b32 v0, v0, v228, s28 bitop3:0x1e
	v_bitop3_b32 v1, v1, v229, s28 bitop3:0x1e
	v_cvt_f16_f32_sdwa v2, v2 dst_sel:WORD_1 dst_unused:UNUSED_PAD src0_sel:DWORD
	v_cvt_f16_f32_sdwa v3, v3 dst_sel:WORD_1 dst_unused:UNUSED_PAD src0_sel:DWORD
	s_nop 0
	v_ashrrev_i32_e32 v228, 31, v2
	v_ashrrev_i32_e32 v229, 31, v3
	v_bitop3_b32 v2, v2, v228, s28 bitop3:0x1e
	v_bitop3_b32 v3, v3, v229, s28 bitop3:0x1e
	v_cvt_f16_f32_sdwa v4, v4 dst_sel:WORD_1 dst_unused:UNUSED_PAD src0_sel:DWORD
	v_cvt_f16_f32_sdwa v5, v5 dst_sel:WORD_1 dst_unused:UNUSED_PAD src0_sel:DWORD
	s_nop 0
	v_ashrrev_i32_e32 v228, 31, v4
	v_ashrrev_i32_e32 v229, 31, v5
	v_bitop3_b32 v4, v4, v228, s28 bitop3:0x1e
	v_bitop3_b32 v5, v5, v229, s28 bitop3:0x1e
	v_cvt_f16_f32_sdwa v6, v6 dst_sel:WORD_1 dst_unused:UNUSED_PAD src0_sel:DWORD
	v_cvt_f16_f32_sdwa v7, v7 dst_sel:WORD_1 dst_unused:UNUSED_PAD src0_sel:DWORD
	s_nop 0
	v_ashrrev_i32_e32 v228, 31, v6
	v_ashrrev_i32_e32 v229, 31, v7
	v_bitop3_b32 v6, v6, v228, s28 bitop3:0x1e
	v_bitop3_b32 v7, v7, v229, s28 bitop3:0x1e
	ds_read_b32 v8, v249 offset:2048
	ds_read_b32 v9, v249 offset:2304
	ds_read_b32 v10, v249 offset:2560
	ds_read_b32 v11, v249 offset:2816
	ds_read_b32 v12, v249 offset:3072
	ds_read_b32 v13, v249 offset:3328
	ds_read_b32 v14, v249 offset:3584
	ds_read_b32 v15, v249 offset:3840
	s_cmp_gt_i32 s38, 6
	s_cbranch_scc1 .Lsel_kb_full0
	s_cmp_gt_i32 s38, 0
	s_cselect_b32 s4, -1, 0
	v_and_b32_e32 v1, s4, v1
	s_cmp_gt_i32 s38, 1
	s_cselect_b32 s4, -1, 0
	v_and_b32_e32 v2, s4, v2
	s_cmp_gt_i32 s38, 2
	s_cselect_b32 s4, -1, 0
	v_and_b32_e32 v3, s4, v3
	s_cmp_gt_i32 s38, 3
	s_cselect_b32 s4, -1, 0
	v_and_b32_e32 v4, s4, v4
	s_cmp_gt_i32 s38, 4
	s_cselect_b32 s4, -1, 0
	v_and_b32_e32 v5, s4, v5
	s_cmp_gt_i32 s38, 5
	s_cselect_b32 s4, -1, 0
	v_and_b32_e32 v6, s4, v6
	s_cmp_gt_i32 s38, 6
	s_cselect_b32 s4, -1, 0
	v_and_b32_e32 v7, s4, v7
	v_bfe_u32 v230, v0, 24, 8
	v_lshl_add_u32 v230, v230, 2, v233
	ds_add_u32 v230, v232
	v_bfe_u32 v231, v1, 24, 8
	v_lshl_add_u32 v231, v231, 2, v233
	ds_add_u32 v231, v232
	v_bfe_u32 v230, v2, 24, 8
	v_lshl_add_u32 v230, v230, 2, v233
	ds_add_u32 v230, v232
	v_bfe_u32 v231, v3, 24, 8
	v_lshl_add_u32 v231, v231, 2, v233
	ds_add_u32 v231, v232
	v_bfe_u32 v230, v4, 24, 8
	v_lshl_add_u32 v230, v230, 2, v233
	ds_add_u32 v230, v232
	v_bfe_u32 v231, v5, 24, 8
	v_lshl_add_u32 v231, v231, 2, v233
	ds_add_u32 v231, v232
	v_bfe_u32 v230, v6, 24, 8
	v_lshl_add_u32 v230, v230, 2, v233
	ds_add_u32 v230, v232
	v_bfe_u32 v231, v7, 24, 8
	v_lshl_add_u32 v231, v231, 2, v233
	ds_add_u32 v231, v232
	s_branch .Lsel_kb_done
.Lsel_kb_full0:
	v_bfe_u32 v230, v0, 24, 8
	v_lshl_add_u32 v230, v230, 2, v233
	ds_add_u32 v230, v232
	v_bfe_u32 v231, v1, 24, 8
	v_lshl_add_u32 v231, v231, 2, v233
	ds_add_u32 v231, v232
	v_bfe_u32 v230, v2, 24, 8
	v_lshl_add_u32 v230, v230, 2, v233
	ds_add_u32 v230, v232
	v_bfe_u32 v231, v3, 24, 8
	v_lshl_add_u32 v231, v231, 2, v233
	ds_add_u32 v231, v232
	v_bfe_u32 v230, v4, 24, 8
	v_lshl_add_u32 v230, v230, 2, v233
	ds_add_u32 v230, v232
	v_bfe_u32 v231, v5, 24, 8
	v_lshl_add_u32 v231, v231, 2, v233
	ds_add_u32 v231, v232
	v_bfe_u32 v230, v6, 24, 8
	v_lshl_add_u32 v230, v230, 2, v233
	ds_add_u32 v230, v232
	v_bfe_u32 v231, v7, 24, 8
	v_lshl_add_u32 v231, v231, 2, v233
	ds_add_u32 v231, v232
	s_cmp_lt_i32 s38, 8
	s_cbranch_scc1 .Lsel_kb_done
	s_waitcnt lgkmcnt(8)
	v_cvt_f16_f32_sdwa v8, v8 dst_sel:WORD_1 dst_unused:UNUSED_PAD src0_sel:DWORD
	v_cvt_f16_f32_sdwa v9, v9 dst_sel:WORD_1 dst_unused:UNUSED_PAD src0_sel:DWORD
	s_nop 0
	v_ashrrev_i32_e32 v228, 31, v8
	v_ashrrev_i32_e32 v229, 31, v9
	v_bitop3_b32 v8, v8, v228, s28 bitop3:0x1e
	v_bitop3_b32 v9, v9, v229, s28 bitop3:0x1e
	v_cvt_f16_f32_sdwa v10, v10 dst_sel:WORD_1 dst_unused:UNUSED_PAD src0_sel:DWORD
	v_cvt_f16_f32_sdwa v11, v11 dst_sel:WORD_1 dst_unused:UNUSED_PAD src0_sel:DWORD
	s_nop 0
	v_ashrrev_i32_e32 v228, 31, v10
	v_ashrrev_i32_e32 v229, 31, v11
	v_bitop3_b32 v10, v10, v228, s28 bitop3:0x1e
	v_bitop3_b32 v11, v11, v229, s28 bitop3:0x1e
	v_cvt_f16_f32_sdwa v12, v12 dst_sel:WORD_1 dst_unused:UNUSED_PAD src0_sel:DWORD
	v_cvt_f16_f32_sdwa v13, v13 dst_sel:WORD_1 dst_unused:UNUSED_PAD src0_sel:DWORD
	s_nop 0
	v_ashrrev_i32_e32 v228, 31, v12
	v_ashrrev_i32_e32 v229, 31, v13
	v_bitop3_b32 v12, v12, v228, s28 bitop3:0x1e
	v_bitop3_b32 v13, v13, v229, s28 bitop3:0x1e
	v_cvt_f16_f32_sdwa v14, v14 dst_sel:WORD_1 dst_unused:UNUSED_PAD src0_sel:DWORD
	v_cvt_f16_f32_sdwa v15, v15 dst_sel:WORD_1 dst_unused:UNUSED_PAD src0_sel:DWORD
	s_nop 0
	v_ashrrev_i32_e32 v228, 31, v14
	v_ashrrev_i32_e32 v229, 31, v15
	v_bitop3_b32 v14, v14, v228, s28 bitop3:0x1e
	v_bitop3_b32 v15, v15, v229, s28 bitop3:0x1e
	ds_read_b32 v16, v249 offset:4096
	ds_read_b32 v17, v249 offset:4352
	ds_read_b32 v18, v249 offset:4608
	ds_read_b32 v19, v249 offset:4864
	ds_read_b32 v20, v249 offset:5120
	ds_read_b32 v21, v249 offset:5376
	ds_read_b32 v22, v249 offset:5632
	ds_read_b32 v23, v249 offset:5888
	s_cmp_gt_i32 s38, 14
	s_cbranch_scc1 .Lsel_kb_full1
	s_cmp_gt_i32 s38, 8
	s_cselect_b32 s4, -1, 0
	v_and_b32_e32 v9, s4, v9
	s_cmp_gt_i32 s38, 9
	s_cselect_b32 s4, -1, 0
	v_and_b32_e32 v10, s4, v10
	s_cmp_gt_i32 s38, 10
	s_cselect_b32 s4, -1, 0
	v_and_b32_e32 v11, s4, v11
	s_cmp_gt_i32 s38, 11
	s_cselect_b32 s4, -1, 0
	v_and_b32_e32 v12, s4, v12
	s_cmp_gt_i32 s38, 12
	s_cselect_b32 s4, -1, 0
	v_and_b32_e32 v13, s4, v13
	s_cmp_gt_i32 s38, 13
	s_cselect_b32 s4, -1, 0
	v_and_b32_e32 v14, s4, v14
	s_cmp_gt_i32 s38, 14
	s_cselect_b32 s4, -1, 0
	v_and_b32_e32 v15, s4, v15
	v_bfe_u32 v230, v8, 24, 8
	v_lshl_add_u32 v230, v230, 2, v233
	ds_add_u32 v230, v232
	v_bfe_u32 v231, v9, 24, 8
	v_lshl_add_u32 v231, v231, 2, v233
	ds_add_u32 v231, v232
	v_bfe_u32 v230, v10, 24, 8
	v_lshl_add_u32 v230, v230, 2, v233
	ds_add_u32 v230, v232
	v_bfe_u32 v231, v11, 24, 8
	v_lshl_add_u32 v231, v231, 2, v233
	ds_add_u32 v231, v232
	v_bfe_u32 v230, v12, 24, 8
	v_lshl_add_u32 v230, v230, 2, v233
	ds_add_u32 v230, v232
	v_bfe_u32 v231, v13, 24, 8
	v_lshl_add_u32 v231, v231, 2, v233
	ds_add_u32 v231, v232
	v_bfe_u32 v230, v14, 24, 8
	v_lshl_add_u32 v230, v230, 2, v233
	ds_add_u32 v230, v232
	v_bfe_u32 v231, v15, 24, 8
	v_lshl_add_u32 v231, v231, 2, v233
	ds_add_u32 v231, v232
	s_branch .Lsel_kb_done
.Lsel_kb_full1:
	v_bfe_u32 v230, v8, 24, 8
	v_lshl_add_u32 v230, v230, 2, v233
	ds_add_u32 v230, v232
	v_bfe_u32 v231, v9, 24, 8
	v_lshl_add_u32 v231, v231, 2, v233
	ds_add_u32 v231, v232
	v_bfe_u32 v230, v10, 24, 8
	v_lshl_add_u32 v230, v230, 2, v233
	ds_add_u32 v230, v232
	v_bfe_u32 v231, v11, 24, 8
	v_lshl_add_u32 v231, v231, 2, v233
	ds_add_u32 v231, v232
	v_bfe_u32 v230, v12, 24, 8
	v_lshl_add_u32 v230, v230, 2, v233
	ds_add_u32 v230, v232
	v_bfe_u32 v231, v13, 24, 8
	v_lshl_add_u32 v231, v231, 2, v233
	ds_add_u32 v231, v232
	v_bfe_u32 v230, v14, 24, 8
	v_lshl_add_u32 v230, v230, 2, v233
	ds_add_u32 v230, v232
	v_bfe_u32 v231, v15, 24, 8
	v_lshl_add_u32 v231, v231, 2, v233
	ds_add_u32 v231, v232
	s_cmp_lt_i32 s38, 16
	s_cbranch_scc1 .Lsel_kb_done
	s_waitcnt lgkmcnt(8)
	v_cvt_f16_f32_sdwa v16, v16 dst_sel:WORD_1 dst_unused:UNUSED_PAD src0_sel:DWORD
	v_cvt_f16_f32_sdwa v17, v17 dst_sel:WORD_1 dst_unused:UNUSED_PAD src0_sel:DWORD
	s_nop 0
	v_ashrrev_i32_e32 v228, 31, v16
	v_ashrrev_i32_e32 v229, 31, v17
	v_bitop3_b32 v16, v16, v228, s28 bitop3:0x1e
	v_bitop3_b32 v17, v17, v229, s28 bitop3:0x1e
	v_cvt_f16_f32_sdwa v18, v18 dst_sel:WORD_1 dst_unused:UNUSED_PAD src0_sel:DWORD
	v_cvt_f16_f32_sdwa v19, v19 dst_sel:WORD_1 dst_unused:UNUSED_PAD src0_sel:DWORD
	s_nop 0
	v_ashrrev_i32_e32 v228, 31, v18
	v_ashrrev_i32_e32 v229, 31, v19
	v_bitop3_b32 v18, v18, v228, s28 bitop3:0x1e
	v_bitop3_b32 v19, v19, v229, s28 bitop3:0x1e
	v_cvt_f16_f32_sdwa v20, v20 dst_sel:WORD_1 dst_unused:UNUSED_PAD src0_sel:DWORD
	v_cvt_f16_f32_sdwa v21, v21 dst_sel:WORD_1 dst_unused:UNUSED_PAD src0_sel:DWORD
	s_nop 0
	v_ashrrev_i32_e32 v228, 31, v20
	v_ashrrev_i32_e32 v229, 31, v21
	v_bitop3_b32 v20, v20, v228, s28 bitop3:0x1e
	v_bitop3_b32 v21, v21, v229, s28 bitop3:0x1e
	v_cvt_f16_f32_sdwa v22, v22 dst_sel:WORD_1 dst_unused:UNUSED_PAD src0_sel:DWORD
	v_cvt_f16_f32_sdwa v23, v23 dst_sel:WORD_1 dst_unused:UNUSED_PAD src0_sel:DWORD
	s_nop 0
	v_ashrrev_i32_e32 v228, 31, v22
	v_ashrrev_i32_e32 v229, 31, v23
	v_bitop3_b32 v22, v22, v228, s28 bitop3:0x1e
	v_bitop3_b32 v23, v23, v229, s28 bitop3:0x1e
	ds_read_b32 v24, v249 offset:6144
	ds_read_b32 v25, v249 offset:6400
	ds_read_b32 v26, v249 offset:6656
	ds_read_b32 v27, v249 offset:6912
	ds_read_b32 v28, v249 offset:7168
	ds_read_b32 v29, v249 offset:7424
	ds_read_b32 v30, v249 offset:7680
	ds_read_b32 v31, v249 offset:7936
	s_cmp_gt_i32 s38, 22
	s_cbranch_scc1 .Lsel_kb_full2
	s_cmp_gt_i32 s38, 16
	s_cselect_b32 s4, -1, 0
	v_and_b32_e32 v17, s4, v17
	s_cmp_gt_i32 s38, 17
	s_cselect_b32 s4, -1, 0
	v_and_b32_e32 v18, s4, v18
	s_cmp_gt_i32 s38, 18
	s_cselect_b32 s4, -1, 0
	v_and_b32_e32 v19, s4, v19
	s_cmp_gt_i32 s38, 19
	s_cselect_b32 s4, -1, 0
	v_and_b32_e32 v20, s4, v20
	s_cmp_gt_i32 s38, 20
	s_cselect_b32 s4, -1, 0
	v_and_b32_e32 v21, s4, v21
	s_cmp_gt_i32 s38, 21
	s_cselect_b32 s4, -1, 0
	v_and_b32_e32 v22, s4, v22
	s_cmp_gt_i32 s38, 22
	s_cselect_b32 s4, -1, 0
	v_and_b32_e32 v23, s4, v23
	v_bfe_u32 v230, v16, 24, 8
	v_lshl_add_u32 v230, v230, 2, v233
	ds_add_u32 v230, v232
	v_bfe_u32 v231, v17, 24, 8
	v_lshl_add_u32 v231, v231, 2, v233
	ds_add_u32 v231, v232
	v_bfe_u32 v230, v18, 24, 8
	v_lshl_add_u32 v230, v230, 2, v233
	ds_add_u32 v230, v232
	v_bfe_u32 v231, v19, 24, 8
	v_lshl_add_u32 v231, v231, 2, v233
	ds_add_u32 v231, v232
	v_bfe_u32 v230, v20, 24, 8
	v_lshl_add_u32 v230, v230, 2, v233
	ds_add_u32 v230, v232
	v_bfe_u32 v231, v21, 24, 8
	v_lshl_add_u32 v231, v231, 2, v233
	ds_add_u32 v231, v232
	v_bfe_u32 v230, v22, 24, 8
	v_lshl_add_u32 v230, v230, 2, v233
	ds_add_u32 v230, v232
	v_bfe_u32 v231, v23, 24, 8
	v_lshl_add_u32 v231, v231, 2, v233
	ds_add_u32 v231, v232
	s_branch .Lsel_kb_done
.Lsel_kb_full2:
	v_bfe_u32 v230, v16, 24, 8
	v_lshl_add_u32 v230, v230, 2, v233
	ds_add_u32 v230, v232
	v_bfe_u32 v231, v17, 24, 8
	v_lshl_add_u32 v231, v231, 2, v233
	ds_add_u32 v231, v232
	v_bfe_u32 v230, v18, 24, 8
	v_lshl_add_u32 v230, v230, 2, v233
	ds_add_u32 v230, v232
	v_bfe_u32 v231, v19, 24, 8
	v_lshl_add_u32 v231, v231, 2, v233
	ds_add_u32 v231, v232
	v_bfe_u32 v230, v20, 24, 8
	v_lshl_add_u32 v230, v230, 2, v233
	ds_add_u32 v230, v232
	v_bfe_u32 v231, v21, 24, 8
	v_lshl_add_u32 v231, v231, 2, v233
	ds_add_u32 v231, v232
	v_bfe_u32 v230, v22, 24, 8
	v_lshl_add_u32 v230, v230, 2, v233
	ds_add_u32 v230, v232
	v_bfe_u32 v231, v23, 24, 8
	v_lshl_add_u32 v231, v231, 2, v233
	ds_add_u32 v231, v232
	s_cmp_lt_i32 s38, 24
	s_cbranch_scc1 .Lsel_kb_done
	s_waitcnt lgkmcnt(8)
	v_cvt_f16_f32_sdwa v24, v24 dst_sel:WORD_1 dst_unused:UNUSED_PAD src0_sel:DWORD
	v_cvt_f16_f32_sdwa v25, v25 dst_sel:WORD_1 dst_unused:UNUSED_PAD src0_sel:DWORD
	s_nop 0
	v_ashrrev_i32_e32 v228, 31, v24
	v_ashrrev_i32_e32 v229, 31, v25
	v_bitop3_b32 v24, v24, v228, s28 bitop3:0x1e
	v_bitop3_b32 v25, v25, v229, s28 bitop3:0x1e
	v_cvt_f16_f32_sdwa v26, v26 dst_sel:WORD_1 dst_unused:UNUSED_PAD src0_sel:DWORD
	v_cvt_f16_f32_sdwa v27, v27 dst_sel:WORD_1 dst_unused:UNUSED_PAD src0_sel:DWORD
	s_nop 0
	v_ashrrev_i32_e32 v228, 31, v26
	v_ashrrev_i32_e32 v229, 31, v27
	v_bitop3_b32 v26, v26, v228, s28 bitop3:0x1e
	v_bitop3_b32 v27, v27, v229, s28 bitop3:0x1e
	v_cvt_f16_f32_sdwa v28, v28 dst_sel:WORD_1 dst_unused:UNUSED_PAD src0_sel:DWORD
	v_cvt_f16_f32_sdwa v29, v29 dst_sel:WORD_1 dst_unused:UNUSED_PAD src0_sel:DWORD
	s_nop 0
	v_ashrrev_i32_e32 v228, 31, v28
	v_ashrrev_i32_e32 v229, 31, v29
	v_bitop3_b32 v28, v28, v228, s28 bitop3:0x1e
	v_bitop3_b32 v29, v29, v229, s28 bitop3:0x1e
	v_cvt_f16_f32_sdwa v30, v30 dst_sel:WORD_1 dst_unused:UNUSED_PAD src0_sel:DWORD
	v_cvt_f16_f32_sdwa v31, v31 dst_sel:WORD_1 dst_unused:UNUSED_PAD src0_sel:DWORD
	s_nop 0
	v_ashrrev_i32_e32 v228, 31, v30
	v_ashrrev_i32_e32 v229, 31, v31
	v_bitop3_b32 v30, v30, v228, s28 bitop3:0x1e
	v_bitop3_b32 v31, v31, v229, s28 bitop3:0x1e
	ds_read_b32 v196, v249 offset:8192
	ds_read_b32 v197, v249 offset:8448
	ds_read_b32 v198, v249 offset:8704
	ds_read_b32 v199, v249 offset:8960
	ds_read_b32 v200, v249 offset:9216
	ds_read_b32 v201, v249 offset:9472
	ds_read_b32 v202, v249 offset:9728
	ds_read_b32 v203, v249 offset:9984
	s_cmp_gt_i32 s38, 30
	s_cbranch_scc1 .Lsel_kb_full3
	s_cmp_gt_i32 s38, 24
	s_cselect_b32 s4, -1, 0
	v_and_b32_e32 v25, s4, v25
	s_cmp_gt_i32 s38, 25
	s_cselect_b32 s4, -1, 0
	v_and_b32_e32 v26, s4, v26
	s_cmp_gt_i32 s38, 26
	s_cselect_b32 s4, -1, 0
	v_and_b32_e32 v27, s4, v27
	s_cmp_gt_i32 s38, 27
	s_cselect_b32 s4, -1, 0
	v_and_b32_e32 v28, s4, v28
	s_cmp_gt_i32 s38, 28
	s_cselect_b32 s4, -1, 0
	v_and_b32_e32 v29, s4, v29
	s_cmp_gt_i32 s38, 29
	s_cselect_b32 s4, -1, 0
	v_and_b32_e32 v30, s4, v30
	s_cmp_gt_i32 s38, 30
	s_cselect_b32 s4, -1, 0
	v_and_b32_e32 v31, s4, v31
	v_bfe_u32 v230, v24, 24, 8
	v_lshl_add_u32 v230, v230, 2, v233
	ds_add_u32 v230, v232
	v_bfe_u32 v231, v25, 24, 8
	v_lshl_add_u32 v231, v231, 2, v233
	ds_add_u32 v231, v232
	v_bfe_u32 v230, v26, 24, 8
	v_lshl_add_u32 v230, v230, 2, v233
	ds_add_u32 v230, v232
	v_bfe_u32 v231, v27, 24, 8
	v_lshl_add_u32 v231, v231, 2, v233
	ds_add_u32 v231, v232
	v_bfe_u32 v230, v28, 24, 8
	v_lshl_add_u32 v230, v230, 2, v233
	ds_add_u32 v230, v232
	v_bfe_u32 v231, v29, 24, 8
	v_lshl_add_u32 v231, v231, 2, v233
	ds_add_u32 v231, v232
	v_bfe_u32 v230, v30, 24, 8
	v_lshl_add_u32 v230, v230, 2, v233
	ds_add_u32 v230, v232
	v_bfe_u32 v231, v31, 24, 8
	v_lshl_add_u32 v231, v231, 2, v233
	ds_add_u32 v231, v232
	s_branch .Lsel_kb_done
.Lsel_kb_full3:
	v_bfe_u32 v230, v24, 24, 8
	v_lshl_add_u32 v230, v230, 2, v233
	ds_add_u32 v230, v232
	v_bfe_u32 v231, v25, 24, 8
	v_lshl_add_u32 v231, v231, 2, v233
	ds_add_u32 v231, v232
	v_bfe_u32 v230, v26, 24, 8
	v_lshl_add_u32 v230, v230, 2, v233
	ds_add_u32 v230, v232
	v_bfe_u32 v231, v27, 24, 8
	v_lshl_add_u32 v231, v231, 2, v233
	ds_add_u32 v231, v232
	v_bfe_u32 v230, v28, 24, 8
	v_lshl_add_u32 v230, v230, 2, v233
	ds_add_u32 v230, v232
	v_bfe_u32 v231, v29, 24, 8
	v_lshl_add_u32 v231, v231, 2, v233
	ds_add_u32 v231, v232
	v_bfe_u32 v230, v30, 24, 8
	v_lshl_add_u32 v230, v230, 2, v233
	ds_add_u32 v230, v232
	v_bfe_u32 v231, v31, 24, 8
	v_lshl_add_u32 v231, v231, 2, v233
	ds_add_u32 v231, v232
	s_cmp_lt_i32 s38, 32
	s_cbranch_scc1 .Lsel_kb_done
	s_waitcnt lgkmcnt(8)
	v_cvt_f16_f32_sdwa v196, v196 dst_sel:WORD_1 dst_unused:UNUSED_PAD src0_sel:DWORD
	v_cvt_f16_f32_sdwa v197, v197 dst_sel:WORD_1 dst_unused:UNUSED_PAD src0_sel:DWORD
	s_nop 0
	v_ashrrev_i32_e32 v228, 31, v196
	v_ashrrev_i32_e32 v229, 31, v197
	v_bitop3_b32 v196, v196, v228, s28 bitop3:0x1e
	v_bitop3_b32 v197, v197, v229, s28 bitop3:0x1e
	v_cvt_f16_f32_sdwa v198, v198 dst_sel:WORD_1 dst_unused:UNUSED_PAD src0_sel:DWORD
	v_cvt_f16_f32_sdwa v199, v199 dst_sel:WORD_1 dst_unused:UNUSED_PAD src0_sel:DWORD
	s_nop 0
	v_ashrrev_i32_e32 v228, 31, v198
	v_ashrrev_i32_e32 v229, 31, v199
	v_bitop3_b32 v198, v198, v228, s28 bitop3:0x1e
	v_bitop3_b32 v199, v199, v229, s28 bitop3:0x1e
	v_cvt_f16_f32_sdwa v200, v200 dst_sel:WORD_1 dst_unused:UNUSED_PAD src0_sel:DWORD
	v_cvt_f16_f32_sdwa v201, v201 dst_sel:WORD_1 dst_unused:UNUSED_PAD src0_sel:DWORD
	s_nop 0
	v_ashrrev_i32_e32 v228, 31, v200
	v_ashrrev_i32_e32 v229, 31, v201
	v_bitop3_b32 v200, v200, v228, s28 bitop3:0x1e
	v_bitop3_b32 v201, v201, v229, s28 bitop3:0x1e
	v_cvt_f16_f32_sdwa v202, v202 dst_sel:WORD_1 dst_unused:UNUSED_PAD src0_sel:DWORD
	v_cvt_f16_f32_sdwa v203, v203 dst_sel:WORD_1 dst_unused:UNUSED_PAD src0_sel:DWORD
	s_nop 0
	v_ashrrev_i32_e32 v228, 31, v202
	v_ashrrev_i32_e32 v229, 31, v203
	v_bitop3_b32 v202, v202, v228, s28 bitop3:0x1e
	v_bitop3_b32 v203, v203, v229, s28 bitop3:0x1e
	ds_read_b32 v204, v249 offset:10240
	ds_read_b32 v205, v249 offset:10496
	ds_read_b32 v206, v249 offset:10752
	ds_read_b32 v207, v249 offset:11008
	ds_read_b32 v208, v249 offset:11264
	ds_read_b32 v209, v249 offset:11520
	ds_read_b32 v210, v249 offset:11776
	ds_read_b32 v211, v249 offset:12032
	s_cmp_gt_i32 s38, 38
	s_cbranch_scc1 .Lsel_kb_full4
	s_cmp_gt_i32 s38, 32
	s_cselect_b32 s4, -1, 0
	v_and_b32_e32 v197, s4, v197
	s_cmp_gt_i32 s38, 33
	s_cselect_b32 s4, -1, 0
	v_and_b32_e32 v198, s4, v198
	s_cmp_gt_i32 s38, 34
	s_cselect_b32 s4, -1, 0
	v_and_b32_e32 v199, s4, v199
	s_cmp_gt_i32 s38, 35
	s_cselect_b32 s4, -1, 0
	v_and_b32_e32 v200, s4, v200
	s_cmp_gt_i32 s38, 36
	s_cselect_b32 s4, -1, 0
	v_and_b32_e32 v201, s4, v201
	s_cmp_gt_i32 s38, 37
	s_cselect_b32 s4, -1, 0
	v_and_b32_e32 v202, s4, v202
	s_cmp_gt_i32 s38, 38
	s_cselect_b32 s4, -1, 0
	v_and_b32_e32 v203, s4, v203
	v_bfe_u32 v230, v196, 24, 8
	v_lshl_add_u32 v230, v230, 2, v233
	ds_add_u32 v230, v232
	v_bfe_u32 v231, v197, 24, 8
	v_lshl_add_u32 v231, v231, 2, v233
	ds_add_u32 v231, v232
	v_bfe_u32 v230, v198, 24, 8
	v_lshl_add_u32 v230, v230, 2, v233
	ds_add_u32 v230, v232
	v_bfe_u32 v231, v199, 24, 8
	v_lshl_add_u32 v231, v231, 2, v233
	ds_add_u32 v231, v232
	v_bfe_u32 v230, v200, 24, 8
	v_lshl_add_u32 v230, v230, 2, v233
	ds_add_u32 v230, v232
	v_bfe_u32 v231, v201, 24, 8
	v_lshl_add_u32 v231, v231, 2, v233
	ds_add_u32 v231, v232
	v_bfe_u32 v230, v202, 24, 8
	v_lshl_add_u32 v230, v230, 2, v233
	ds_add_u32 v230, v232
	v_bfe_u32 v231, v203, 24, 8
	v_lshl_add_u32 v231, v231, 2, v233
	ds_add_u32 v231, v232
	s_branch .Lsel_kb_done
.Lsel_kb_full4:
	v_bfe_u32 v230, v196, 24, 8
	v_lshl_add_u32 v230, v230, 2, v233
	ds_add_u32 v230, v232
	v_bfe_u32 v231, v197, 24, 8
	v_lshl_add_u32 v231, v231, 2, v233
	ds_add_u32 v231, v232
	v_bfe_u32 v230, v198, 24, 8
	v_lshl_add_u32 v230, v230, 2, v233
	ds_add_u32 v230, v232
	v_bfe_u32 v231, v199, 24, 8
	v_lshl_add_u32 v231, v231, 2, v233
	ds_add_u32 v231, v232
	v_bfe_u32 v230, v200, 24, 8
	v_lshl_add_u32 v230, v230, 2, v233
	ds_add_u32 v230, v232
	v_bfe_u32 v231, v201, 24, 8
	v_lshl_add_u32 v231, v231, 2, v233
	ds_add_u32 v231, v232
	v_bfe_u32 v230, v202, 24, 8
	v_lshl_add_u32 v230, v230, 2, v233
	ds_add_u32 v230, v232
	v_bfe_u32 v231, v203, 24, 8
	v_lshl_add_u32 v231, v231, 2, v233
	ds_add_u32 v231, v232
	s_cmp_lt_i32 s38, 40
	s_cbranch_scc1 .Lsel_kb_done
	s_waitcnt lgkmcnt(8)
	v_cvt_f16_f32_sdwa v204, v204 dst_sel:WORD_1 dst_unused:UNUSED_PAD src0_sel:DWORD
	v_cvt_f16_f32_sdwa v205, v205 dst_sel:WORD_1 dst_unused:UNUSED_PAD src0_sel:DWORD
	s_nop 0
	v_ashrrev_i32_e32 v228, 31, v204
	v_ashrrev_i32_e32 v229, 31, v205
	v_bitop3_b32 v204, v204, v228, s28 bitop3:0x1e
	v_bitop3_b32 v205, v205, v229, s28 bitop3:0x1e
	v_cvt_f16_f32_sdwa v206, v206 dst_sel:WORD_1 dst_unused:UNUSED_PAD src0_sel:DWORD
	v_cvt_f16_f32_sdwa v207, v207 dst_sel:WORD_1 dst_unused:UNUSED_PAD src0_sel:DWORD
	s_nop 0
	v_ashrrev_i32_e32 v228, 31, v206
	v_ashrrev_i32_e32 v229, 31, v207
	v_bitop3_b32 v206, v206, v228, s28 bitop3:0x1e
	v_bitop3_b32 v207, v207, v229, s28 bitop3:0x1e
	v_cvt_f16_f32_sdwa v208, v208 dst_sel:WORD_1 dst_unused:UNUSED_PAD src0_sel:DWORD
	v_cvt_f16_f32_sdwa v209, v209 dst_sel:WORD_1 dst_unused:UNUSED_PAD src0_sel:DWORD
	s_nop 0
	v_ashrrev_i32_e32 v228, 31, v208
	v_ashrrev_i32_e32 v229, 31, v209
	v_bitop3_b32 v208, v208, v228, s28 bitop3:0x1e
	v_bitop3_b32 v209, v209, v229, s28 bitop3:0x1e
	v_cvt_f16_f32_sdwa v210, v210 dst_sel:WORD_1 dst_unused:UNUSED_PAD src0_sel:DWORD
	v_cvt_f16_f32_sdwa v211, v211 dst_sel:WORD_1 dst_unused:UNUSED_PAD src0_sel:DWORD
	s_nop 0
	v_ashrrev_i32_e32 v228, 31, v210
	v_ashrrev_i32_e32 v229, 31, v211
	v_bitop3_b32 v210, v210, v228, s28 bitop3:0x1e
	v_bitop3_b32 v211, v211, v229, s28 bitop3:0x1e
	ds_read_b32 v212, v249 offset:12288
	ds_read_b32 v213, v249 offset:12544
	ds_read_b32 v214, v249 offset:12800
	ds_read_b32 v215, v249 offset:13056
	ds_read_b32 v216, v249 offset:13312
	ds_read_b32 v217, v249 offset:13568
	ds_read_b32 v218, v249 offset:13824
	ds_read_b32 v219, v249 offset:14080
	s_cmp_gt_i32 s38, 46
	s_cbranch_scc1 .Lsel_kb_full5
	s_cmp_gt_i32 s38, 40
	s_cselect_b32 s4, -1, 0
	v_and_b32_e32 v205, s4, v205
	s_cmp_gt_i32 s38, 41
	s_cselect_b32 s4, -1, 0
	v_and_b32_e32 v206, s4, v206
	s_cmp_gt_i32 s38, 42
	s_cselect_b32 s4, -1, 0
	v_and_b32_e32 v207, s4, v207
	s_cmp_gt_i32 s38, 43
	s_cselect_b32 s4, -1, 0
	v_and_b32_e32 v208, s4, v208
	s_cmp_gt_i32 s38, 44
	s_cselect_b32 s4, -1, 0
	v_and_b32_e32 v209, s4, v209
	s_cmp_gt_i32 s38, 45
	s_cselect_b32 s4, -1, 0
	v_and_b32_e32 v210, s4, v210
	s_cmp_gt_i32 s38, 46
	s_cselect_b32 s4, -1, 0
	v_and_b32_e32 v211, s4, v211
	v_bfe_u32 v230, v204, 24, 8
	v_lshl_add_u32 v230, v230, 2, v233
	ds_add_u32 v230, v232
	v_bfe_u32 v231, v205, 24, 8
	v_lshl_add_u32 v231, v231, 2, v233
	ds_add_u32 v231, v232
	v_bfe_u32 v230, v206, 24, 8
	v_lshl_add_u32 v230, v230, 2, v233
	ds_add_u32 v230, v232
	v_bfe_u32 v231, v207, 24, 8
	v_lshl_add_u32 v231, v231, 2, v233
	ds_add_u32 v231, v232
	v_bfe_u32 v230, v208, 24, 8
	v_lshl_add_u32 v230, v230, 2, v233
	ds_add_u32 v230, v232
	v_bfe_u32 v231, v209, 24, 8
	v_lshl_add_u32 v231, v231, 2, v233
	ds_add_u32 v231, v232
	v_bfe_u32 v230, v210, 24, 8
	v_lshl_add_u32 v230, v230, 2, v233
	ds_add_u32 v230, v232
	v_bfe_u32 v231, v211, 24, 8
	v_lshl_add_u32 v231, v231, 2, v233
	ds_add_u32 v231, v232
	s_branch .Lsel_kb_done
.Lsel_kb_full5:
	v_bfe_u32 v230, v204, 24, 8
	v_lshl_add_u32 v230, v230, 2, v233
	ds_add_u32 v230, v232
	v_bfe_u32 v231, v205, 24, 8
	v_lshl_add_u32 v231, v231, 2, v233
	ds_add_u32 v231, v232
	v_bfe_u32 v230, v206, 24, 8
	v_lshl_add_u32 v230, v230, 2, v233
	ds_add_u32 v230, v232
	v_bfe_u32 v231, v207, 24, 8
	v_lshl_add_u32 v231, v231, 2, v233
	ds_add_u32 v231, v232
	v_bfe_u32 v230, v208, 24, 8
	v_lshl_add_u32 v230, v230, 2, v233
	ds_add_u32 v230, v232
	v_bfe_u32 v231, v209, 24, 8
	v_lshl_add_u32 v231, v231, 2, v233
	ds_add_u32 v231, v232
	v_bfe_u32 v230, v210, 24, 8
	v_lshl_add_u32 v230, v230, 2, v233
	ds_add_u32 v230, v232
	v_bfe_u32 v231, v211, 24, 8
	v_lshl_add_u32 v231, v231, 2, v233
	ds_add_u32 v231, v232
	s_cmp_lt_i32 s38, 48
	s_cbranch_scc1 .Lsel_kb_done
	s_waitcnt lgkmcnt(8)
	v_cvt_f16_f32_sdwa v212, v212 dst_sel:WORD_1 dst_unused:UNUSED_PAD src0_sel:DWORD
	v_cvt_f16_f32_sdwa v213, v213 dst_sel:WORD_1 dst_unused:UNUSED_PAD src0_sel:DWORD
	s_nop 0
	v_ashrrev_i32_e32 v228, 31, v212
	v_ashrrev_i32_e32 v229, 31, v213
	v_bitop3_b32 v212, v212, v228, s28 bitop3:0x1e
	v_bitop3_b32 v213, v213, v229, s28 bitop3:0x1e
	v_cvt_f16_f32_sdwa v214, v214 dst_sel:WORD_1 dst_unused:UNUSED_PAD src0_sel:DWORD
	v_cvt_f16_f32_sdwa v215, v215 dst_sel:WORD_1 dst_unused:UNUSED_PAD src0_sel:DWORD
	s_nop 0
	v_ashrrev_i32_e32 v228, 31, v214
	v_ashrrev_i32_e32 v229, 31, v215
	v_bitop3_b32 v214, v214, v228, s28 bitop3:0x1e
	v_bitop3_b32 v215, v215, v229, s28 bitop3:0x1e
	v_cvt_f16_f32_sdwa v216, v216 dst_sel:WORD_1 dst_unused:UNUSED_PAD src0_sel:DWORD
	v_cvt_f16_f32_sdwa v217, v217 dst_sel:WORD_1 dst_unused:UNUSED_PAD src0_sel:DWORD
	s_nop 0
	v_ashrrev_i32_e32 v228, 31, v216
	v_ashrrev_i32_e32 v229, 31, v217
	v_bitop3_b32 v216, v216, v228, s28 bitop3:0x1e
	v_bitop3_b32 v217, v217, v229, s28 bitop3:0x1e
	v_cvt_f16_f32_sdwa v218, v218 dst_sel:WORD_1 dst_unused:UNUSED_PAD src0_sel:DWORD
	v_cvt_f16_f32_sdwa v219, v219 dst_sel:WORD_1 dst_unused:UNUSED_PAD src0_sel:DWORD
	s_nop 0
	v_ashrrev_i32_e32 v228, 31, v218
	v_ashrrev_i32_e32 v229, 31, v219
	v_bitop3_b32 v218, v218, v228, s28 bitop3:0x1e
	v_bitop3_b32 v219, v219, v229, s28 bitop3:0x1e
	ds_read_b32 v220, v249 offset:14336
	ds_read_b32 v221, v249 offset:14592
	ds_read_b32 v222, v249 offset:14848
	ds_read_b32 v223, v249 offset:15104
	ds_read_b32 v224, v249 offset:15360
	ds_read_b32 v225, v249 offset:15616
	ds_read_b32 v226, v249 offset:15872
	ds_read_b32 v227, v249 offset:16128
	s_cmp_gt_i32 s38, 54
	s_cbranch_scc1 .Lsel_kb_full6
	s_cmp_gt_i32 s38, 48
	s_cselect_b32 s4, -1, 0
	v_and_b32_e32 v213, s4, v213
	s_cmp_gt_i32 s38, 49
	s_cselect_b32 s4, -1, 0
	v_and_b32_e32 v214, s4, v214
	s_cmp_gt_i32 s38, 50
	s_cselect_b32 s4, -1, 0
	v_and_b32_e32 v215, s4, v215
	s_cmp_gt_i32 s38, 51
	s_cselect_b32 s4, -1, 0
	v_and_b32_e32 v216, s4, v216
	s_cmp_gt_i32 s38, 52
	s_cselect_b32 s4, -1, 0
	v_and_b32_e32 v217, s4, v217
	s_cmp_gt_i32 s38, 53
	s_cselect_b32 s4, -1, 0
	v_and_b32_e32 v218, s4, v218
	s_cmp_gt_i32 s38, 54
	s_cselect_b32 s4, -1, 0
	v_and_b32_e32 v219, s4, v219
	v_bfe_u32 v230, v212, 24, 8
	v_lshl_add_u32 v230, v230, 2, v233
	ds_add_u32 v230, v232
	v_bfe_u32 v231, v213, 24, 8
	v_lshl_add_u32 v231, v231, 2, v233
	ds_add_u32 v231, v232
	v_bfe_u32 v230, v214, 24, 8
	v_lshl_add_u32 v230, v230, 2, v233
	ds_add_u32 v230, v232
	v_bfe_u32 v231, v215, 24, 8
	v_lshl_add_u32 v231, v231, 2, v233
	ds_add_u32 v231, v232
	v_bfe_u32 v230, v216, 24, 8
	v_lshl_add_u32 v230, v230, 2, v233
	ds_add_u32 v230, v232
	v_bfe_u32 v231, v217, 24, 8
	v_lshl_add_u32 v231, v231, 2, v233
	ds_add_u32 v231, v232
	v_bfe_u32 v230, v218, 24, 8
	v_lshl_add_u32 v230, v230, 2, v233
	ds_add_u32 v230, v232
	v_bfe_u32 v231, v219, 24, 8
	v_lshl_add_u32 v231, v231, 2, v233
	ds_add_u32 v231, v232
	s_branch .Lsel_kb_done
.Lsel_kb_full6:
	v_bfe_u32 v230, v212, 24, 8
	v_lshl_add_u32 v230, v230, 2, v233
	ds_add_u32 v230, v232
	v_bfe_u32 v231, v213, 24, 8
	v_lshl_add_u32 v231, v231, 2, v233
	ds_add_u32 v231, v232
	v_bfe_u32 v230, v214, 24, 8
	v_lshl_add_u32 v230, v230, 2, v233
	ds_add_u32 v230, v232
	v_bfe_u32 v231, v215, 24, 8
	v_lshl_add_u32 v231, v231, 2, v233
	ds_add_u32 v231, v232
	v_bfe_u32 v230, v216, 24, 8
	v_lshl_add_u32 v230, v230, 2, v233
	ds_add_u32 v230, v232
	v_bfe_u32 v231, v217, 24, 8
	v_lshl_add_u32 v231, v231, 2, v233
	ds_add_u32 v231, v232
	v_bfe_u32 v230, v218, 24, 8
	v_lshl_add_u32 v230, v230, 2, v233
	ds_add_u32 v230, v232
	v_bfe_u32 v231, v219, 24, 8
	v_lshl_add_u32 v231, v231, 2, v233
	ds_add_u32 v231, v232
	s_cmp_lt_i32 s38, 56
	s_cbranch_scc1 .Lsel_kb_done
	s_waitcnt lgkmcnt(8)
	v_cvt_f16_f32_sdwa v220, v220 dst_sel:WORD_1 dst_unused:UNUSED_PAD src0_sel:DWORD
	v_cvt_f16_f32_sdwa v221, v221 dst_sel:WORD_1 dst_unused:UNUSED_PAD src0_sel:DWORD
	s_nop 0
	v_ashrrev_i32_e32 v228, 31, v220
	v_ashrrev_i32_e32 v229, 31, v221
	v_bitop3_b32 v220, v220, v228, s28 bitop3:0x1e
	v_bitop3_b32 v221, v221, v229, s28 bitop3:0x1e
	v_cvt_f16_f32_sdwa v222, v222 dst_sel:WORD_1 dst_unused:UNUSED_PAD src0_sel:DWORD
	v_cvt_f16_f32_sdwa v223, v223 dst_sel:WORD_1 dst_unused:UNUSED_PAD src0_sel:DWORD
	s_nop 0
	v_ashrrev_i32_e32 v228, 31, v222
	v_ashrrev_i32_e32 v229, 31, v223
	v_bitop3_b32 v222, v222, v228, s28 bitop3:0x1e
	v_bitop3_b32 v223, v223, v229, s28 bitop3:0x1e
	v_cvt_f16_f32_sdwa v224, v224 dst_sel:WORD_1 dst_unused:UNUSED_PAD src0_sel:DWORD
	v_cvt_f16_f32_sdwa v225, v225 dst_sel:WORD_1 dst_unused:UNUSED_PAD src0_sel:DWORD
	s_nop 0
	v_ashrrev_i32_e32 v228, 31, v224
	v_ashrrev_i32_e32 v229, 31, v225
	v_bitop3_b32 v224, v224, v228, s28 bitop3:0x1e
	v_bitop3_b32 v225, v225, v229, s28 bitop3:0x1e
	v_cvt_f16_f32_sdwa v226, v226 dst_sel:WORD_1 dst_unused:UNUSED_PAD src0_sel:DWORD
	v_cvt_f16_f32_sdwa v227, v227 dst_sel:WORD_1 dst_unused:UNUSED_PAD src0_sel:DWORD
	s_nop 0
	v_ashrrev_i32_e32 v228, 31, v226
	v_ashrrev_i32_e32 v229, 31, v227
	v_bitop3_b32 v226, v226, v228, s28 bitop3:0x1e
	v_bitop3_b32 v227, v227, v229, s28 bitop3:0x1e
	s_cmp_gt_i32 s38, 62
	s_cbranch_scc1 .Lsel_kb_full7
	s_cmp_gt_i32 s38, 56
	s_cselect_b32 s4, -1, 0
	v_and_b32_e32 v221, s4, v221
	s_cmp_gt_i32 s38, 57
	s_cselect_b32 s4, -1, 0
	v_and_b32_e32 v222, s4, v222
	s_cmp_gt_i32 s38, 58
	s_cselect_b32 s4, -1, 0
	v_and_b32_e32 v223, s4, v223
	s_cmp_gt_i32 s38, 59
	s_cselect_b32 s4, -1, 0
	v_and_b32_e32 v224, s4, v224
	s_cmp_gt_i32 s38, 60
	s_cselect_b32 s4, -1, 0
	v_and_b32_e32 v225, s4, v225
	s_cmp_gt_i32 s38, 61
	s_cselect_b32 s4, -1, 0
	v_and_b32_e32 v226, s4, v226
	s_cmp_gt_i32 s38, 62
	s_cselect_b32 s4, -1, 0
	v_and_b32_e32 v227, s4, v227
	v_bfe_u32 v230, v220, 24, 8
	v_lshl_add_u32 v230, v230, 2, v233
	ds_add_u32 v230, v232
	v_bfe_u32 v231, v221, 24, 8
	v_lshl_add_u32 v231, v231, 2, v233
	ds_add_u32 v231, v232
	v_bfe_u32 v230, v222, 24, 8
	v_lshl_add_u32 v230, v230, 2, v233
	ds_add_u32 v230, v232
	v_bfe_u32 v231, v223, 24, 8
	v_lshl_add_u32 v231, v231, 2, v233
	ds_add_u32 v231, v232
	v_bfe_u32 v230, v224, 24, 8
	v_lshl_add_u32 v230, v230, 2, v233
	ds_add_u32 v230, v232
	v_bfe_u32 v231, v225, 24, 8
	v_lshl_add_u32 v231, v231, 2, v233
	ds_add_u32 v231, v232
	v_bfe_u32 v230, v226, 24, 8
	v_lshl_add_u32 v230, v230, 2, v233
	ds_add_u32 v230, v232
	v_bfe_u32 v231, v227, 24, 8
	v_lshl_add_u32 v231, v231, 2, v233
	ds_add_u32 v231, v232
	s_branch .Lsel_kb_done
.Lsel_kb_full7:
	v_bfe_u32 v230, v220, 24, 8
	v_lshl_add_u32 v230, v230, 2, v233
	ds_add_u32 v230, v232
	v_bfe_u32 v231, v221, 24, 8
	v_lshl_add_u32 v231, v231, 2, v233
	ds_add_u32 v231, v232
	v_bfe_u32 v230, v222, 24, 8
	v_lshl_add_u32 v230, v230, 2, v233
	ds_add_u32 v230, v232
	v_bfe_u32 v231, v223, 24, 8
	v_lshl_add_u32 v231, v231, 2, v233
	ds_add_u32 v231, v232
	v_bfe_u32 v230, v224, 24, 8
	v_lshl_add_u32 v230, v230, 2, v233
	ds_add_u32 v230, v232
	v_bfe_u32 v231, v225, 24, 8
	v_lshl_add_u32 v231, v231, 2, v233
	ds_add_u32 v231, v232
	v_bfe_u32 v230, v226, 24, 8
	v_lshl_add_u32 v230, v230, 2, v233
	ds_add_u32 v230, v232
	v_bfe_u32 v231, v227, 24, 8
	v_lshl_add_u32 v231, v231, 2, v233
	ds_add_u32 v231, v232
.Lsel_kb_done:
	s_movk_i32 s29, 0x100
	s_waitcnt lgkmcnt(0)
	ds_read_b128 v[236:239], v235
	s_waitcnt lgkmcnt(0)
	ds_write_b128 v234, v[172:175]
	v_add3_u32 v240, v236, v237, v238
	v_add_u32_e32 v240, v240, v239
	v_mov_b32_e32 v241, v240
	s_nop 1
	v_add_u32_dpp v241, v241, v241 row_shr:1 row_mask:0xf bank_mask:0xf
	s_nop 1
	v_add_u32_dpp v241, v241, v241 row_shr:2 row_mask:0xf bank_mask:0xf
	s_nop 1
	v_add_u32_dpp v241, v241, v241 row_shr:4 row_mask:0xf bank_mask:0xf
	s_nop 1
	v_add_u32_dpp v241, v241, v241 row_shr:8 row_mask:0xf bank_mask:0xf
	s_nop 1
	v_readlane_b32 s40, v241, 15
	v_readlane_b32 s41, v241, 31
	v_readlane_b32 s42, v241, 47
	s_add_i32 s41, s40, s41
	s_add_i32 s42, s41, s42
	s_mov_b32 exec_lo, 0xffff0000
	s_mov_b32 exec_hi, 0
	v_add_u32_e32 v241, s40, v241
	s_mov_b32 exec_lo, 0
	s_mov_b32 exec_hi, 0xffff
	v_add_u32_e32 v241, s41, v241
	s_mov_b32 exec_hi, 0xffff0000
	v_add_u32_e32 v241, s42, v241
	s_mov_b64 exec, -1
	v_sub_u32_e32 v242, v241, v240
	v_add_u32_e32 v243, v242, v239
	v_add_u32_e32 v244, v243, v238
	v_add_u32_e32 v245, v244, v237
	v_cmp_gt_u32_e32 vcc, s29, v242
	s_bcnt1_i32_b64 s30, vcc
	v_cmp_gt_u32_e32 vcc, s29, v243
	s_bcnt1_i32_b64 s4, vcc
	s_add_i32 s30, s30, s4
	v_cmp_gt_u32_e32 vcc, s29, v244
	s_bcnt1_i32_b64 s4, vcc
	s_add_i32 s30, s30, s4
	v_cmp_gt_u32_e32 vcc, s29, v245
	s_bcnt1_i32_b64 s4, vcc
	s_add_i32 s30, s30, s4
	s_add_i32 s30, s30, -1
	s_lshr_b32 s5, s30, 2
	s_and_b32 s6, s30, 3
	s_sub_i32 s34, 0xff, s30
	s_nop 3
	v_readlane_b32 s40, v242, s5
	v_readlane_b32 s41, v243, s5
	v_readlane_b32 s42, v244, s5
	v_readlane_b32 s43, v245, s5
	s_cmp_eq_u32 s6, 1
	s_cselect_b32 s40, s41, s40
	s_cmp_eq_u32 s6, 2
	s_cselect_b32 s40, s42, s40
	s_cmp_eq_u32 s6, 3
	s_cselect_b32 s40, s43, s40
	s_mov_b32 s35, s40
	s_sub_i32 s29, 0x100, s35
	s_lshl_b32 s36, s34, 24
	v_subrev_u32_e32 v230, s36, v0
	v_cmp_gt_u32_e32 vcc, 0x1000000, v230
	v_bfe_u32 v231, v230, 16, 8
	v_lshl_add_u32 v231, v231, 2, v233
	s_mov_b64 exec, vcc
	ds_add_u32 v231, v232
	s_mov_b64 exec, -1
	v_subrev_u32_e32 v230, s36, v1
	v_cmp_gt_u32_e32 vcc, 0x1000000, v230
	v_bfe_u32 v231, v230, 16, 8
	v_lshl_add_u32 v231, v231, 2, v233
	s_mov_b64 exec, vcc
	ds_add_u32 v231, v232
	s_mov_b64 exec, -1
	v_subrev_u32_e32 v230, s36, v2
	v_cmp_gt_u32_e32 vcc, 0x1000000, v230
	v_bfe_u32 v231, v230, 16, 8
	v_lshl_add_u32 v231, v231, 2, v233
	s_mov_b64 exec, vcc
	ds_add_u32 v231, v232
	s_mov_b64 exec, -1
	v_subrev_u32_e32 v230, s36, v3
	v_cmp_gt_u32_e32 vcc, 0x1000000, v230
	v_bfe_u32 v231, v230, 16, 8
	v_lshl_add_u32 v231, v231, 2, v233
	s_mov_b64 exec, vcc
	ds_add_u32 v231, v232
	s_mov_b64 exec, -1
	v_subrev_u32_e32 v230, s36, v4
	v_cmp_gt_u32_e32 vcc, 0x1000000, v230
	v_bfe_u32 v231, v230, 16, 8
	v_lshl_add_u32 v231, v231, 2, v233
	s_mov_b64 exec, vcc
	ds_add_u32 v231, v232
	s_mov_b64 exec, -1
	v_subrev_u32_e32 v230, s36, v5
	v_cmp_gt_u32_e32 vcc, 0x1000000, v230
	v_bfe_u32 v231, v230, 16, 8
	v_lshl_add_u32 v231, v231, 2, v233
	s_mov_b64 exec, vcc
	ds_add_u32 v231, v232
	s_mov_b64 exec, -1
	v_subrev_u32_e32 v230, s36, v6
	v_cmp_gt_u32_e32 vcc, 0x1000000, v230
	v_bfe_u32 v231, v230, 16, 8
	v_lshl_add_u32 v231, v231, 2, v233
	s_mov_b64 exec, vcc
	ds_add_u32 v231, v232
	s_mov_b64 exec, -1
	v_subrev_u32_e32 v230, s36, v7
	v_cmp_gt_u32_e32 vcc, 0x1000000, v230
	v_bfe_u32 v231, v230, 16, 8
	v_lshl_add_u32 v231, v231, 2, v233
	s_mov_b64 exec, vcc
	ds_add_u32 v231, v232
	s_mov_b64 exec, -1
	s_cmp_lt_i32 s38, 8
	s_cbranch_scc1 .Lsel_p2_done
	v_subrev_u32_e32 v230, s36, v8
	v_cmp_gt_u32_e32 vcc, 0x1000000, v230
	v_bfe_u32 v231, v230, 16, 8
	v_lshl_add_u32 v231, v231, 2, v233
	s_mov_b64 exec, vcc
	ds_add_u32 v231, v232
	s_mov_b64 exec, -1
	v_subrev_u32_e32 v230, s36, v9
	v_cmp_gt_u32_e32 vcc, 0x1000000, v230
	v_bfe_u32 v231, v230, 16, 8
	v_lshl_add_u32 v231, v231, 2, v233
	s_mov_b64 exec, vcc
	ds_add_u32 v231, v232
	s_mov_b64 exec, -1
	v_subrev_u32_e32 v230, s36, v10
	v_cmp_gt_u32_e32 vcc, 0x1000000, v230
	v_bfe_u32 v231, v230, 16, 8
	v_lshl_add_u32 v231, v231, 2, v233
	s_mov_b64 exec, vcc
	ds_add_u32 v231, v232
	s_mov_b64 exec, -1
	v_subrev_u32_e32 v230, s36, v11
	v_cmp_gt_u32_e32 vcc, 0x1000000, v230
	v_bfe_u32 v231, v230, 16, 8
	v_lshl_add_u32 v231, v231, 2, v233
	s_mov_b64 exec, vcc
	ds_add_u32 v231, v232
	s_mov_b64 exec, -1
	v_subrev_u32_e32 v230, s36, v12
	v_cmp_gt_u32_e32 vcc, 0x1000000, v230
	v_bfe_u32 v231, v230, 16, 8
	v_lshl_add_u32 v231, v231, 2, v233
	s_mov_b64 exec, vcc
	ds_add_u32 v231, v232
	s_mov_b64 exec, -1
	v_subrev_u32_e32 v230, s36, v13
	v_cmp_gt_u32_e32 vcc, 0x1000000, v230
	v_bfe_u32 v231, v230, 16, 8
	v_lshl_add_u32 v231, v231, 2, v233
	s_mov_b64 exec, vcc
	ds_add_u32 v231, v232
	s_mov_b64 exec, -1
	v_subrev_u32_e32 v230, s36, v14
	v_cmp_gt_u32_e32 vcc, 0x1000000, v230
	v_bfe_u32 v231, v230, 16, 8
	v_lshl_add_u32 v231, v231, 2, v233
	s_mov_b64 exec, vcc
	ds_add_u32 v231, v232
	s_mov_b64 exec, -1
	v_subrev_u32_e32 v230, s36, v15
	v_cmp_gt_u32_e32 vcc, 0x1000000, v230
	v_bfe_u32 v231, v230, 16, 8
	v_lshl_add_u32 v231, v231, 2, v233
	s_mov_b64 exec, vcc
	ds_add_u32 v231, v232
	s_mov_b64 exec, -1
	s_cmp_lt_i32 s38, 16
	s_cbranch_scc1 .Lsel_p2_done
	v_subrev_u32_e32 v230, s36, v16
	v_cmp_gt_u32_e32 vcc, 0x1000000, v230
	v_bfe_u32 v231, v230, 16, 8
	v_lshl_add_u32 v231, v231, 2, v233
	s_mov_b64 exec, vcc
	ds_add_u32 v231, v232
	s_mov_b64 exec, -1
	v_subrev_u32_e32 v230, s36, v17
	v_cmp_gt_u32_e32 vcc, 0x1000000, v230
	v_bfe_u32 v231, v230, 16, 8
	v_lshl_add_u32 v231, v231, 2, v233
	s_mov_b64 exec, vcc
	ds_add_u32 v231, v232
	s_mov_b64 exec, -1
	v_subrev_u32_e32 v230, s36, v18
	v_cmp_gt_u32_e32 vcc, 0x1000000, v230
	v_bfe_u32 v231, v230, 16, 8
	v_lshl_add_u32 v231, v231, 2, v233
	s_mov_b64 exec, vcc
	ds_add_u32 v231, v232
	s_mov_b64 exec, -1
	v_subrev_u32_e32 v230, s36, v19
	v_cmp_gt_u32_e32 vcc, 0x1000000, v230
	v_bfe_u32 v231, v230, 16, 8
	v_lshl_add_u32 v231, v231, 2, v233
	s_mov_b64 exec, vcc
	ds_add_u32 v231, v232
	s_mov_b64 exec, -1
	v_subrev_u32_e32 v230, s36, v20
	v_cmp_gt_u32_e32 vcc, 0x1000000, v230
	v_bfe_u32 v231, v230, 16, 8
	v_lshl_add_u32 v231, v231, 2, v233
	s_mov_b64 exec, vcc
	ds_add_u32 v231, v232
	s_mov_b64 exec, -1
	v_subrev_u32_e32 v230, s36, v21
	v_cmp_gt_u32_e32 vcc, 0x1000000, v230
	v_bfe_u32 v231, v230, 16, 8
	v_lshl_add_u32 v231, v231, 2, v233
	s_mov_b64 exec, vcc
	ds_add_u32 v231, v232
	s_mov_b64 exec, -1
	v_subrev_u32_e32 v230, s36, v22
	v_cmp_gt_u32_e32 vcc, 0x1000000, v230
	v_bfe_u32 v231, v230, 16, 8
	v_lshl_add_u32 v231, v231, 2, v233
	s_mov_b64 exec, vcc
	ds_add_u32 v231, v232
	s_mov_b64 exec, -1
	v_subrev_u32_e32 v230, s36, v23
	v_cmp_gt_u32_e32 vcc, 0x1000000, v230
	v_bfe_u32 v231, v230, 16, 8
	v_lshl_add_u32 v231, v231, 2, v233
	s_mov_b64 exec, vcc
	ds_add_u32 v231, v232
	s_mov_b64 exec, -1
	s_cmp_lt_i32 s38, 24
	s_cbranch_scc1 .Lsel_p2_done
	v_subrev_u32_e32 v230, s36, v24
	v_cmp_gt_u32_e32 vcc, 0x1000000, v230
	v_bfe_u32 v231, v230, 16, 8
	v_lshl_add_u32 v231, v231, 2, v233
	s_mov_b64 exec, vcc
	ds_add_u32 v231, v232
	s_mov_b64 exec, -1
	v_subrev_u32_e32 v230, s36, v25
	v_cmp_gt_u32_e32 vcc, 0x1000000, v230
	v_bfe_u32 v231, v230, 16, 8
	v_lshl_add_u32 v231, v231, 2, v233
	s_mov_b64 exec, vcc
	ds_add_u32 v231, v232
	s_mov_b64 exec, -1
	v_subrev_u32_e32 v230, s36, v26
	v_cmp_gt_u32_e32 vcc, 0x1000000, v230
	v_bfe_u32 v231, v230, 16, 8
	v_lshl_add_u32 v231, v231, 2, v233
	s_mov_b64 exec, vcc
	ds_add_u32 v231, v232
	s_mov_b64 exec, -1
	v_subrev_u32_e32 v230, s36, v27
	v_cmp_gt_u32_e32 vcc, 0x1000000, v230
	v_bfe_u32 v231, v230, 16, 8
	v_lshl_add_u32 v231, v231, 2, v233
	s_mov_b64 exec, vcc
	ds_add_u32 v231, v232
	s_mov_b64 exec, -1
	v_subrev_u32_e32 v230, s36, v28
	v_cmp_gt_u32_e32 vcc, 0x1000000, v230
	v_bfe_u32 v231, v230, 16, 8
	v_lshl_add_u32 v231, v231, 2, v233
	s_mov_b64 exec, vcc
	ds_add_u32 v231, v232
	s_mov_b64 exec, -1
	v_subrev_u32_e32 v230, s36, v29
	v_cmp_gt_u32_e32 vcc, 0x1000000, v230
	v_bfe_u32 v231, v230, 16, 8
	v_lshl_add_u32 v231, v231, 2, v233
	s_mov_b64 exec, vcc
	ds_add_u32 v231, v232
	s_mov_b64 exec, -1
	v_subrev_u32_e32 v230, s36, v30
	v_cmp_gt_u32_e32 vcc, 0x1000000, v230
	v_bfe_u32 v231, v230, 16, 8
	v_lshl_add_u32 v231, v231, 2, v233
	s_mov_b64 exec, vcc
	ds_add_u32 v231, v232
	s_mov_b64 exec, -1
	v_subrev_u32_e32 v230, s36, v31
	v_cmp_gt_u32_e32 vcc, 0x1000000, v230
	v_bfe_u32 v231, v230, 16, 8
	v_lshl_add_u32 v231, v231, 2, v233
	s_mov_b64 exec, vcc
	ds_add_u32 v231, v232
	s_mov_b64 exec, -1
	s_cmp_lt_i32 s38, 32
	s_cbranch_scc1 .Lsel_p2_done
	v_subrev_u32_e32 v230, s36, v196
	v_cmp_gt_u32_e32 vcc, 0x1000000, v230
	v_bfe_u32 v231, v230, 16, 8
	v_lshl_add_u32 v231, v231, 2, v233
	s_mov_b64 exec, vcc
	ds_add_u32 v231, v232
	s_mov_b64 exec, -1
	v_subrev_u32_e32 v230, s36, v197
	v_cmp_gt_u32_e32 vcc, 0x1000000, v230
	v_bfe_u32 v231, v230, 16, 8
	v_lshl_add_u32 v231, v231, 2, v233
	s_mov_b64 exec, vcc
	ds_add_u32 v231, v232
	s_mov_b64 exec, -1
	v_subrev_u32_e32 v230, s36, v198
	v_cmp_gt_u32_e32 vcc, 0x1000000, v230
	v_bfe_u32 v231, v230, 16, 8
	v_lshl_add_u32 v231, v231, 2, v233
	s_mov_b64 exec, vcc
	ds_add_u32 v231, v232
	s_mov_b64 exec, -1
	v_subrev_u32_e32 v230, s36, v199
	v_cmp_gt_u32_e32 vcc, 0x1000000, v230
	v_bfe_u32 v231, v230, 16, 8
	v_lshl_add_u32 v231, v231, 2, v233
	s_mov_b64 exec, vcc
	ds_add_u32 v231, v232
	s_mov_b64 exec, -1
	v_subrev_u32_e32 v230, s36, v200
	v_cmp_gt_u32_e32 vcc, 0x1000000, v230
	v_bfe_u32 v231, v230, 16, 8
	v_lshl_add_u32 v231, v231, 2, v233
	s_mov_b64 exec, vcc
	ds_add_u32 v231, v232
	s_mov_b64 exec, -1
	v_subrev_u32_e32 v230, s36, v201
	v_cmp_gt_u32_e32 vcc, 0x1000000, v230
	v_bfe_u32 v231, v230, 16, 8
	v_lshl_add_u32 v231, v231, 2, v233
	s_mov_b64 exec, vcc
	ds_add_u32 v231, v232
	s_mov_b64 exec, -1
	v_subrev_u32_e32 v230, s36, v202
	v_cmp_gt_u32_e32 vcc, 0x1000000, v230
	v_bfe_u32 v231, v230, 16, 8
	v_lshl_add_u32 v231, v231, 2, v233
	s_mov_b64 exec, vcc
	ds_add_u32 v231, v232
	s_mov_b64 exec, -1
	v_subrev_u32_e32 v230, s36, v203
	v_cmp_gt_u32_e32 vcc, 0x1000000, v230
	v_bfe_u32 v231, v230, 16, 8
	v_lshl_add_u32 v231, v231, 2, v233
	s_mov_b64 exec, vcc
	ds_add_u32 v231, v232
	s_mov_b64 exec, -1
	s_cmp_lt_i32 s38, 40
	s_cbranch_scc1 .Lsel_p2_done
	v_subrev_u32_e32 v230, s36, v204
	v_cmp_gt_u32_e32 vcc, 0x1000000, v230
	v_bfe_u32 v231, v230, 16, 8
	v_lshl_add_u32 v231, v231, 2, v233
	s_mov_b64 exec, vcc
	ds_add_u32 v231, v232
	s_mov_b64 exec, -1
	v_subrev_u32_e32 v230, s36, v205
	v_cmp_gt_u32_e32 vcc, 0x1000000, v230
	v_bfe_u32 v231, v230, 16, 8
	v_lshl_add_u32 v231, v231, 2, v233
	s_mov_b64 exec, vcc
	ds_add_u32 v231, v232
	s_mov_b64 exec, -1
	v_subrev_u32_e32 v230, s36, v206
	v_cmp_gt_u32_e32 vcc, 0x1000000, v230
	v_bfe_u32 v231, v230, 16, 8
	v_lshl_add_u32 v231, v231, 2, v233
	s_mov_b64 exec, vcc
	ds_add_u32 v231, v232
	s_mov_b64 exec, -1
	v_subrev_u32_e32 v230, s36, v207
	v_cmp_gt_u32_e32 vcc, 0x1000000, v230
	v_bfe_u32 v231, v230, 16, 8
	v_lshl_add_u32 v231, v231, 2, v233
	s_mov_b64 exec, vcc
	ds_add_u32 v231, v232
	s_mov_b64 exec, -1
	v_subrev_u32_e32 v230, s36, v208
	v_cmp_gt_u32_e32 vcc, 0x1000000, v230
	v_bfe_u32 v231, v230, 16, 8
	v_lshl_add_u32 v231, v231, 2, v233
	s_mov_b64 exec, vcc
	ds_add_u32 v231, v232
	s_mov_b64 exec, -1
	v_subrev_u32_e32 v230, s36, v209
	v_cmp_gt_u32_e32 vcc, 0x1000000, v230
	v_bfe_u32 v231, v230, 16, 8
	v_lshl_add_u32 v231, v231, 2, v233
	s_mov_b64 exec, vcc
	ds_add_u32 v231, v232
	s_mov_b64 exec, -1
	v_subrev_u32_e32 v230, s36, v210
	v_cmp_gt_u32_e32 vcc, 0x1000000, v230
	v_bfe_u32 v231, v230, 16, 8
	v_lshl_add_u32 v231, v231, 2, v233
	s_mov_b64 exec, vcc
	ds_add_u32 v231, v232
	s_mov_b64 exec, -1
	v_subrev_u32_e32 v230, s36, v211
	v_cmp_gt_u32_e32 vcc, 0x1000000, v230
	v_bfe_u32 v231, v230, 16, 8
	v_lshl_add_u32 v231, v231, 2, v233
	s_mov_b64 exec, vcc
	ds_add_u32 v231, v232
	s_mov_b64 exec, -1
	s_cmp_lt_i32 s38, 48
	s_cbranch_scc1 .Lsel_p2_done
	v_subrev_u32_e32 v230, s36, v212
	v_cmp_gt_u32_e32 vcc, 0x1000000, v230
	v_bfe_u32 v231, v230, 16, 8
	v_lshl_add_u32 v231, v231, 2, v233
	s_mov_b64 exec, vcc
	ds_add_u32 v231, v232
	s_mov_b64 exec, -1
	v_subrev_u32_e32 v230, s36, v213
	v_cmp_gt_u32_e32 vcc, 0x1000000, v230
	v_bfe_u32 v231, v230, 16, 8
	v_lshl_add_u32 v231, v231, 2, v233
	s_mov_b64 exec, vcc
	ds_add_u32 v231, v232
	s_mov_b64 exec, -1
	v_subrev_u32_e32 v230, s36, v214
	v_cmp_gt_u32_e32 vcc, 0x1000000, v230
	v_bfe_u32 v231, v230, 16, 8
	v_lshl_add_u32 v231, v231, 2, v233
	s_mov_b64 exec, vcc
	ds_add_u32 v231, v232
	s_mov_b64 exec, -1
	v_subrev_u32_e32 v230, s36, v215
	v_cmp_gt_u32_e32 vcc, 0x1000000, v230
	v_bfe_u32 v231, v230, 16, 8
	v_lshl_add_u32 v231, v231, 2, v233
	s_mov_b64 exec, vcc
	ds_add_u32 v231, v232
	s_mov_b64 exec, -1
	v_subrev_u32_e32 v230, s36, v216
	v_cmp_gt_u32_e32 vcc, 0x1000000, v230
	v_bfe_u32 v231, v230, 16, 8
	v_lshl_add_u32 v231, v231, 2, v233
	s_mov_b64 exec, vcc
	ds_add_u32 v231, v232
	s_mov_b64 exec, -1
	v_subrev_u32_e32 v230, s36, v217
	v_cmp_gt_u32_e32 vcc, 0x1000000, v230
	v_bfe_u32 v231, v230, 16, 8
	v_lshl_add_u32 v231, v231, 2, v233
	s_mov_b64 exec, vcc
	ds_add_u32 v231, v232
	s_mov_b64 exec, -1
	v_subrev_u32_e32 v230, s36, v218
	v_cmp_gt_u32_e32 vcc, 0x1000000, v230
	v_bfe_u32 v231, v230, 16, 8
	v_lshl_add_u32 v231, v231, 2, v233
	s_mov_b64 exec, vcc
	ds_add_u32 v231, v232
	s_mov_b64 exec, -1
	v_subrev_u32_e32 v230, s36, v219
	v_cmp_gt_u32_e32 vcc, 0x1000000, v230
	v_bfe_u32 v231, v230, 16, 8
	v_lshl_add_u32 v231, v231, 2, v233
	s_mov_b64 exec, vcc
	ds_add_u32 v231, v232
	s_mov_b64 exec, -1
	s_cmp_lt_i32 s38, 56
	s_cbranch_scc1 .Lsel_p2_done
	v_subrev_u32_e32 v230, s36, v220
	v_cmp_gt_u32_e32 vcc, 0x1000000, v230
	v_bfe_u32 v231, v230, 16, 8
	v_lshl_add_u32 v231, v231, 2, v233
	s_mov_b64 exec, vcc
	ds_add_u32 v231, v232
	s_mov_b64 exec, -1
	v_subrev_u32_e32 v230, s36, v221
	v_cmp_gt_u32_e32 vcc, 0x1000000, v230
	v_bfe_u32 v231, v230, 16, 8
	v_lshl_add_u32 v231, v231, 2, v233
	s_mov_b64 exec, vcc
	ds_add_u32 v231, v232
	s_mov_b64 exec, -1
	v_subrev_u32_e32 v230, s36, v222
	v_cmp_gt_u32_e32 vcc, 0x1000000, v230
	v_bfe_u32 v231, v230, 16, 8
	v_lshl_add_u32 v231, v231, 2, v233
	s_mov_b64 exec, vcc
	ds_add_u32 v231, v232
	s_mov_b64 exec, -1
	v_subrev_u32_e32 v230, s36, v223
	v_cmp_gt_u32_e32 vcc, 0x1000000, v230
	v_bfe_u32 v231, v230, 16, 8
	v_lshl_add_u32 v231, v231, 2, v233
	s_mov_b64 exec, vcc
	ds_add_u32 v231, v232
	s_mov_b64 exec, -1
	v_subrev_u32_e32 v230, s36, v224
	v_cmp_gt_u32_e32 vcc, 0x1000000, v230
	v_bfe_u32 v231, v230, 16, 8
	v_lshl_add_u32 v231, v231, 2, v233
	s_mov_b64 exec, vcc
	ds_add_u32 v231, v232
	s_mov_b64 exec, -1
	v_subrev_u32_e32 v230, s36, v225
	v_cmp_gt_u32_e32 vcc, 0x1000000, v230
	v_bfe_u32 v231, v230, 16, 8
	v_lshl_add_u32 v231, v231, 2, v233
	s_mov_b64 exec, vcc
	ds_add_u32 v231, v232
	s_mov_b64 exec, -1
	v_subrev_u32_e32 v230, s36, v226
	v_cmp_gt_u32_e32 vcc, 0x1000000, v230
	v_bfe_u32 v231, v230, 16, 8
	v_lshl_add_u32 v231, v231, 2, v233
	s_mov_b64 exec, vcc
	ds_add_u32 v231, v232
	s_mov_b64 exec, -1
	v_subrev_u32_e32 v230, s36, v227
	v_cmp_gt_u32_e32 vcc, 0x1000000, v230
	v_bfe_u32 v231, v230, 16, 8
	v_lshl_add_u32 v231, v231, 2, v233
	s_mov_b64 exec, vcc
	ds_add_u32 v231, v232
	s_mov_b64 exec, -1
.Lsel_p2_done:
	s_waitcnt lgkmcnt(0)
	ds_read_b128 v[236:239], v235
	s_waitcnt lgkmcnt(0)
	ds_write_b128 v234, v[172:175]
	v_add3_u32 v240, v236, v237, v238
	v_add_u32_e32 v240, v240, v239
	v_mov_b32_e32 v241, v240
	s_nop 1
	v_add_u32_dpp v241, v241, v241 row_shr:1 row_mask:0xf bank_mask:0xf
	s_nop 1
	v_add_u32_dpp v241, v241, v241 row_shr:2 row_mask:0xf bank_mask:0xf
	s_nop 1
	v_add_u32_dpp v241, v241, v241 row_shr:4 row_mask:0xf bank_mask:0xf
	s_nop 1
	v_add_u32_dpp v241, v241, v241 row_shr:8 row_mask:0xf bank_mask:0xf
	s_nop 1
	v_readlane_b32 s40, v241, 15
	v_readlane_b32 s41, v241, 31
	v_readlane_b32 s42, v241, 47
	s_add_i32 s41, s40, s41
	s_add_i32 s42, s41, s42
	s_mov_b32 exec_lo, 0xffff0000
	s_mov_b32 exec_hi, 0
	v_add_u32_e32 v241, s40, v241
	s_mov_b32 exec_lo, 0
	s_mov_b32 exec_hi, 0xffff
	v_add_u32_e32 v241, s41, v241
	s_mov_b32 exec_hi, 0xffff0000
	v_add_u32_e32 v241, s42, v241
	s_mov_b64 exec, -1
	v_sub_u32_e32 v242, v241, v240
	v_add_u32_e32 v243, v242, v239
	v_add_u32_e32 v244, v243, v238
	v_add_u32_e32 v245, v244, v237
	v_cmp_gt_u32_e32 vcc, s29, v242
	s_bcnt1_i32_b64 s30, vcc
	v_cmp_gt_u32_e32 vcc, s29, v243
	s_bcnt1_i32_b64 s4, vcc
	s_add_i32 s30, s30, s4
	v_cmp_gt_u32_e32 vcc, s29, v244
	s_bcnt1_i32_b64 s4, vcc
	s_add_i32 s30, s30, s4
	v_cmp_gt_u32_e32 vcc, s29, v245
	s_bcnt1_i32_b64 s4, vcc
	s_add_i32 s30, s30, s4
	s_add_i32 s30, s30, -1
	s_lshr_b32 s5, s30, 2
	s_and_b32 s6, s30, 3
	s_sub_i32 s37, 0xff, s30
	s_nop 3
	v_readlane_b32 s40, v242, s5
	v_readlane_b32 s41, v243, s5
	v_readlane_b32 s42, v244, s5
	v_readlane_b32 s43, v245, s5
	s_cmp_eq_u32 s6, 1
	s_cselect_b32 s40, s41, s40
	s_cmp_eq_u32 s6, 2
	s_cselect_b32 s40, s42, s40
	s_cmp_eq_u32 s6, 3
	s_cselect_b32 s40, s43, s40
	s_lshl_b32 s36, s34, 8
	s_or_b32 s36, s36, s37
	s_lshl_b32 s37, s36, 16
	s_or_b32 s44, s37, 0xffff
	s_add_i32 s45, s35, s40
	v_mov_b32_e32 v246, 0
	v_mov_b32_e32 v247, s45
	v_cmp_lt_u32_e32 vcc, s44, v0
	v_cmp_le_u32_e64 s[0:1], s37, v0
	s_bcnt1_i32_b64 s4, vcc
	v_mbcnt_lo_u32_b32 v248, vcc_lo, v246
	v_mbcnt_hi_u32_b32 v248, vcc_hi, v248
	v_add_u32_e32 v246, s4, v246
	v_lshlrev_b32_e32 v33, 2, v248
	v_mov_b32_e32 v254, v34
	s_mov_b64 exec, vcc
	global_store_dword v33, v254, s[2:3]
	s_mov_b64 exec, -1
	s_andn2_b64 s[0:1], s[0:1], vcc
	s_cbranch_scc1 .Lsel_eq0
.Lsel_eqb0:
	v_cmp_lt_u32_e32 vcc, s44, v1
	v_cmp_le_u32_e64 s[0:1], s37, v1
	s_bcnt1_i32_b64 s4, vcc
	v_mbcnt_lo_u32_b32 v248, vcc_lo, v246
	v_mbcnt_hi_u32_b32 v248, vcc_hi, v248
	v_add_u32_e32 v246, s4, v246
	v_lshlrev_b32_e32 v33, 2, v248
	v_or_b32_e32 v254, 64, v34
	s_mov_b64 exec, vcc
	global_store_dword v33, v254, s[2:3]
	s_mov_b64 exec, -1
	s_andn2_b64 s[0:1], s[0:1], vcc
	s_cbranch_scc1 .Lsel_eq1
.Lsel_eqb1:
	v_cmp_lt_u32_e32 vcc, s44, v2
	v_cmp_le_u32_e64 s[0:1], s37, v2
	s_bcnt1_i32_b64 s4, vcc
	v_mbcnt_lo_u32_b32 v248, vcc_lo, v246
	v_mbcnt_hi_u32_b32 v248, vcc_hi, v248
	v_add_u32_e32 v246, s4, v246
	v_lshlrev_b32_e32 v33, 2, v248
	v_or_b32_e32 v254, 128, v34
	s_mov_b64 exec, vcc
	global_store_dword v33, v254, s[2:3]
	s_mov_b64 exec, -1
	s_andn2_b64 s[0:1], s[0:1], vcc
	s_cbranch_scc1 .Lsel_eq2
.Lsel_eqb2:
	v_cmp_lt_u32_e32 vcc, s44, v3
	v_cmp_le_u32_e64 s[0:1], s37, v3
	s_bcnt1_i32_b64 s4, vcc
	v_mbcnt_lo_u32_b32 v248, vcc_lo, v246
	v_mbcnt_hi_u32_b32 v248, vcc_hi, v248
	v_add_u32_e32 v246, s4, v246
	v_lshlrev_b32_e32 v33, 2, v248
	v_or_b32_e32 v254, 192, v34
	s_mov_b64 exec, vcc
	global_store_dword v33, v254, s[2:3]
	s_mov_b64 exec, -1
	s_andn2_b64 s[0:1], s[0:1], vcc
	s_cbranch_scc1 .Lsel_eq3
.Lsel_eqb3:
	v_cmp_lt_u32_e32 vcc, s44, v4
	v_cmp_le_u32_e64 s[0:1], s37, v4
	s_bcnt1_i32_b64 s4, vcc
	v_mbcnt_lo_u32_b32 v248, vcc_lo, v246
	v_mbcnt_hi_u32_b32 v248, vcc_hi, v248
	v_add_u32_e32 v246, s4, v246
	v_lshlrev_b32_e32 v33, 2, v248
	v_or_b32_e32 v254, 256, v34
	s_mov_b64 exec, vcc
	global_store_dword v33, v254, s[2:3]
	s_mov_b64 exec, -1
	s_andn2_b64 s[0:1], s[0:1], vcc
	s_cbranch_scc1 .Lsel_eq4
.Lsel_eqb4:
	v_cmp_lt_u32_e32 vcc, s44, v5
	v_cmp_le_u32_e64 s[0:1], s37, v5
	s_bcnt1_i32_b64 s4, vcc
	v_mbcnt_lo_u32_b32 v248, vcc_lo, v246
	v_mbcnt_hi_u32_b32 v248, vcc_hi, v248
	v_add_u32_e32 v246, s4, v246
	v_lshlrev_b32_e32 v33, 2, v248
	v_or_b32_e32 v254, 320, v34
	s_mov_b64 exec, vcc
	global_store_dword v33, v254, s[2:3]
	s_mov_b64 exec, -1
	s_andn2_b64 s[0:1], s[0:1], vcc
	s_cbranch_scc1 .Lsel_eq5
.Lsel_eqb5:
	v_cmp_lt_u32_e32 vcc, s44, v6
	v_cmp_le_u32_e64 s[0:1], s37, v6
	s_bcnt1_i32_b64 s4, vcc
	v_mbcnt_lo_u32_b32 v248, vcc_lo, v246
	v_mbcnt_hi_u32_b32 v248, vcc_hi, v248
	v_add_u32_e32 v246, s4, v246
	v_lshlrev_b32_e32 v33, 2, v248
	v_or_b32_e32 v254, 384, v34
	s_mov_b64 exec, vcc
	global_store_dword v33, v254, s[2:3]
	s_mov_b64 exec, -1
	s_andn2_b64 s[0:1], s[0:1], vcc
	s_cbranch_scc1 .Lsel_eq6
.Lsel_eqb6:
	v_cmp_lt_u32_e32 vcc, s44, v7
	v_cmp_le_u32_e64 s[0:1], s37, v7
	s_bcnt1_i32_b64 s4, vcc
	v_mbcnt_lo_u32_b32 v248, vcc_lo, v246
	v_mbcnt_hi_u32_b32 v248, vcc_hi, v248
	v_add_u32_e32 v246, s4, v246
	v_lshlrev_b32_e32 v33, 2, v248
	v_or_b32_e32 v254, 448, v34
	s_mov_b64 exec, vcc
	global_store_dword v33, v254, s[2:3]
	s_mov_b64 exec, -1
	s_andn2_b64 s[0:1], s[0:1], vcc
	s_cbranch_scc1 .Lsel_eq7
.Lsel_eqb7:
	s_cmp_lt_i32 s38, 8
	s_cbranch_scc1 .Lsel_cp_done
	v_cmp_lt_u32_e32 vcc, s44, v8
	v_cmp_le_u32_e64 s[0:1], s37, v8
	s_bcnt1_i32_b64 s4, vcc
	v_mbcnt_lo_u32_b32 v248, vcc_lo, v246
	v_mbcnt_hi_u32_b32 v248, vcc_hi, v248
	v_add_u32_e32 v246, s4, v246
	v_lshlrev_b32_e32 v33, 2, v248
	v_or_b32_e32 v254, 512, v34
	s_mov_b64 exec, vcc
	global_store_dword v33, v254, s[2:3]
	s_mov_b64 exec, -1
	s_andn2_b64 s[0:1], s[0:1], vcc
	s_cbranch_scc1 .Lsel_eq8
.Lsel_eqb8:
	v_cmp_lt_u32_e32 vcc, s44, v9
	v_cmp_le_u32_e64 s[0:1], s37, v9
	s_bcnt1_i32_b64 s4, vcc
	v_mbcnt_lo_u32_b32 v248, vcc_lo, v246
	v_mbcnt_hi_u32_b32 v248, vcc_hi, v248
	v_add_u32_e32 v246, s4, v246
	v_lshlrev_b32_e32 v33, 2, v248
	v_or_b32_e32 v254, 576, v34
	s_mov_b64 exec, vcc
	global_store_dword v33, v254, s[2:3]
	s_mov_b64 exec, -1
	s_andn2_b64 s[0:1], s[0:1], vcc
	s_cbranch_scc1 .Lsel_eq9
.Lsel_eqb9:
	v_cmp_lt_u32_e32 vcc, s44, v10
	v_cmp_le_u32_e64 s[0:1], s37, v10
	s_bcnt1_i32_b64 s4, vcc
	v_mbcnt_lo_u32_b32 v248, vcc_lo, v246
	v_mbcnt_hi_u32_b32 v248, vcc_hi, v248
	v_add_u32_e32 v246, s4, v246
	v_lshlrev_b32_e32 v33, 2, v248
	v_or_b32_e32 v254, 640, v34
	s_mov_b64 exec, vcc
	global_store_dword v33, v254, s[2:3]
	s_mov_b64 exec, -1
	s_andn2_b64 s[0:1], s[0:1], vcc
	s_cbranch_scc1 .Lsel_eq10
.Lsel_eqb10:
	v_cmp_lt_u32_e32 vcc, s44, v11
	v_cmp_le_u32_e64 s[0:1], s37, v11
	s_bcnt1_i32_b64 s4, vcc
	v_mbcnt_lo_u32_b32 v248, vcc_lo, v246
	v_mbcnt_hi_u32_b32 v248, vcc_hi, v248
	v_add_u32_e32 v246, s4, v246
	v_lshlrev_b32_e32 v33, 2, v248
	v_or_b32_e32 v254, 704, v34
	s_mov_b64 exec, vcc
	global_store_dword v33, v254, s[2:3]
	s_mov_b64 exec, -1
	s_andn2_b64 s[0:1], s[0:1], vcc
	s_cbranch_scc1 .Lsel_eq11
.Lsel_eqb11:
	v_cmp_lt_u32_e32 vcc, s44, v12
	v_cmp_le_u32_e64 s[0:1], s37, v12
	s_bcnt1_i32_b64 s4, vcc
	v_mbcnt_lo_u32_b32 v248, vcc_lo, v246
	v_mbcnt_hi_u32_b32 v248, vcc_hi, v248
	v_add_u32_e32 v246, s4, v246
	v_lshlrev_b32_e32 v33, 2, v248
	v_or_b32_e32 v254, 768, v34
	s_mov_b64 exec, vcc
	global_store_dword v33, v254, s[2:3]
	s_mov_b64 exec, -1
	s_andn2_b64 s[0:1], s[0:1], vcc
	s_cbranch_scc1 .Lsel_eq12
.Lsel_eqb12:
	v_cmp_lt_u32_e32 vcc, s44, v13
	v_cmp_le_u32_e64 s[0:1], s37, v13
	s_bcnt1_i32_b64 s4, vcc
	v_mbcnt_lo_u32_b32 v248, vcc_lo, v246
	v_mbcnt_hi_u32_b32 v248, vcc_hi, v248
	v_add_u32_e32 v246, s4, v246
	v_lshlrev_b32_e32 v33, 2, v248
	v_or_b32_e32 v254, 832, v34
	s_mov_b64 exec, vcc
	global_store_dword v33, v254, s[2:3]
	s_mov_b64 exec, -1
	s_andn2_b64 s[0:1], s[0:1], vcc
	s_cbranch_scc1 .Lsel_eq13
.Lsel_eqb13:
	v_cmp_lt_u32_e32 vcc, s44, v14
	v_cmp_le_u32_e64 s[0:1], s37, v14
	s_bcnt1_i32_b64 s4, vcc
	v_mbcnt_lo_u32_b32 v248, vcc_lo, v246
	v_mbcnt_hi_u32_b32 v248, vcc_hi, v248
	v_add_u32_e32 v246, s4, v246
	v_lshlrev_b32_e32 v33, 2, v248
	v_or_b32_e32 v254, 896, v34
	s_mov_b64 exec, vcc
	global_store_dword v33, v254, s[2:3]
	s_mov_b64 exec, -1
	s_andn2_b64 s[0:1], s[0:1], vcc
	s_cbranch_scc1 .Lsel_eq14
.Lsel_eqb14:
	v_cmp_lt_u32_e32 vcc, s44, v15
	v_cmp_le_u32_e64 s[0:1], s37, v15
	s_bcnt1_i32_b64 s4, vcc
	v_mbcnt_lo_u32_b32 v248, vcc_lo, v246
	v_mbcnt_hi_u32_b32 v248, vcc_hi, v248
	v_add_u32_e32 v246, s4, v246
	v_lshlrev_b32_e32 v33, 2, v248
	v_or_b32_e32 v254, 960, v34
	s_mov_b64 exec, vcc
	global_store_dword v33, v254, s[2:3]
	s_mov_b64 exec, -1
	s_andn2_b64 s[0:1], s[0:1], vcc
	s_cbranch_scc1 .Lsel_eq15
.Lsel_eqb15:
	s_cmp_lt_i32 s38, 16
	s_cbranch_scc1 .Lsel_cp_done
	v_cmp_lt_u32_e32 vcc, s44, v16
	v_cmp_le_u32_e64 s[0:1], s37, v16
	s_bcnt1_i32_b64 s4, vcc
	v_mbcnt_lo_u32_b32 v248, vcc_lo, v246
	v_mbcnt_hi_u32_b32 v248, vcc_hi, v248
	v_add_u32_e32 v246, s4, v246
	v_lshlrev_b32_e32 v33, 2, v248
	v_or_b32_e32 v254, 1024, v34
	s_mov_b64 exec, vcc
	global_store_dword v33, v254, s[2:3]
	s_mov_b64 exec, -1
	s_andn2_b64 s[0:1], s[0:1], vcc
	s_cbranch_scc1 .Lsel_eq16
.Lsel_eqb16:
	v_cmp_lt_u32_e32 vcc, s44, v17
	v_cmp_le_u32_e64 s[0:1], s37, v17
	s_bcnt1_i32_b64 s4, vcc
	v_mbcnt_lo_u32_b32 v248, vcc_lo, v246
	v_mbcnt_hi_u32_b32 v248, vcc_hi, v248
	v_add_u32_e32 v246, s4, v246
	v_lshlrev_b32_e32 v33, 2, v248
	v_or_b32_e32 v254, 1088, v34
	s_mov_b64 exec, vcc
	global_store_dword v33, v254, s[2:3]
	s_mov_b64 exec, -1
	s_andn2_b64 s[0:1], s[0:1], vcc
	s_cbranch_scc1 .Lsel_eq17
.Lsel_eqb17:
	v_cmp_lt_u32_e32 vcc, s44, v18
	v_cmp_le_u32_e64 s[0:1], s37, v18
	s_bcnt1_i32_b64 s4, vcc
	v_mbcnt_lo_u32_b32 v248, vcc_lo, v246
	v_mbcnt_hi_u32_b32 v248, vcc_hi, v248
	v_add_u32_e32 v246, s4, v246
	v_lshlrev_b32_e32 v33, 2, v248
	v_or_b32_e32 v254, 1152, v34
	s_mov_b64 exec, vcc
	global_store_dword v33, v254, s[2:3]
	s_mov_b64 exec, -1
	s_andn2_b64 s[0:1], s[0:1], vcc
	s_cbranch_scc1 .Lsel_eq18
.Lsel_eqb18:
	v_cmp_lt_u32_e32 vcc, s44, v19
	v_cmp_le_u32_e64 s[0:1], s37, v19
	s_bcnt1_i32_b64 s4, vcc
	v_mbcnt_lo_u32_b32 v248, vcc_lo, v246
	v_mbcnt_hi_u32_b32 v248, vcc_hi, v248
	v_add_u32_e32 v246, s4, v246
	v_lshlrev_b32_e32 v33, 2, v248
	v_or_b32_e32 v254, 1216, v34
	s_mov_b64 exec, vcc
	global_store_dword v33, v254, s[2:3]
	s_mov_b64 exec, -1
	s_andn2_b64 s[0:1], s[0:1], vcc
	s_cbranch_scc1 .Lsel_eq19
.Lsel_eqb19:
	v_cmp_lt_u32_e32 vcc, s44, v20
	v_cmp_le_u32_e64 s[0:1], s37, v20
	s_bcnt1_i32_b64 s4, vcc
	v_mbcnt_lo_u32_b32 v248, vcc_lo, v246
	v_mbcnt_hi_u32_b32 v248, vcc_hi, v248
	v_add_u32_e32 v246, s4, v246
	v_lshlrev_b32_e32 v33, 2, v248
	v_or_b32_e32 v254, 1280, v34
	s_mov_b64 exec, vcc
	global_store_dword v33, v254, s[2:3]
	s_mov_b64 exec, -1
	s_andn2_b64 s[0:1], s[0:1], vcc
	s_cbranch_scc1 .Lsel_eq20
.Lsel_eqb20:
	v_cmp_lt_u32_e32 vcc, s44, v21
	v_cmp_le_u32_e64 s[0:1], s37, v21
	s_bcnt1_i32_b64 s4, vcc
	v_mbcnt_lo_u32_b32 v248, vcc_lo, v246
	v_mbcnt_hi_u32_b32 v248, vcc_hi, v248
	v_add_u32_e32 v246, s4, v246
	v_lshlrev_b32_e32 v33, 2, v248
	v_or_b32_e32 v254, 1344, v34
	s_mov_b64 exec, vcc
	global_store_dword v33, v254, s[2:3]
	s_mov_b64 exec, -1
	s_andn2_b64 s[0:1], s[0:1], vcc
	s_cbranch_scc1 .Lsel_eq21
.Lsel_eqb21:
	v_cmp_lt_u32_e32 vcc, s44, v22
	v_cmp_le_u32_e64 s[0:1], s37, v22
	s_bcnt1_i32_b64 s4, vcc
	v_mbcnt_lo_u32_b32 v248, vcc_lo, v246
	v_mbcnt_hi_u32_b32 v248, vcc_hi, v248
	v_add_u32_e32 v246, s4, v246
	v_lshlrev_b32_e32 v33, 2, v248
	v_or_b32_e32 v254, 1408, v34
	s_mov_b64 exec, vcc
	global_store_dword v33, v254, s[2:3]
	s_mov_b64 exec, -1
	s_andn2_b64 s[0:1], s[0:1], vcc
	s_cbranch_scc1 .Lsel_eq22
.Lsel_eqb22:
	v_cmp_lt_u32_e32 vcc, s44, v23
	v_cmp_le_u32_e64 s[0:1], s37, v23
	s_bcnt1_i32_b64 s4, vcc
	v_mbcnt_lo_u32_b32 v248, vcc_lo, v246
	v_mbcnt_hi_u32_b32 v248, vcc_hi, v248
	v_add_u32_e32 v246, s4, v246
	v_lshlrev_b32_e32 v33, 2, v248
	v_or_b32_e32 v254, 1472, v34
	s_mov_b64 exec, vcc
	global_store_dword v33, v254, s[2:3]
	s_mov_b64 exec, -1
	s_andn2_b64 s[0:1], s[0:1], vcc
	s_cbranch_scc1 .Lsel_eq23
.Lsel_eqb23:
	s_cmp_lt_i32 s38, 24
	s_cbranch_scc1 .Lsel_cp_done
	v_cmp_lt_u32_e32 vcc, s44, v24
	v_cmp_le_u32_e64 s[0:1], s37, v24
	s_bcnt1_i32_b64 s4, vcc
	v_mbcnt_lo_u32_b32 v248, vcc_lo, v246
	v_mbcnt_hi_u32_b32 v248, vcc_hi, v248
	v_add_u32_e32 v246, s4, v246
	v_lshlrev_b32_e32 v33, 2, v248
	v_or_b32_e32 v254, 1536, v34
	s_mov_b64 exec, vcc
	global_store_dword v33, v254, s[2:3]
	s_mov_b64 exec, -1
	s_andn2_b64 s[0:1], s[0:1], vcc
	s_cbranch_scc1 .Lsel_eq24
.Lsel_eqb24:
	v_cmp_lt_u32_e32 vcc, s44, v25
	v_cmp_le_u32_e64 s[0:1], s37, v25
	s_bcnt1_i32_b64 s4, vcc
	v_mbcnt_lo_u32_b32 v248, vcc_lo, v246
	v_mbcnt_hi_u32_b32 v248, vcc_hi, v248
	v_add_u32_e32 v246, s4, v246
	v_lshlrev_b32_e32 v33, 2, v248
	v_or_b32_e32 v254, 1600, v34
	s_mov_b64 exec, vcc
	global_store_dword v33, v254, s[2:3]
	s_mov_b64 exec, -1
	s_andn2_b64 s[0:1], s[0:1], vcc
	s_cbranch_scc1 .Lsel_eq25
.Lsel_eqb25:
	v_cmp_lt_u32_e32 vcc, s44, v26
	v_cmp_le_u32_e64 s[0:1], s37, v26
	s_bcnt1_i32_b64 s4, vcc
	v_mbcnt_lo_u32_b32 v248, vcc_lo, v246
	v_mbcnt_hi_u32_b32 v248, vcc_hi, v248
	v_add_u32_e32 v246, s4, v246
	v_lshlrev_b32_e32 v33, 2, v248
	v_or_b32_e32 v254, 1664, v34
	s_mov_b64 exec, vcc
	global_store_dword v33, v254, s[2:3]
	s_mov_b64 exec, -1
	s_andn2_b64 s[0:1], s[0:1], vcc
	s_cbranch_scc1 .Lsel_eq26
.Lsel_eqb26:
	v_cmp_lt_u32_e32 vcc, s44, v27
	v_cmp_le_u32_e64 s[0:1], s37, v27
	s_bcnt1_i32_b64 s4, vcc
	v_mbcnt_lo_u32_b32 v248, vcc_lo, v246
	v_mbcnt_hi_u32_b32 v248, vcc_hi, v248
	v_add_u32_e32 v246, s4, v246
	v_lshlrev_b32_e32 v33, 2, v248
	v_or_b32_e32 v254, 1728, v34
	s_mov_b64 exec, vcc
	global_store_dword v33, v254, s[2:3]
	s_mov_b64 exec, -1
	s_andn2_b64 s[0:1], s[0:1], vcc
	s_cbranch_scc1 .Lsel_eq27
.Lsel_eqb27:
	v_cmp_lt_u32_e32 vcc, s44, v28
	v_cmp_le_u32_e64 s[0:1], s37, v28
	s_bcnt1_i32_b64 s4, vcc
	v_mbcnt_lo_u32_b32 v248, vcc_lo, v246
	v_mbcnt_hi_u32_b32 v248, vcc_hi, v248
	v_add_u32_e32 v246, s4, v246
	v_lshlrev_b32_e32 v33, 2, v248
	v_or_b32_e32 v254, 1792, v34
	s_mov_b64 exec, vcc
	global_store_dword v33, v254, s[2:3]
	s_mov_b64 exec, -1
	s_andn2_b64 s[0:1], s[0:1], vcc
	s_cbranch_scc1 .Lsel_eq28
.Lsel_eqb28:
	v_cmp_lt_u32_e32 vcc, s44, v29
	v_cmp_le_u32_e64 s[0:1], s37, v29
	s_bcnt1_i32_b64 s4, vcc
	v_mbcnt_lo_u32_b32 v248, vcc_lo, v246
	v_mbcnt_hi_u32_b32 v248, vcc_hi, v248
	v_add_u32_e32 v246, s4, v246
	v_lshlrev_b32_e32 v33, 2, v248
	v_or_b32_e32 v254, 1856, v34
	s_mov_b64 exec, vcc
	global_store_dword v33, v254, s[2:3]
	s_mov_b64 exec, -1
	s_andn2_b64 s[0:1], s[0:1], vcc
	s_cbranch_scc1 .Lsel_eq29
.Lsel_eqb29:
	v_cmp_lt_u32_e32 vcc, s44, v30
	v_cmp_le_u32_e64 s[0:1], s37, v30
	s_bcnt1_i32_b64 s4, vcc
	v_mbcnt_lo_u32_b32 v248, vcc_lo, v246
	v_mbcnt_hi_u32_b32 v248, vcc_hi, v248
	v_add_u32_e32 v246, s4, v246
	v_lshlrev_b32_e32 v33, 2, v248
	v_or_b32_e32 v254, 1920, v34
	s_mov_b64 exec, vcc
	global_store_dword v33, v254, s[2:3]
	s_mov_b64 exec, -1
	s_andn2_b64 s[0:1], s[0:1], vcc
	s_cbranch_scc1 .Lsel_eq30
.Lsel_eqb30:
	v_cmp_lt_u32_e32 vcc, s44, v31
	v_cmp_le_u32_e64 s[0:1], s37, v31
	s_bcnt1_i32_b64 s4, vcc
	v_mbcnt_lo_u32_b32 v248, vcc_lo, v246
	v_mbcnt_hi_u32_b32 v248, vcc_hi, v248
	v_add_u32_e32 v246, s4, v246
	v_lshlrev_b32_e32 v33, 2, v248
	v_or_b32_e32 v254, 1984, v34
	s_mov_b64 exec, vcc
	global_store_dword v33, v254, s[2:3]
	s_mov_b64 exec, -1
	s_andn2_b64 s[0:1], s[0:1], vcc
	s_cbranch_scc1 .Lsel_eq31
.Lsel_eqb31:
	s_cmp_lt_i32 s38, 32
	s_cbranch_scc1 .Lsel_cp_done
	v_cmp_lt_u32_e32 vcc, s44, v196
	v_cmp_le_u32_e64 s[0:1], s37, v196
	s_bcnt1_i32_b64 s4, vcc
	v_mbcnt_lo_u32_b32 v248, vcc_lo, v246
	v_mbcnt_hi_u32_b32 v248, vcc_hi, v248
	v_add_u32_e32 v246, s4, v246
	v_lshlrev_b32_e32 v33, 2, v248
	v_or_b32_e32 v254, 2048, v34
	s_mov_b64 exec, vcc
	global_store_dword v33, v254, s[2:3]
	s_mov_b64 exec, -1
	s_andn2_b64 s[0:1], s[0:1], vcc
	s_cbranch_scc1 .Lsel_eq32
.Lsel_eqb32:
	v_cmp_lt_u32_e32 vcc, s44, v197
	v_cmp_le_u32_e64 s[0:1], s37, v197
	s_bcnt1_i32_b64 s4, vcc
	v_mbcnt_lo_u32_b32 v248, vcc_lo, v246
	v_mbcnt_hi_u32_b32 v248, vcc_hi, v248
	v_add_u32_e32 v246, s4, v246
	v_lshlrev_b32_e32 v33, 2, v248
	v_or_b32_e32 v254, 2112, v34
	s_mov_b64 exec, vcc
	global_store_dword v33, v254, s[2:3]
	s_mov_b64 exec, -1
	s_andn2_b64 s[0:1], s[0:1], vcc
	s_cbranch_scc1 .Lsel_eq33
.Lsel_eqb33:
	v_cmp_lt_u32_e32 vcc, s44, v198
	v_cmp_le_u32_e64 s[0:1], s37, v198
	s_bcnt1_i32_b64 s4, vcc
	v_mbcnt_lo_u32_b32 v248, vcc_lo, v246
	v_mbcnt_hi_u32_b32 v248, vcc_hi, v248
	v_add_u32_e32 v246, s4, v246
	v_lshlrev_b32_e32 v33, 2, v248
	v_or_b32_e32 v254, 2176, v34
	s_mov_b64 exec, vcc
	global_store_dword v33, v254, s[2:3]
	s_mov_b64 exec, -1
	s_andn2_b64 s[0:1], s[0:1], vcc
	s_cbranch_scc1 .Lsel_eq34
.Lsel_eqb34:
	v_cmp_lt_u32_e32 vcc, s44, v199
	v_cmp_le_u32_e64 s[0:1], s37, v199
	s_bcnt1_i32_b64 s4, vcc
	v_mbcnt_lo_u32_b32 v248, vcc_lo, v246
	v_mbcnt_hi_u32_b32 v248, vcc_hi, v248
	v_add_u32_e32 v246, s4, v246
	v_lshlrev_b32_e32 v33, 2, v248
	v_or_b32_e32 v254, 2240, v34
	s_mov_b64 exec, vcc
	global_store_dword v33, v254, s[2:3]
	s_mov_b64 exec, -1
	s_andn2_b64 s[0:1], s[0:1], vcc
	s_cbranch_scc1 .Lsel_eq35
.Lsel_eqb35:
	v_cmp_lt_u32_e32 vcc, s44, v200
	v_cmp_le_u32_e64 s[0:1], s37, v200
	s_bcnt1_i32_b64 s4, vcc
	v_mbcnt_lo_u32_b32 v248, vcc_lo, v246
	v_mbcnt_hi_u32_b32 v248, vcc_hi, v248
	v_add_u32_e32 v246, s4, v246
	v_lshlrev_b32_e32 v33, 2, v248
	v_or_b32_e32 v254, 2304, v34
	s_mov_b64 exec, vcc
	global_store_dword v33, v254, s[2:3]
	s_mov_b64 exec, -1
	s_andn2_b64 s[0:1], s[0:1], vcc
	s_cbranch_scc1 .Lsel_eq36
.Lsel_eqb36:
	v_cmp_lt_u32_e32 vcc, s44, v201
	v_cmp_le_u32_e64 s[0:1], s37, v201
	s_bcnt1_i32_b64 s4, vcc
	v_mbcnt_lo_u32_b32 v248, vcc_lo, v246
	v_mbcnt_hi_u32_b32 v248, vcc_hi, v248
	v_add_u32_e32 v246, s4, v246
	v_lshlrev_b32_e32 v33, 2, v248
	v_or_b32_e32 v254, 2368, v34
	s_mov_b64 exec, vcc
	global_store_dword v33, v254, s[2:3]
	s_mov_b64 exec, -1
	s_andn2_b64 s[0:1], s[0:1], vcc
	s_cbranch_scc1 .Lsel_eq37
.Lsel_eqb37:
	v_cmp_lt_u32_e32 vcc, s44, v202
	v_cmp_le_u32_e64 s[0:1], s37, v202
	s_bcnt1_i32_b64 s4, vcc
	v_mbcnt_lo_u32_b32 v248, vcc_lo, v246
	v_mbcnt_hi_u32_b32 v248, vcc_hi, v248
	v_add_u32_e32 v246, s4, v246
	v_lshlrev_b32_e32 v33, 2, v248
	v_or_b32_e32 v254, 2432, v34
	s_mov_b64 exec, vcc
	global_store_dword v33, v254, s[2:3]
	s_mov_b64 exec, -1
	s_andn2_b64 s[0:1], s[0:1], vcc
	s_cbranch_scc1 .Lsel_eq38
.Lsel_eqb38:
	v_cmp_lt_u32_e32 vcc, s44, v203
	v_cmp_le_u32_e64 s[0:1], s37, v203
	s_bcnt1_i32_b64 s4, vcc
	v_mbcnt_lo_u32_b32 v248, vcc_lo, v246
	v_mbcnt_hi_u32_b32 v248, vcc_hi, v248
	v_add_u32_e32 v246, s4, v246
	v_lshlrev_b32_e32 v33, 2, v248
	v_or_b32_e32 v254, 2496, v34
	s_mov_b64 exec, vcc
	global_store_dword v33, v254, s[2:3]
	s_mov_b64 exec, -1
	s_andn2_b64 s[0:1], s[0:1], vcc
	s_cbranch_scc1 .Lsel_eq39
.Lsel_eqb39:
	s_cmp_lt_i32 s38, 40
	s_cbranch_scc1 .Lsel_cp_done
	v_cmp_lt_u32_e32 vcc, s44, v204
	v_cmp_le_u32_e64 s[0:1], s37, v204
	s_bcnt1_i32_b64 s4, vcc
	v_mbcnt_lo_u32_b32 v248, vcc_lo, v246
	v_mbcnt_hi_u32_b32 v248, vcc_hi, v248
	v_add_u32_e32 v246, s4, v246
	v_lshlrev_b32_e32 v33, 2, v248
	v_or_b32_e32 v254, 2560, v34
	s_mov_b64 exec, vcc
	global_store_dword v33, v254, s[2:3]
	s_mov_b64 exec, -1
	s_andn2_b64 s[0:1], s[0:1], vcc
	s_cbranch_scc1 .Lsel_eq40
.Lsel_eqb40:
	v_cmp_lt_u32_e32 vcc, s44, v205
	v_cmp_le_u32_e64 s[0:1], s37, v205
	s_bcnt1_i32_b64 s4, vcc
	v_mbcnt_lo_u32_b32 v248, vcc_lo, v246
	v_mbcnt_hi_u32_b32 v248, vcc_hi, v248
	v_add_u32_e32 v246, s4, v246
	v_lshlrev_b32_e32 v33, 2, v248
	v_or_b32_e32 v254, 2624, v34
	s_mov_b64 exec, vcc
	global_store_dword v33, v254, s[2:3]
	s_mov_b64 exec, -1
	s_andn2_b64 s[0:1], s[0:1], vcc
	s_cbranch_scc1 .Lsel_eq41
.Lsel_eqb41:
	v_cmp_lt_u32_e32 vcc, s44, v206
	v_cmp_le_u32_e64 s[0:1], s37, v206
	s_bcnt1_i32_b64 s4, vcc
	v_mbcnt_lo_u32_b32 v248, vcc_lo, v246
	v_mbcnt_hi_u32_b32 v248, vcc_hi, v248
	v_add_u32_e32 v246, s4, v246
	v_lshlrev_b32_e32 v33, 2, v248
	v_or_b32_e32 v254, 2688, v34
	s_mov_b64 exec, vcc
	global_store_dword v33, v254, s[2:3]
	s_mov_b64 exec, -1
	s_andn2_b64 s[0:1], s[0:1], vcc
	s_cbranch_scc1 .Lsel_eq42
.Lsel_eqb42:
	v_cmp_lt_u32_e32 vcc, s44, v207
	v_cmp_le_u32_e64 s[0:1], s37, v207
	s_bcnt1_i32_b64 s4, vcc
	v_mbcnt_lo_u32_b32 v248, vcc_lo, v246
	v_mbcnt_hi_u32_b32 v248, vcc_hi, v248
	v_add_u32_e32 v246, s4, v246
	v_lshlrev_b32_e32 v33, 2, v248
	v_or_b32_e32 v254, 2752, v34
	s_mov_b64 exec, vcc
	global_store_dword v33, v254, s[2:3]
	s_mov_b64 exec, -1
	s_andn2_b64 s[0:1], s[0:1], vcc
	s_cbranch_scc1 .Lsel_eq43
.Lsel_eqb43:
	v_cmp_lt_u32_e32 vcc, s44, v208
	v_cmp_le_u32_e64 s[0:1], s37, v208
	s_bcnt1_i32_b64 s4, vcc
	v_mbcnt_lo_u32_b32 v248, vcc_lo, v246
	v_mbcnt_hi_u32_b32 v248, vcc_hi, v248
	v_add_u32_e32 v246, s4, v246
	v_lshlrev_b32_e32 v33, 2, v248
	v_or_b32_e32 v254, 2816, v34
	s_mov_b64 exec, vcc
	global_store_dword v33, v254, s[2:3]
	s_mov_b64 exec, -1
	s_andn2_b64 s[0:1], s[0:1], vcc
	s_cbranch_scc1 .Lsel_eq44
.Lsel_eqb44:
	v_cmp_lt_u32_e32 vcc, s44, v209
	v_cmp_le_u32_e64 s[0:1], s37, v209
	s_bcnt1_i32_b64 s4, vcc
	v_mbcnt_lo_u32_b32 v248, vcc_lo, v246
	v_mbcnt_hi_u32_b32 v248, vcc_hi, v248
	v_add_u32_e32 v246, s4, v246
	v_lshlrev_b32_e32 v33, 2, v248
	v_or_b32_e32 v254, 2880, v34
	s_mov_b64 exec, vcc
	global_store_dword v33, v254, s[2:3]
	s_mov_b64 exec, -1
	s_andn2_b64 s[0:1], s[0:1], vcc
	s_cbranch_scc1 .Lsel_eq45
.Lsel_eqb45:
	v_cmp_lt_u32_e32 vcc, s44, v210
	v_cmp_le_u32_e64 s[0:1], s37, v210
	s_bcnt1_i32_b64 s4, vcc
	v_mbcnt_lo_u32_b32 v248, vcc_lo, v246
	v_mbcnt_hi_u32_b32 v248, vcc_hi, v248
	v_add_u32_e32 v246, s4, v246
	v_lshlrev_b32_e32 v33, 2, v248
	v_or_b32_e32 v254, 2944, v34
	s_mov_b64 exec, vcc
	global_store_dword v33, v254, s[2:3]
	s_mov_b64 exec, -1
	s_andn2_b64 s[0:1], s[0:1], vcc
	s_cbranch_scc1 .Lsel_eq46
.Lsel_eqb46:
	v_cmp_lt_u32_e32 vcc, s44, v211
	v_cmp_le_u32_e64 s[0:1], s37, v211
	s_bcnt1_i32_b64 s4, vcc
	v_mbcnt_lo_u32_b32 v248, vcc_lo, v246
	v_mbcnt_hi_u32_b32 v248, vcc_hi, v248
	v_add_u32_e32 v246, s4, v246
	v_lshlrev_b32_e32 v33, 2, v248
	v_or_b32_e32 v254, 3008, v34
	s_mov_b64 exec, vcc
	global_store_dword v33, v254, s[2:3]
	s_mov_b64 exec, -1
	s_andn2_b64 s[0:1], s[0:1], vcc
	s_cbranch_scc1 .Lsel_eq47
.Lsel_eqb47:
	s_cmp_lt_i32 s38, 48
	s_cbranch_scc1 .Lsel_cp_done
	v_cmp_lt_u32_e32 vcc, s44, v212
	v_cmp_le_u32_e64 s[0:1], s37, v212
	s_bcnt1_i32_b64 s4, vcc
	v_mbcnt_lo_u32_b32 v248, vcc_lo, v246
	v_mbcnt_hi_u32_b32 v248, vcc_hi, v248
	v_add_u32_e32 v246, s4, v246
	v_lshlrev_b32_e32 v33, 2, v248
	v_or_b32_e32 v254, 3072, v34
	s_mov_b64 exec, vcc
	global_store_dword v33, v254, s[2:3]
	s_mov_b64 exec, -1
	s_andn2_b64 s[0:1], s[0:1], vcc
	s_cbranch_scc1 .Lsel_eq48
.Lsel_eqb48:
	v_cmp_lt_u32_e32 vcc, s44, v213
	v_cmp_le_u32_e64 s[0:1], s37, v213
	s_bcnt1_i32_b64 s4, vcc
	v_mbcnt_lo_u32_b32 v248, vcc_lo, v246
	v_mbcnt_hi_u32_b32 v248, vcc_hi, v248
	v_add_u32_e32 v246, s4, v246
	v_lshlrev_b32_e32 v33, 2, v248
	v_or_b32_e32 v254, 3136, v34
	s_mov_b64 exec, vcc
	global_store_dword v33, v254, s[2:3]
	s_mov_b64 exec, -1
	s_andn2_b64 s[0:1], s[0:1], vcc
	s_cbranch_scc1 .Lsel_eq49
.Lsel_eqb49:
	v_cmp_lt_u32_e32 vcc, s44, v214
	v_cmp_le_u32_e64 s[0:1], s37, v214
	s_bcnt1_i32_b64 s4, vcc
	v_mbcnt_lo_u32_b32 v248, vcc_lo, v246
	v_mbcnt_hi_u32_b32 v248, vcc_hi, v248
	v_add_u32_e32 v246, s4, v246
	v_lshlrev_b32_e32 v33, 2, v248
	v_or_b32_e32 v254, 3200, v34
	s_mov_b64 exec, vcc
	global_store_dword v33, v254, s[2:3]
	s_mov_b64 exec, -1
	s_andn2_b64 s[0:1], s[0:1], vcc
	s_cbranch_scc1 .Lsel_eq50
.Lsel_eqb50:
	v_cmp_lt_u32_e32 vcc, s44, v215
	v_cmp_le_u32_e64 s[0:1], s37, v215
	s_bcnt1_i32_b64 s4, vcc
	v_mbcnt_lo_u32_b32 v248, vcc_lo, v246
	v_mbcnt_hi_u32_b32 v248, vcc_hi, v248
	v_add_u32_e32 v246, s4, v246
	v_lshlrev_b32_e32 v33, 2, v248
	v_or_b32_e32 v254, 3264, v34
	s_mov_b64 exec, vcc
	global_store_dword v33, v254, s[2:3]
	s_mov_b64 exec, -1
	s_andn2_b64 s[0:1], s[0:1], vcc
	s_cbranch_scc1 .Lsel_eq51
.Lsel_eqb51:
	v_cmp_lt_u32_e32 vcc, s44, v216
	v_cmp_le_u32_e64 s[0:1], s37, v216
	s_bcnt1_i32_b64 s4, vcc
	v_mbcnt_lo_u32_b32 v248, vcc_lo, v246
	v_mbcnt_hi_u32_b32 v248, vcc_hi, v248
	v_add_u32_e32 v246, s4, v246
	v_lshlrev_b32_e32 v33, 2, v248
	v_or_b32_e32 v254, 3328, v34
	s_mov_b64 exec, vcc
	global_store_dword v33, v254, s[2:3]
	s_mov_b64 exec, -1
	s_andn2_b64 s[0:1], s[0:1], vcc
	s_cbranch_scc1 .Lsel_eq52
.Lsel_eqb52:
	v_cmp_lt_u32_e32 vcc, s44, v217
	v_cmp_le_u32_e64 s[0:1], s37, v217
	s_bcnt1_i32_b64 s4, vcc
	v_mbcnt_lo_u32_b32 v248, vcc_lo, v246
	v_mbcnt_hi_u32_b32 v248, vcc_hi, v248
	v_add_u32_e32 v246, s4, v246
	v_lshlrev_b32_e32 v33, 2, v248
	v_or_b32_e32 v254, 3392, v34
	s_mov_b64 exec, vcc
	global_store_dword v33, v254, s[2:3]
	s_mov_b64 exec, -1
	s_andn2_b64 s[0:1], s[0:1], vcc
	s_cbranch_scc1 .Lsel_eq53
.Lsel_eqb53:
	v_cmp_lt_u32_e32 vcc, s44, v218
	v_cmp_le_u32_e64 s[0:1], s37, v218
	s_bcnt1_i32_b64 s4, vcc
	v_mbcnt_lo_u32_b32 v248, vcc_lo, v246
	v_mbcnt_hi_u32_b32 v248, vcc_hi, v248
	v_add_u32_e32 v246, s4, v246
	v_lshlrev_b32_e32 v33, 2, v248
	v_or_b32_e32 v254, 3456, v34
	s_mov_b64 exec, vcc
	global_store_dword v33, v254, s[2:3]
	s_mov_b64 exec, -1
	s_andn2_b64 s[0:1], s[0:1], vcc
	s_cbranch_scc1 .Lsel_eq54
.Lsel_eqb54:
	v_cmp_lt_u32_e32 vcc, s44, v219
	v_cmp_le_u32_e64 s[0:1], s37, v219
	s_bcnt1_i32_b64 s4, vcc
	v_mbcnt_lo_u32_b32 v248, vcc_lo, v246
	v_mbcnt_hi_u32_b32 v248, vcc_hi, v248
	v_add_u32_e32 v246, s4, v246
	v_lshlrev_b32_e32 v33, 2, v248
	v_or_b32_e32 v254, 3520, v34
	s_mov_b64 exec, vcc
	global_store_dword v33, v254, s[2:3]
	s_mov_b64 exec, -1
	s_andn2_b64 s[0:1], s[0:1], vcc
	s_cbranch_scc1 .Lsel_eq55
.Lsel_eqb55:
	s_cmp_lt_i32 s38, 56
	s_cbranch_scc1 .Lsel_cp_done
	v_cmp_lt_u32_e32 vcc, s44, v220
	v_cmp_le_u32_e64 s[0:1], s37, v220
	s_bcnt1_i32_b64 s4, vcc
	v_mbcnt_lo_u32_b32 v248, vcc_lo, v246
	v_mbcnt_hi_u32_b32 v248, vcc_hi, v248
	v_add_u32_e32 v246, s4, v246
	v_lshlrev_b32_e32 v33, 2, v248
	v_or_b32_e32 v254, 3584, v34
	s_mov_b64 exec, vcc
	global_store_dword v33, v254, s[2:3]
	s_mov_b64 exec, -1
	s_andn2_b64 s[0:1], s[0:1], vcc
	s_cbranch_scc1 .Lsel_eq56
.Lsel_eqb56:
	v_cmp_lt_u32_e32 vcc, s44, v221
	v_cmp_le_u32_e64 s[0:1], s37, v221
	s_bcnt1_i32_b64 s4, vcc
	v_mbcnt_lo_u32_b32 v248, vcc_lo, v246
	v_mbcnt_hi_u32_b32 v248, vcc_hi, v248
	v_add_u32_e32 v246, s4, v246
	v_lshlrev_b32_e32 v33, 2, v248
	v_or_b32_e32 v254, 3648, v34
	s_mov_b64 exec, vcc
	global_store_dword v33, v254, s[2:3]
	s_mov_b64 exec, -1
	s_andn2_b64 s[0:1], s[0:1], vcc
	s_cbranch_scc1 .Lsel_eq57
.Lsel_eqb57:
	v_cmp_lt_u32_e32 vcc, s44, v222
	v_cmp_le_u32_e64 s[0:1], s37, v222
	s_bcnt1_i32_b64 s4, vcc
	v_mbcnt_lo_u32_b32 v248, vcc_lo, v246
	v_mbcnt_hi_u32_b32 v248, vcc_hi, v248
	v_add_u32_e32 v246, s4, v246
	v_lshlrev_b32_e32 v33, 2, v248
	v_or_b32_e32 v254, 3712, v34
	s_mov_b64 exec, vcc
	global_store_dword v33, v254, s[2:3]
	s_mov_b64 exec, -1
	s_andn2_b64 s[0:1], s[0:1], vcc
	s_cbranch_scc1 .Lsel_eq58
.Lsel_eqb58:
	v_cmp_lt_u32_e32 vcc, s44, v223
	v_cmp_le_u32_e64 s[0:1], s37, v223
	s_bcnt1_i32_b64 s4, vcc
	v_mbcnt_lo_u32_b32 v248, vcc_lo, v246
	v_mbcnt_hi_u32_b32 v248, vcc_hi, v248
	v_add_u32_e32 v246, s4, v246
	v_lshlrev_b32_e32 v33, 2, v248
	v_or_b32_e32 v254, 3776, v34
	s_mov_b64 exec, vcc
	global_store_dword v33, v254, s[2:3]
	s_mov_b64 exec, -1
	s_andn2_b64 s[0:1], s[0:1], vcc
	s_cbranch_scc1 .Lsel_eq59
.Lsel_eqb59:
	v_cmp_lt_u32_e32 vcc, s44, v224
	v_cmp_le_u32_e64 s[0:1], s37, v224
	s_bcnt1_i32_b64 s4, vcc
	v_mbcnt_lo_u32_b32 v248, vcc_lo, v246
	v_mbcnt_hi_u32_b32 v248, vcc_hi, v248
	v_add_u32_e32 v246, s4, v246
	v_lshlrev_b32_e32 v33, 2, v248
	v_or_b32_e32 v254, 3840, v34
	s_mov_b64 exec, vcc
	global_store_dword v33, v254, s[2:3]
	s_mov_b64 exec, -1
	s_andn2_b64 s[0:1], s[0:1], vcc
	s_cbranch_scc1 .Lsel_eq60
.Lsel_eqb60:
	v_cmp_lt_u32_e32 vcc, s44, v225
	v_cmp_le_u32_e64 s[0:1], s37, v225
	s_bcnt1_i32_b64 s4, vcc
	v_mbcnt_lo_u32_b32 v248, vcc_lo, v246
	v_mbcnt_hi_u32_b32 v248, vcc_hi, v248
	v_add_u32_e32 v246, s4, v246
	v_lshlrev_b32_e32 v33, 2, v248
	v_or_b32_e32 v254, 3904, v34
	s_mov_b64 exec, vcc
	global_store_dword v33, v254, s[2:3]
	s_mov_b64 exec, -1
	s_andn2_b64 s[0:1], s[0:1], vcc
	s_cbranch_scc1 .Lsel_eq61
.Lsel_eqb61:
	v_cmp_lt_u32_e32 vcc, s44, v226
	v_cmp_le_u32_e64 s[0:1], s37, v226
	s_bcnt1_i32_b64 s4, vcc
	v_mbcnt_lo_u32_b32 v248, vcc_lo, v246
	v_mbcnt_hi_u32_b32 v248, vcc_hi, v248
	v_add_u32_e32 v246, s4, v246
	v_lshlrev_b32_e32 v33, 2, v248
	v_or_b32_e32 v254, 3968, v34
	s_mov_b64 exec, vcc
	global_store_dword v33, v254, s[2:3]
	s_mov_b64 exec, -1
	s_andn2_b64 s[0:1], s[0:1], vcc
	s_cbranch_scc1 .Lsel_eq62
.Lsel_eqb62:
	v_cmp_lt_u32_e32 vcc, s44, v227
	v_cmp_le_u32_e64 s[0:1], s37, v227
	s_bcnt1_i32_b64 s4, vcc
	v_mbcnt_lo_u32_b32 v248, vcc_lo, v246
	v_mbcnt_hi_u32_b32 v248, vcc_hi, v248
	v_add_u32_e32 v246, s4, v246
	v_lshlrev_b32_e32 v33, 2, v248
	v_or_b32_e32 v254, 4032, v34
	s_mov_b64 exec, vcc
	global_store_dword v33, v254, s[2:3]
	s_mov_b64 exec, -1
	s_andn2_b64 s[0:1], s[0:1], vcc
	s_cbranch_scc1 .Lsel_eq63
.Lsel_eqb63:
.Lsel_cp_done:
.Lsel_end:
	s_waitcnt lgkmcnt(0)
	v_readlane_b32 s56, v253, 17
	v_readlane_b32 s57, v253, 18
	v_readlane_b32 s68, v253, 19
	v_readlane_b32 s69, v253, 20
	v_readlane_b32 s84, v252, 48
	v_readlane_b32 s85, v252, 49
	v_readlane_b32 s86, v252, 50
	v_readlane_b32 s87, v252, 51
	v_readlane_b32 s88, v252, 52
	v_readlane_b32 s89, v252, 53
	v_readlane_b32 s90, v252, 54
	v_readlane_b32 s91, v252, 55
	s_mov_b32 s54, 0xf800000
	s_movk_i32 s53, 0x6640
	s_mov_b64 s[24:25], -1
	s_branch .LBB0_144
.Lsel_eq0:
	v_mbcnt_lo_u32_b32 v248, s0, v247
	v_mbcnt_hi_u32_b32 v248, s1, v248
	s_bcnt1_i32_b64 s4, s[0:1]
	v_cmp_gt_u32_e32 vcc, 0x100, v248
	v_lshlrev_b32_e32 v33, 2, v248
	v_add_u32_e32 v247, s4, v247
	s_and_b64 exec, vcc, s[0:1]
	global_store_dword v33, v254, s[2:3]
	s_mov_b64 exec, -1
	s_branch .Lsel_eqb0

.LBB0_804:
	s_andn2_b64 vcc, exec, s[0:1]
	s_cbranch_vccnz .LBB0_811
	s_cmp_lg_u32 s70, 2
	s_cbranch_scc1 .LBB0_811
	s_waitcnt vmcnt(0)
	v_mov_b32_e32 v0, v165
	s_lshl_b32 s1, s10, 3
	v_readfirstlane_b32 s0, v0
	s_ashr_i32 s0, s0, 6
	s_add_i32 s22, s0, s1
	s_cmpk_gt_i32 s22, 0x3fff
	s_cbranch_scc1 .LBB0_811
	s_mov_b64 s[24:25], s[12:13]
	s_mov_b64 s[26:27], s[8:9]
	s_mov_b64 s[30:31], s[16:17]
	s_mov_b64 s[34:35], s[18:19]
	s_mov_b64 s[36:37], s[6:7]
	s_mov_b32 s38, s15
	v_readlane_b32 s4, v252, 32
	s_lshl_b64 s[2:3], s[96:97], 9
	v_readlane_b32 s10, v252, 38
	v_and_b32_e32 v6, 63, v0
	v_readlane_b32 s5, v252, 33
	v_readlane_b32 s11, v252, 39
	s_add_u32 s2, s10, s2
	s_addc_u32 s3, s11, s3
	v_lshlrev_b32_e32 v12, 3, v6
	v_readlane_b32 s5, v253, 3
	v_readlane_b32 s8, v252, 36
	global_load_dwordx2 v[4:5], v12, s[2:3]
	s_lshl_b32 s28, s5, 3
	s_lshl_b64 s[2:3], s[96:97], 10
	v_readlane_b32 s9, v252, 37
	s_add_u32 s2, s8, s2
	s_addc_u32 s3, s9, s3
	v_lshlrev_b32_e32 v0, 4, v6
	global_load_dwordx4 v[0:3], v0, s[2:3]
	v_readlane_b32 s12, v252, 40
	v_readlane_b32 s13, v252, 41
	v_cmp_lt_i32_e32 vcc, v182, v181
	s_mov_b64 s[12:13], s[24:25]
	s_ashr_i32 s24, s0, 31
	v_cndmask_b32_e32 v7, v179, v182, vcc
	v_cmp_lt_i32_e32 vcc, v183, v181
	s_ashr_i32 s25, s1, 31
	v_lshlrev_b32_e32 v18, 2, v7
	v_cndmask_b32_e32 v7, v179, v183, vcc
	v_cmp_lt_i32_e32 vcc, v184, v181
	s_add_u32 s0, s0, s1
	v_lshlrev_b32_e32 v19, 2, v7
	v_cndmask_b32_e32 v7, v179, v184, vcc
	v_cmp_lt_i32_e32 vcc, v185, v181
	s_addc_u32 s1, s24, s25
	v_lshlrev_b32_e32 v20, 2, v7
	v_cndmask_b32_e32 v7, v179, v185, vcc
	v_cmp_lt_i32_e32 vcc, v186, v181
	s_lshl_b64 s[24:25], s[0:1], 6
	v_readlane_b32 s4, v252, 17
	v_lshlrev_b32_e32 v21, 2, v7
	v_cndmask_b32_e32 v7, v179, v186, vcc
	v_cmp_lt_i32_e32 vcc, v187, v181
	s_add_u32 s24, s4, s24
	v_readlane_b32 s4, v252, 18
	v_readlane_b32 s16, v252, 44
	v_readlane_b32 s17, v252, 45
	v_lshlrev_b32_e32 v14, 2, v6
	v_mov_b32_e32 v15, v32
	v_lshlrev_b32_e32 v22, 2, v7
	v_cndmask_b32_e32 v7, v179, v187, vcc
	s_addc_u32 s25, s4, s25
	s_ashr_i32 s29, s28, 31
	s_mov_b64 s[16:17], s[30:31]
	v_lshlrev_b32_e32 v16, 1, v6
	v_lshlrev_b32_e32 v23, 2, v7
	v_cmp_gt_u32_e64 s[2:3], 16, v6
	v_lshl_add_u64 v[6:7], s[24:25], 0, v[14:15]
	s_lshl_b64 s[24:25], s[28:29], 6
	s_lshl_b64 s[30:31], s[0:1], 8
	v_readlane_b32 s4, v252, 19
	s_add_u32 s30, s4, s30
	v_readlane_b32 s4, v252, 20
	v_readlane_b32 s18, v252, 46
	v_readlane_b32 s19, v252, 47
	s_addc_u32 s31, s4, s31
	s_mov_b64 s[18:19], s[34:35]
	s_and_b32 s4, s0, 15
	s_mul_i32 s4, s4, 0xc0
	s_sub_u32 s30, s30, s4
	s_subb_u32 s31, s31, 0
	v_and_b32_e32 v24, 0x3c, v14
	v_and_b32_e32 v25, 0xc0, v14
	v_lshl_or_b32 v24, v25, 4, v24
	v_mov_b32_e32 v25, v32
	v_lshl_add_u64 v[8:9], s[30:31], 0, v[24:25]
	s_lshl_b64 s[30:31], s[28:29], 8
	s_lshl_b64 s[34:35], s[0:1], 9
	v_readlane_b32 s4, v252, 13
	s_add_u32 s34, s4, s34
	v_readlane_b32 s4, v252, 14
	s_mov_b64 s[8:9], s[26:27]
	v_mov_b32_e32 v13, v32
	s_addc_u32 s35, s4, s35
	s_mulk_i32 s1, 0x3400
	s_mul_hi_u32 s26, s0, 0x3400
	v_lshl_add_u64 v[10:11], s[34:35], 0, v[12:13]
	s_lshl_b64 s[34:35], s[28:29], 9
	s_add_i32 s26, s26, s1
	s_mul_i32 s27, s0, 0x3400
	v_readlane_b32 s0, v252, 21
	s_add_u32 s0, s0, s27
	v_readlane_b32 s1, v252, 22
	s_addc_u32 s1, s1, s26
	v_readlane_b32 s6, v252, 34
	v_lshl_add_u64 v[12:13], s[0:1], 0, v[12:13]
	v_readlane_b32 s0, v252, 23
	s_add_u32 s0, s0, s27
	v_readlane_b32 s1, v252, 24
	s_addc_u32 s1, s1, s26
	v_readlane_b32 s7, v252, 35
	v_lshl_add_u64 v[14:15], s[0:1], 0, v[14:15]
	v_readlane_b32 s0, v252, 25
	s_add_u32 s0, s0, s27
	v_readlane_b32 s1, v252, 26
	v_readlane_b32 s15, v252, 43
	v_mov_b32_e32 v17, v32
	s_addc_u32 s1, s1, s26
	s_mov_b32 s15, s38
	s_mov_b64 s[6:7], s[36:37]
	v_readlane_b32 s10, v253, 6
	s_mul_i32 s36, s5, 0x1a000
	s_mul_hi_i32 s37, s28, 0x3400
	v_lshl_add_u64 v[16:17], s[0:1], 0, v[16:17]
	v_readlane_b32 s14, v252, 42
	s_branch .LBB0_809
